# epilogue de-serialisation: wave halves re-synchronised around each tile epilogue (extra barrier after K-loop for waves 0-3, before K-loop for waves 4-7)
# speedup vs baseline: 1.0542x; 1.0271x over previous
.LBB0_34:
	s_and_b64 vcc, exec, s[28:29]
	s_cbranch_vccz .LBB0_68
	v_readlane_b32 s0, v253, 45
	s_mov_b32 s4, s82
	v_mov_b32_e32 v10, v167
	v_readlane_b32 s1, v253, 46
	s_andn2_b64 vcc, exec, s[0:1]
	v_readfirstlane_b32 s0, v10
	s_cbranch_vccnz .LBB0_67
	v_lshlrev_b32_e32 v0, 4, v10
	v_add_u32_e32 v2, 0x2000, v0
	v_ashrrev_i32_e32 v3, 31, v2
	v_lshrrev_b32_e32 v3, 22, v3
	v_add_u32_e32 v3, v2, v3
	v_ashrrev_i32_e32 v11, 10, v3
	v_mul_i32_i24_e32 v3, 0x400, v11
	v_sub_u32_e32 v2, v2, v3
	v_lshrrev_b32_e32 v3, 4, v2
	v_bitop3_b32 v2, v3, v2, 32 bitop3:0x6c
	v_ashrrev_i32_e32 v3, 31, v2
	s_cmp_gt_i32 s4, 10
	v_lshrrev_b32_e32 v3, 26, v3
	s_cselect_b64 s[36:37], -1, 0
	v_add_u32_e32 v3, v2, v3
	v_lshlrev_b32_e32 v4, 3, v11
	s_and_b64 s[16:17], s[36:37], exec
	s_mov_b32 s1, 0x4100000
	v_ashrrev_i32_e32 v12, 6, v3
	v_and_b32_e32 v4, -16, v4
	s_cselect_b32 s1, s1, 0x3f00000
	v_add_u32_e32 v4, v12, v4
	s_add_u32 s16, s10, s1
	v_and_b32_e32 v5, 3, v12
	s_mov_b32 s1, 0x1fffe0
	v_lshrrev_b32_e32 v6, 2, v4
	v_lshlrev_b32_e32 v7, 1, v4
	v_and_b32_e32 v3, 0xc0, v3
	v_and_or_b32 v5, v4, s1, v5
	v_and_b32_e32 v6, 4, v6
	v_and_b32_e32 v7, 24, v7
	v_sub_u32_e32 v2, v2, v3
	v_or3_b32 v5, v5, v6, v7
	v_lshlrev_b32_e32 v6, 5, v11
	v_ashrrev_i16_sdwa v2, v211, sext(v2) dst_sel:DWORD dst_unused:UNUSED_PAD src0_sel:DWORD src1_sel:BYTE_0
	v_and_b32_e32 v6, 32, v6
	v_bfe_i32 v13, v2, 0, 16
	v_add_lshl_u32 v2, v6, v13, 1
	v_lshl_add_u32 v154, v5, 11, v2
	v_lshl_add_u32 v156, v4, 11, v2
	v_bfe_i32 v2, v10, 27, 1
	v_lshrrev_b32_e32 v2, 22, v2
	v_add_u32_e32 v2, v0, v2
	v_and_b32_e32 v2, 0xfffffc00, v2
	v_sub_u32_e32 v0, v0, v2
	v_lshrrev_b32_e32 v2, 4, v0
	v_ashrrev_i32_e32 v3, 31, v10
	v_bitop3_b32 v0, v2, v0, 32 bitop3:0x6c
	v_lshrrev_b32_e32 v3, 26, v3
	v_ashrrev_i32_e32 v2, 31, v0
	v_add_u32_e32 v3, v10, v3
	v_lshrrev_b32_e32 v2, 26, v2
	v_ashrrev_i32_e32 v15, 6, v3
	v_add_u32_e32 v2, v0, v2
	v_lshlrev_b32_e32 v3, 3, v15
	v_ashrrev_i32_e32 v14, 6, v2
	v_and_b32_e32 v3, -16, v3
	v_add_u32_e32 v3, v14, v3
	v_and_b32_e32 v4, 3, v14
	v_lshrrev_b32_e32 v5, 2, v3
	v_lshlrev_b32_e32 v6, 1, v3
	v_and_b32_e32 v2, 0xc0, v2
	s_addc_u32 s17, s11, 0
	s_ashr_i32 s20, s0, 6
	v_and_or_b32 v4, v3, s1, v4
	v_and_b32_e32 v5, 4, v5
	v_and_b32_e32 v6, 24, v6
	v_sub_u32_e32 v0, v0, v2
	s_ashr_i32 s4, s0, 8
	s_lshl_b32 s58, s20, 10
	v_or3_b32 v4, v4, v5, v6
	v_lshlrev_b32_e32 v5, 5, v15
	v_ashrrev_i16_sdwa v0, v211, sext(v0) dst_sel:DWORD dst_unused:UNUSED_PAD src0_sel:DWORD src1_sel:BYTE_0
	v_readlane_b32 s22, v253, 41
	v_and_b32_e32 v5, 32, v5
	v_bfe_i32 v16, v0, 0, 16
	v_readlane_b32 s23, v253, 42
	s_add_u32 s30, s16, s22
	v_add_lshl_u32 v2, v5, v16, 1
	s_addc_u32 s31, s17, s23
	s_add_i32 s59, s58, 0
	v_lshl_add_u32 v0, v4, 11, v2
	s_add_i32 m0, s59, 0x10000
	v_readlane_b32 s22, v253, 37
	global_load_lds_dwordx4 v0, s[30:31]
	s_add_i32 m0, s59, 0x12000
	v_readlane_b32 s23, v253, 38
	s_add_u32 s28, s96, s22
	v_lshl_add_u32 v158, v3, 11, v2
	global_load_lds_dwordx4 v154, s[30:31]
	s_addc_u32 s29, s97, s23
	s_mov_b32 m0, s59
	s_add_i32 s60, s59, 0x2000
	global_load_lds_dwordx4 v158, s[28:29]
	s_mov_b32 m0, s60
	s_add_u32 s22, s30, 0x40000
	global_load_lds_dwordx4 v156, s[28:29]
	s_addc_u32 s23, s31, 0
	s_add_i32 m0, s59, 0x14000
	v_mov_b32_e32 v155, v1
	global_load_lds_dwordx4 v0, s[22:23]
	s_add_i32 m0, s59, 0x16000
	v_mov_b32_e32 v159, v1
	global_load_lds_dwordx4 v154, s[22:23]
	s_add_u32 s22, s28, 0x40000
	s_addc_u32 s23, s29, 0
	s_add_i32 s61, s59, 0x4000
	s_mov_b32 m0, s61
	s_add_i32 s62, s59, 0x6000
	global_load_lds_dwordx4 v158, s[22:23]
	s_mov_b32 m0, s62
	v_mov_b32_e32 v157, v1
	global_load_lds_dwordx4 v156, s[22:23]
	v_lshl_add_u64 v[8:9], s[30:31], 0, v[0:1]
	v_lshl_add_u64 v[6:7], s[30:31], 0, v[154:155]
	v_lshl_add_u64 v[4:5], s[28:29], 0, v[158:159]
	s_cmp_lg_u32 s4, 1
	v_lshl_add_u64 v[2:3], s[28:29], 0, v[156:157]
	s_cbranch_scc1 .LBB0_38
	s_nop 0

.LBB0_46:
	s_ashr_i32 s49, s48, 31
	s_lshl_b64 s[22:23], s[48:49], 19
	v_cmp_lt_i64_e32 vcc, s[52:53], v[164:165]
	s_add_u32 s52, s96, s22
	s_addc_u32 s53, s97, s23
	s_and_b64 s[22:23], vcc, exec
	s_cselect_b32 s21, s53, s29
	s_cselect_b32 s34, s52, s28
	s_ashr_i32 s47, s46, 31
	s_lshl_b64 s[22:23], s[46:47], 19
	s_add_u32 s54, s16, s22
	s_addc_u32 s55, s17, s23
	s_and_b64 s[22:23], vcc, exec
	s_cselect_b32 s47, s55, s31
	s_cselect_b32 s49, s54, s30
	s_add_u32 s28, s28, 0x40080
	s_addc_u32 s29, s29, 0
	s_add_u32 s67, s30, 0x100
	v_mov_b32_e32 v2, 0
	s_addc_u32 s68, s31, 0
	s_mov_b32 s69, -2
	s_waitcnt lgkmcnt(0)
	v_mov_b32_e32 v3, v2
	v_mov_b32_e32 v4, v2
	v_mov_b32_e32 v5, v2
	v_mov_b32_e32 v6, v2
	v_mov_b32_e32 v7, v2
	v_mov_b32_e32 v8, v2
	v_mov_b32_e32 v9, v2
	v_mov_b32_e32 v18, v2
	v_mov_b32_e32 v19, v2
	v_mov_b32_e32 v20, v2
	v_mov_b32_e32 v21, v2
	v_mov_b32_e32 v22, v2
	v_mov_b32_e32 v23, v2
	v_mov_b32_e32 v24, v2
	v_mov_b32_e32 v25, v2
	v_mov_b32_e32 v34, v2
	v_mov_b32_e32 v35, v2
	v_mov_b32_e32 v36, v2
	v_mov_b32_e32 v37, v2
	v_mov_b32_e32 v38, v2
	v_mov_b32_e32 v39, v2
	v_mov_b32_e32 v40, v2
	v_mov_b32_e32 v41, v2
	v_mov_b32_e32 v50, v2
	v_mov_b32_e32 v51, v2
	v_mov_b32_e32 v52, v2
	v_mov_b32_e32 v53, v2
	v_mov_b32_e32 v54, v2
	v_mov_b32_e32 v55, v2
	v_mov_b32_e32 v56, v2
	v_mov_b32_e32 v57, v2
	v_mov_b32_e32 v10, v2
	v_mov_b32_e32 v11, v2
	v_mov_b32_e32 v12, v2
	v_mov_b32_e32 v13, v2
	v_mov_b32_e32 v14, v2
	v_mov_b32_e32 v15, v2
	v_mov_b32_e32 v16, v2
	v_mov_b32_e32 v17, v2
	v_mov_b32_e32 v26, v2
	v_mov_b32_e32 v27, v2
	v_mov_b32_e32 v28, v2
	v_mov_b32_e32 v29, v2
	v_mov_b32_e32 v30, v2
	v_mov_b32_e32 v31, v2
	v_mov_b32_e32 v32, v2
	v_mov_b32_e32 v33, v2
	v_mov_b32_e32 v42, v2
	v_mov_b32_e32 v43, v2
	v_mov_b32_e32 v44, v2
	v_mov_b32_e32 v45, v2
	v_mov_b32_e32 v46, v2
	v_mov_b32_e32 v47, v2
	v_mov_b32_e32 v48, v2
	v_mov_b32_e32 v49, v2
	v_mov_b32_e32 v58, v2
	v_mov_b32_e32 v59, v2
	v_mov_b32_e32 v60, v2
	v_mov_b32_e32 v61, v2
	v_mov_b32_e32 v62, v2
	v_mov_b32_e32 v63, v2
	v_mov_b32_e32 v64, v2
	v_mov_b32_e32 v65, v2
	v_mov_b32_e32 v66, v2
	v_mov_b32_e32 v67, v2
	v_mov_b32_e32 v68, v2
	v_mov_b32_e32 v69, v2
	v_mov_b32_e32 v70, v2
	v_mov_b32_e32 v71, v2
	v_mov_b32_e32 v72, v2
	v_mov_b32_e32 v73, v2
	v_mov_b32_e32 v82, v2
	v_mov_b32_e32 v83, v2
	v_mov_b32_e32 v84, v2
	v_mov_b32_e32 v85, v2
	v_mov_b32_e32 v86, v2
	v_mov_b32_e32 v87, v2
	v_mov_b32_e32 v88, v2
	v_mov_b32_e32 v89, v2
	v_mov_b32_e32 v98, v2
	v_mov_b32_e32 v99, v2
	v_mov_b32_e32 v100, v2
	v_mov_b32_e32 v101, v2
	v_mov_b32_e32 v102, v2
	v_mov_b32_e32 v103, v2
	v_mov_b32_e32 v104, v2
	v_mov_b32_e32 v105, v2
	v_mov_b32_e32 v114, v2
	v_mov_b32_e32 v115, v2
	v_mov_b32_e32 v116, v2
	v_mov_b32_e32 v117, v2
	v_mov_b32_e32 v118, v2
	v_mov_b32_e32 v119, v2
	v_mov_b32_e32 v120, v2
	v_mov_b32_e32 v121, v2
	v_mov_b32_e32 v74, v2
	v_mov_b32_e32 v75, v2
	v_mov_b32_e32 v76, v2
	v_mov_b32_e32 v77, v2
	v_mov_b32_e32 v78, v2
	v_mov_b32_e32 v79, v2
	v_mov_b32_e32 v80, v2
	v_mov_b32_e32 v81, v2
	v_mov_b32_e32 v90, v2
	v_mov_b32_e32 v91, v2
	v_mov_b32_e32 v92, v2
	v_mov_b32_e32 v93, v2
	v_mov_b32_e32 v94, v2
	v_mov_b32_e32 v95, v2
	v_mov_b32_e32 v96, v2
	v_mov_b32_e32 v97, v2
	v_mov_b32_e32 v106, v2
	v_mov_b32_e32 v107, v2
	v_mov_b32_e32 v108, v2
	v_mov_b32_e32 v109, v2
	v_mov_b32_e32 v110, v2
	v_mov_b32_e32 v111, v2
	v_mov_b32_e32 v112, v2
	v_mov_b32_e32 v113, v2
	v_mov_b32_e32 v122, v2
	v_mov_b32_e32 v123, v2
	v_mov_b32_e32 v124, v2
	v_mov_b32_e32 v125, v2
	v_mov_b32_e32 v126, v2
	v_mov_b32_e32 v127, v2
	v_mov_b32_e32 v128, v2
	v_mov_b32_e32 v129, v2
	s_cmpk_gt_u32 s0, 0xff
	s_cbranch_scc0 .Lrs_i1_pre
	s_barrier
.Lrs_i1_pre:
.LBB0_47:
	s_add_u32 s1, s28, 0xfffc0080
	s_addc_u32 s22, s29, -1
	s_add_i32 s23, 0, 0x10000
	v_add_u32_e32 v142, s23, v195
	ds_read_b128 v[130:133], v142
	ds_read_b128 v[134:137], v142 offset:1024
	ds_read_b128 v[138:141], v142 offset:2048
	ds_read_b128 v[142:145], v142 offset:3072
	s_cmp_eq_u32 s69, 12
	s_cselect_b32 s57, s21, s22
	s_cselect_b32 s56, s34, s1
	s_cselect_b32 s31, s47, s68
	s_cselect_b32 s30, s49, s67
	v_lshl_add_u64 v[176:177], s[28:29], 0, v[178:179]
	s_add_i32 m0, s59, 0xc000
	ds_read_b128 v[146:149], v197
	ds_read_b128 v[150:153], v197 offset:1024
	ds_read_b128 v[182:185], v197 offset:2048
	ds_read_b128 v[186:189], v197 offset:3072
	ds_read_b128 v[190:193], v197 offset:4096
	ds_read_b128 v[198:201], v197 offset:5120
	ds_read_b128 v[202:205], v197 offset:6144
	ds_read_b128 v[206:209], v197 offset:7168
	global_load_lds_dwordx4 v[176:177], off
	v_lshl_add_u64 v[176:177], s[28:29], 0, v[180:181]
	s_add_i32 m0, s59, 0xe000
	s_nop 0
	global_load_lds_dwordx4 v[176:177], off
	s_add_i32 s1, 0, 0x14000
	v_add_u32_e32 v168, s1, v195
	ds_read_b128 v[216:219], v168
	ds_read_b128 v[230:233], v168 offset:1024
	ds_read_b128 v[234:237], v168 offset:2048
	ds_read_b128 v[238:241], v168 offset:3072
	s_waitcnt vmcnt(8)
	s_waitcnt lgkmcnt(0)
	s_barrier
	s_setprio 1
	v_mfma_f32_16x16x32_bf16 v[126:129], v[130:133], v[146:149], v[126:129]
	v_mfma_f32_16x16x32_bf16 v[122:125], v[138:141], v[146:149], v[122:125]
	v_mfma_f32_16x16x32_bf16 v[110:113], v[130:133], v[182:185], v[110:113]
	v_mfma_f32_16x16x32_bf16 v[106:109], v[138:141], v[182:185], v[106:109]
	v_mfma_f32_16x16x32_bf16 v[94:97], v[130:133], v[190:193], v[94:97]
	v_mfma_f32_16x16x32_bf16 v[90:93], v[138:141], v[190:193], v[90:93]
	v_mfma_f32_16x16x32_bf16 v[78:81], v[130:133], v[202:205], v[78:81]
	v_mfma_f32_16x16x32_bf16 v[74:77], v[138:141], v[202:205], v[74:77]
	v_mfma_f32_16x16x32_bf16 v[126:129], v[134:137], v[150:153], v[126:129]
	v_mfma_f32_16x16x32_bf16 v[122:125], v[142:145], v[150:153], v[122:125]
	v_mfma_f32_16x16x32_bf16 v[110:113], v[134:137], v[186:189], v[110:113]
	v_mfma_f32_16x16x32_bf16 v[106:109], v[142:145], v[186:189], v[106:109]
	v_mfma_f32_16x16x32_bf16 v[94:97], v[134:137], v[198:201], v[94:97]
	v_mfma_f32_16x16x32_bf16 v[90:93], v[142:145], v[198:201], v[90:93]
	v_mfma_f32_16x16x32_bf16 v[78:81], v[134:137], v[206:209], v[78:81]
	v_mfma_f32_16x16x32_bf16 v[74:77], v[142:145], v[206:209], v[74:77]
	v_mfma_f32_16x16x32_bf16 v[118:121], v[216:219], v[146:149], v[118:121]
	v_mfma_f32_16x16x32_bf16 v[114:117], v[234:237], v[146:149], v[114:117]
	v_mfma_f32_16x16x32_bf16 v[102:105], v[216:219], v[182:185], v[102:105]
	v_mfma_f32_16x16x32_bf16 v[98:101], v[234:237], v[182:185], v[98:101]
	v_mfma_f32_16x16x32_bf16 v[86:89], v[216:219], v[190:193], v[86:89]
	v_mfma_f32_16x16x32_bf16 v[82:85], v[234:237], v[190:193], v[82:85]
	v_mfma_f32_16x16x32_bf16 v[70:73], v[216:219], v[202:205], v[70:73]
	v_mfma_f32_16x16x32_bf16 v[66:69], v[234:237], v[202:205], v[66:69]
	v_mfma_f32_16x16x32_bf16 v[118:121], v[230:233], v[150:153], v[118:121]
	v_mfma_f32_16x16x32_bf16 v[114:117], v[238:241], v[150:153], v[114:117]
	v_mfma_f32_16x16x32_bf16 v[102:105], v[230:233], v[186:189], v[102:105]
	v_mfma_f32_16x16x32_bf16 v[98:101], v[238:241], v[186:189], v[98:101]
	v_mfma_f32_16x16x32_bf16 v[86:89], v[230:233], v[198:201], v[86:89]
	v_mfma_f32_16x16x32_bf16 v[82:85], v[238:241], v[198:201], v[82:85]
	v_mfma_f32_16x16x32_bf16 v[70:73], v[230:233], v[206:209], v[70:73]
	v_mfma_f32_16x16x32_bf16 v[66:69], v[238:241], v[206:209], v[66:69]
	s_setprio 0
	s_barrier
	ds_read_b128 v[146:149], v197 offset:16384
	ds_read_b128 v[150:153], v197 offset:17408
	ds_read_b128 v[182:185], v197 offset:18432
	ds_read_b128 v[186:189], v197 offset:19456
	ds_read_b128 v[190:193], v197 offset:20480
	ds_read_b128 v[198:201], v197 offset:21504
	ds_read_b128 v[202:205], v197 offset:22528
	ds_read_b128 v[206:209], v197 offset:23552
	s_add_i32 s22, s23, s58
	v_lshl_add_u64 v[176:177], s[30:31], 0, v[0:1]
	s_mov_b32 m0, s22
	s_nop 0
	global_load_lds_dwordx4 v[176:177], off
	v_lshl_add_u64 v[220:221], s[30:31], 0, v[154:155]
	s_add_i32 m0, s22, 0x2000
	s_nop 0
	global_load_lds_dwordx4 v[220:221], off
	s_mov_b32 m0, s59
	v_lshl_add_u64 v[242:243], s[56:57], 0, v[158:159]
	global_load_lds_dwordx4 v[242:243], off
	v_lshl_add_u64 v[244:245], s[56:57], 0, v[156:157]
	s_mov_b32 m0, s60
	s_nop 0
	global_load_lds_dwordx4 v[244:245], off
	s_add_u32 s22, s30, 0x40000
	s_addc_u32 s23, s31, 0
	s_add_i32 s1, s1, s58
	s_mov_b32 m0, s1
	s_nop 0
	global_load_lds_dwordx4 v0, s[22:23]
	s_add_i32 m0, s1, 0x2000
	s_nop 0
	global_load_lds_dwordx4 v154, s[22:23]
	s_waitcnt vmcnt(8)
	s_waitcnt lgkmcnt(0)
	s_barrier
	s_setprio 1
	v_mfma_f32_16x16x32_bf16 v[62:65], v[130:133], v[146:149], v[62:65]
	v_mfma_f32_16x16x32_bf16 v[58:61], v[138:141], v[146:149], v[58:61]
	v_mfma_f32_16x16x32_bf16 v[46:49], v[130:133], v[182:185], v[46:49]
	v_mfma_f32_16x16x32_bf16 v[42:45], v[138:141], v[182:185], v[42:45]
	v_mfma_f32_16x16x32_bf16 v[30:33], v[130:133], v[190:193], v[30:33]
	v_mfma_f32_16x16x32_bf16 v[26:29], v[138:141], v[190:193], v[26:29]
	v_mfma_f32_16x16x32_bf16 v[14:17], v[130:133], v[202:205], v[14:17]
	v_mfma_f32_16x16x32_bf16 v[10:13], v[138:141], v[202:205], v[10:13]
	v_mfma_f32_16x16x32_bf16 v[62:65], v[134:137], v[150:153], v[62:65]
	v_mfma_f32_16x16x32_bf16 v[58:61], v[142:145], v[150:153], v[58:61]
	v_mfma_f32_16x16x32_bf16 v[46:49], v[134:137], v[186:189], v[46:49]
	v_mfma_f32_16x16x32_bf16 v[42:45], v[142:145], v[186:189], v[42:45]
	v_mfma_f32_16x16x32_bf16 v[30:33], v[134:137], v[198:201], v[30:33]
	v_mfma_f32_16x16x32_bf16 v[26:29], v[142:145], v[198:201], v[26:29]
	v_mfma_f32_16x16x32_bf16 v[14:17], v[134:137], v[206:209], v[14:17]
	v_mfma_f32_16x16x32_bf16 v[10:13], v[142:145], v[206:209], v[10:13]
	v_mfma_f32_16x16x32_bf16 v[54:57], v[216:219], v[146:149], v[54:57]
	v_mfma_f32_16x16x32_bf16 v[50:53], v[234:237], v[146:149], v[50:53]
	v_mfma_f32_16x16x32_bf16 v[38:41], v[216:219], v[182:185], v[38:41]
	v_mfma_f32_16x16x32_bf16 v[34:37], v[234:237], v[182:185], v[34:37]
	v_mfma_f32_16x16x32_bf16 v[22:25], v[216:219], v[190:193], v[22:25]
	v_mfma_f32_16x16x32_bf16 v[18:21], v[234:237], v[190:193], v[18:21]
	v_mfma_f32_16x16x32_bf16 v[6:9], v[216:219], v[202:205], v[6:9]
	v_mfma_f32_16x16x32_bf16 v[2:5], v[234:237], v[202:205], v[2:5]
	v_mfma_f32_16x16x32_bf16 v[54:57], v[230:233], v[150:153], v[54:57]
	v_mfma_f32_16x16x32_bf16 v[50:53], v[238:241], v[150:153], v[50:53]
	v_mfma_f32_16x16x32_bf16 v[38:41], v[230:233], v[186:189], v[38:41]
	v_mfma_f32_16x16x32_bf16 v[34:37], v[238:241], v[186:189], v[34:37]
	v_mfma_f32_16x16x32_bf16 v[22:25], v[230:233], v[198:201], v[22:25]
	v_mfma_f32_16x16x32_bf16 v[18:21], v[238:241], v[198:201], v[18:21]
	v_mfma_f32_16x16x32_bf16 v[6:9], v[230:233], v[206:209], v[6:9]
	v_mfma_f32_16x16x32_bf16 v[2:5], v[238:241], v[206:209], v[2:5]
	s_setprio 0
	s_barrier
	s_add_i32 s1, 0, 0x18000
	v_add_u32_e32 v142, s1, v195
	ds_read_b128 v[130:133], v142
	ds_read_b128 v[134:137], v142 offset:1024
	ds_read_b128 v[138:141], v142 offset:2048
	ds_read_b128 v[142:145], v142 offset:3072
	s_add_u32 s22, s56, 0x40000
	s_addc_u32 s23, s57, 0
	s_mov_b32 m0, s61
	v_lshl_add_u64 v[216:217], s[22:23], 0, v[158:159]
	ds_read_b128 v[146:149], v197 offset:32768
	ds_read_b128 v[150:153], v197 offset:33792
	ds_read_b128 v[182:185], v197 offset:34816
	ds_read_b128 v[186:189], v197 offset:35840
	ds_read_b128 v[190:193], v197 offset:36864
	ds_read_b128 v[198:201], v197 offset:37888
	ds_read_b128 v[202:205], v197 offset:38912
	ds_read_b128 v[206:209], v197 offset:39936
	global_load_lds_dwordx4 v[216:217], off
	v_lshl_add_u64 v[216:217], s[22:23], 0, v[156:157]
	s_mov_b32 m0, s62
	s_nop 0
	global_load_lds_dwordx4 v[216:217], off
	s_add_i32 s33, 0, 0x1c000
	v_add_u32_e32 v168, s33, v195
	ds_read_b128 v[216:219], v168
	ds_read_b128 v[230:233], v168 offset:1024
	ds_read_b128 v[234:237], v168 offset:2048
	ds_read_b128 v[238:241], v168 offset:3072
	s_waitcnt vmcnt(8)
	s_waitcnt lgkmcnt(0)
	s_barrier
	s_setprio 1
	v_mfma_f32_16x16x32_bf16 v[126:129], v[130:133], v[146:149], v[126:129]
	v_mfma_f32_16x16x32_bf16 v[122:125], v[138:141], v[146:149], v[122:125]
	v_mfma_f32_16x16x32_bf16 v[110:113], v[130:133], v[182:185], v[110:113]
	v_mfma_f32_16x16x32_bf16 v[106:109], v[138:141], v[182:185], v[106:109]
	v_mfma_f32_16x16x32_bf16 v[94:97], v[130:133], v[190:193], v[94:97]
	v_mfma_f32_16x16x32_bf16 v[90:93], v[138:141], v[190:193], v[90:93]
	v_mfma_f32_16x16x32_bf16 v[78:81], v[130:133], v[202:205], v[78:81]
	v_mfma_f32_16x16x32_bf16 v[74:77], v[138:141], v[202:205], v[74:77]
	v_mfma_f32_16x16x32_bf16 v[126:129], v[134:137], v[150:153], v[126:129]
	v_mfma_f32_16x16x32_bf16 v[122:125], v[142:145], v[150:153], v[122:125]
	v_mfma_f32_16x16x32_bf16 v[110:113], v[134:137], v[186:189], v[110:113]
	v_mfma_f32_16x16x32_bf16 v[106:109], v[142:145], v[186:189], v[106:109]
	v_mfma_f32_16x16x32_bf16 v[94:97], v[134:137], v[198:201], v[94:97]
	v_mfma_f32_16x16x32_bf16 v[90:93], v[142:145], v[198:201], v[90:93]
	v_mfma_f32_16x16x32_bf16 v[78:81], v[134:137], v[206:209], v[78:81]
	v_mfma_f32_16x16x32_bf16 v[74:77], v[142:145], v[206:209], v[74:77]
	v_mfma_f32_16x16x32_bf16 v[118:121], v[216:219], v[146:149], v[118:121]
	v_mfma_f32_16x16x32_bf16 v[114:117], v[234:237], v[146:149], v[114:117]
	v_mfma_f32_16x16x32_bf16 v[102:105], v[216:219], v[182:185], v[102:105]
	v_mfma_f32_16x16x32_bf16 v[98:101], v[234:237], v[182:185], v[98:101]
	v_mfma_f32_16x16x32_bf16 v[86:89], v[216:219], v[190:193], v[86:89]
	v_mfma_f32_16x16x32_bf16 v[82:85], v[234:237], v[190:193], v[82:85]
	v_mfma_f32_16x16x32_bf16 v[70:73], v[216:219], v[202:205], v[70:73]
	v_mfma_f32_16x16x32_bf16 v[66:69], v[234:237], v[202:205], v[66:69]
	v_mfma_f32_16x16x32_bf16 v[118:121], v[230:233], v[150:153], v[118:121]
	v_mfma_f32_16x16x32_bf16 v[114:117], v[238:241], v[150:153], v[114:117]
	v_mfma_f32_16x16x32_bf16 v[102:105], v[230:233], v[186:189], v[102:105]
	v_mfma_f32_16x16x32_bf16 v[98:101], v[238:241], v[186:189], v[98:101]
	v_mfma_f32_16x16x32_bf16 v[86:89], v[230:233], v[198:201], v[86:89]
	v_mfma_f32_16x16x32_bf16 v[82:85], v[238:241], v[198:201], v[82:85]
	v_mfma_f32_16x16x32_bf16 v[70:73], v[230:233], v[206:209], v[70:73]
	v_mfma_f32_16x16x32_bf16 v[66:69], v[238:241], v[206:209], v[66:69]
	s_setprio 0
	s_barrier
	ds_read_b128 v[146:149], v197 offset:49152
	ds_read_b128 v[150:153], v197 offset:50176
	ds_read_b128 v[182:185], v197 offset:51200
	ds_read_b128 v[186:189], v197 offset:52224
	ds_read_b128 v[190:193], v197 offset:53248
	ds_read_b128 v[198:201], v197 offset:54272
	ds_read_b128 v[202:205], v197 offset:55296
	ds_read_b128 v[206:209], v197 offset:56320
	s_add_i32 s1, s1, s58
	v_lshl_add_u64 v[176:177], v[176:177], 0, s[12:13]
	s_mov_b32 m0, s1
	s_nop 0
	global_load_lds_dwordx4 v[176:177], off
	v_lshl_add_u64 v[176:177], v[220:221], 0, s[12:13]
	s_add_i32 m0, s1, 0x2000
	s_nop 0
	global_load_lds_dwordx4 v[176:177], off
	s_mov_b32 m0, s64
	v_lshl_add_u64 v[176:177], v[242:243], 0, s[12:13]
	global_load_lds_dwordx4 v[176:177], off
	v_lshl_add_u64 v[176:177], v[244:245], 0, s[12:13]
	s_mov_b32 m0, s65
	s_nop 0
	global_load_lds_dwordx4 v[176:177], off
	s_add_u32 s22, s30, 0x40080
	s_addc_u32 s23, s31, 0
	s_add_i32 s1, s33, s58
	s_mov_b32 m0, s1
	s_nop 0
	global_load_lds_dwordx4 v0, s[22:23]
	s_add_i32 m0, s1, 0x2000
	s_nop 0
	global_load_lds_dwordx4 v154, s[22:23]
	s_waitcnt vmcnt(8)
	s_waitcnt lgkmcnt(0)
	s_barrier
	s_setprio 1
	v_mfma_f32_16x16x32_bf16 v[62:65], v[130:133], v[146:149], v[62:65]
	v_mfma_f32_16x16x32_bf16 v[58:61], v[138:141], v[146:149], v[58:61]
	v_mfma_f32_16x16x32_bf16 v[46:49], v[130:133], v[182:185], v[46:49]
	v_mfma_f32_16x16x32_bf16 v[42:45], v[138:141], v[182:185], v[42:45]
	v_mfma_f32_16x16x32_bf16 v[30:33], v[130:133], v[190:193], v[30:33]
	v_mfma_f32_16x16x32_bf16 v[26:29], v[138:141], v[190:193], v[26:29]
	v_mfma_f32_16x16x32_bf16 v[14:17], v[130:133], v[202:205], v[14:17]
	v_mfma_f32_16x16x32_bf16 v[10:13], v[138:141], v[202:205], v[10:13]
	v_mfma_f32_16x16x32_bf16 v[62:65], v[134:137], v[150:153], v[62:65]
	v_mfma_f32_16x16x32_bf16 v[58:61], v[142:145], v[150:153], v[58:61]
	v_mfma_f32_16x16x32_bf16 v[46:49], v[134:137], v[186:189], v[46:49]
	v_mfma_f32_16x16x32_bf16 v[42:45], v[142:145], v[186:189], v[42:45]
	v_mfma_f32_16x16x32_bf16 v[30:33], v[134:137], v[198:201], v[30:33]
	v_mfma_f32_16x16x32_bf16 v[26:29], v[142:145], v[198:201], v[26:29]
	v_mfma_f32_16x16x32_bf16 v[14:17], v[134:137], v[206:209], v[14:17]
	v_mfma_f32_16x16x32_bf16 v[10:13], v[142:145], v[206:209], v[10:13]
	v_mfma_f32_16x16x32_bf16 v[54:57], v[216:219], v[146:149], v[54:57]
	v_mfma_f32_16x16x32_bf16 v[50:53], v[234:237], v[146:149], v[50:53]
	v_mfma_f32_16x16x32_bf16 v[38:41], v[216:219], v[182:185], v[38:41]
	v_mfma_f32_16x16x32_bf16 v[34:37], v[234:237], v[182:185], v[34:37]
	v_mfma_f32_16x16x32_bf16 v[22:25], v[216:219], v[190:193], v[22:25]
	v_mfma_f32_16x16x32_bf16 v[18:21], v[234:237], v[190:193], v[18:21]
	v_mfma_f32_16x16x32_bf16 v[6:9], v[216:219], v[202:205], v[6:9]
	v_mfma_f32_16x16x32_bf16 v[2:5], v[234:237], v[202:205], v[2:5]
	v_mfma_f32_16x16x32_bf16 v[54:57], v[230:233], v[150:153], v[54:57]
	v_mfma_f32_16x16x32_bf16 v[50:53], v[238:241], v[150:153], v[50:53]
	v_mfma_f32_16x16x32_bf16 v[38:41], v[230:233], v[186:189], v[38:41]
	v_mfma_f32_16x16x32_bf16 v[34:37], v[238:241], v[186:189], v[34:37]
	v_mfma_f32_16x16x32_bf16 v[22:25], v[230:233], v[198:201], v[22:25]
	v_mfma_f32_16x16x32_bf16 v[18:21], v[238:241], v[198:201], v[18:21]
	v_mfma_f32_16x16x32_bf16 v[6:9], v[230:233], v[206:209], v[6:9]
	v_mfma_f32_16x16x32_bf16 v[2:5], v[238:241], v[206:209], v[2:5]
	s_setprio 0
	s_add_i32 s69, s69, 2
	s_add_u32 s28, s28, 0x100
	s_addc_u32 s29, s29, 0
	s_add_u32 s67, s67, 0x100
	s_addc_u32 s68, s68, 0
	s_cmp_gt_u32 s69, 13
	s_barrier
	s_cbranch_scc0 .LBB0_47
	s_cmpk_gt_u32 s0, 0xff
	s_cbranch_scc1 .Lrs_i1_post
	s_barrier
.Lrs_i1_post:
	v_lshl_add_u32 v184, s20, 8, v194
	v_ashrrev_i32_e32 v185, 31, v184
	v_or_b32_e32 v188, 16, v184
	v_lshlrev_b64 v[190:191], 6, v[184:185]
	v_ashrrev_i32_e32 v189, 31, v188
	v_lshl_add_u64 v[130:131], v[160:161], 0, v[190:191]
	v_lshlrev_b64 v[186:187], 6, v[188:189]
	global_load_dwordx4 v[200:203], v[130:131], off
	v_lshl_add_u64 v[130:131], v[160:161], 0, v[186:187]
	global_load_dwordx4 v[204:207], v[130:131], off
	v_lshl_or_b32 v182, s4, 8, v196
	v_ashrrev_i32_e32 v183, 31, v182
	v_lshlrev_b64 v[130:131], 10, v[184:185]
	v_lshl_add_u64 v[130:131], v[130:131], 0, v[182:183]
	v_lshlrev_b64 v[130:131], 1, v[130:131]
	v_lshl_add_u64 v[132:133], s[96:97], 0, v[130:131]
	global_load_dwordx4 v[216:219], v[132:133], off
	global_load_dwordx4 v[146:149], v[132:133], off offset:256
	v_lshl_add_u64 v[134:135], s[24:25], 0, v[130:131]
	global_load_dwordx4 v[230:233], v[134:135], off
	v_and_b32_e32 v135, 64, v212
	v_xor_b32_e32 v134, 16, v212
	v_add_u32_e32 v135, 64, v135
	v_xor_b32_e32 v136, 32, v212
	v_cmp_lt_i32_e32 vcc, v134, v135
	v_or_b32_e32 v130, 0x100, v130
	v_lshl_add_u64 v[130:131], s[24:25], 0, v[130:131]
	v_cndmask_b32_e32 v134, v212, v134, vcc
	v_cmp_lt_i32_e32 vcc, v136, v135
	v_lshlrev_b32_e32 v199, 2, v134
	s_mov_b32 s20, 0x3a800000
	v_cndmask_b32_e32 v135, v212, v136, vcc
	v_lshlrev_b32_e32 v198, 2, v135
	v_lshlrev_b64 v[134:135], 10, v[188:189]
	v_lshl_add_u64 v[134:135], v[134:135], 0, v[182:183]
	v_lshlrev_b64 v[134:135], 1, v[134:135]
	v_lshl_add_u64 v[132:133], s[96:97], 0, v[134:135]
	global_load_dwordx4 v[150:153], v[130:131], off
	global_load_dwordx4 v[138:141], v[132:133], off
	s_nop 0
	global_load_dwordx4 v[130:133], v[132:133], off offset:256
	v_lshl_add_u64 v[136:137], s[24:25], 0, v[134:135]
	v_or_b32_e32 v134, 0x100, v134
	v_lshl_add_u64 v[134:135], s[24:25], 0, v[134:135]
	global_load_dwordx4 v[142:145], v[136:137], off
	s_nop 0
	global_load_dwordx4 v[134:137], v[134:135], off
	s_lshl_b32 s28, s4, 2
	s_ashr_i32 s29, s28, 31
	s_waitcnt vmcnt(0)
	v_mov_b32_e32 v176, v201
	v_mov_b32_e32 v177, v202
	v_mov_b32_e32 v201, v203
	v_mov_b32_e32 v192, v205
	v_mov_b32_e32 v193, v206
	v_mov_b32_e32 v205, v207
	v_pk_add_f32 v[176:177], v[176:177], v[200:201]
	v_pk_add_f32 v[192:193], v[192:193], v[204:205]
	v_mov_b32_e32 v201, v176
	v_mov_b32_e32 v200, v192
	v_mov_b32_e32 v176, v193
	v_pk_add_f32 v[176:177], v[200:201], v[176:177]
	ds_bpermute_b32 v193, v199, v177
	ds_bpermute_b32 v192, v199, v176
	v_lshlrev_b32_e32 v208, 16, v218
	v_and_b32_e32 v209, 0xffff0000, v218
	v_lshlrev_b32_e32 v202, 16, v216
	v_and_b32_e32 v203, 0xffff0000, v216
	s_waitcnt lgkmcnt(0)
	v_pk_add_f32 v[176:177], v[176:177], v[192:193]
	ds_bpermute_b32 v193, v198, v177
	ds_bpermute_b32 v192, v198, v176
	v_lshlrev_b32_e32 v204, 16, v230
	v_and_b32_e32 v205, 0xffff0000, v230
	v_lshlrev_b32_e32 v200, 16, v217
	v_and_b32_e32 v201, 0xffff0000, v217
	s_waitcnt lgkmcnt(0)
	v_pk_add_f32 v[176:177], v[176:177], v[192:193]
	v_lshlrev_b32_e32 v206, 16, v231
	v_pk_fma_f32 v[192:193], v[176:177], s[20:21], v[166:167] op_sel_hi:[1,0,0]
	v_lshlrev_b32_e32 v176, 16, v219
	v_mul_f32_e32 v168, 0x4b800000, v193
	v_cmp_gt_f32_e32 vcc, s39, v193
	v_and_b32_e32 v177, 0xffff0000, v219
	v_and_b32_e32 v207, 0xffff0000, v231
	v_cndmask_b32_e32 v168, v193, v168, vcc
	v_rsq_f32_e32 v168, v168
	v_lshlrev_b32_e32 v216, 16, v232
	v_and_b32_e32 v217, 0xffff0000, v232
	v_mul_f32_e32 v169, 0x45800000, v168
	v_cndmask_b32_e32 v218, v168, v169, vcc
	v_pk_mul_f32 v[126:127], v[126:127], v[218:219] op_sel_hi:[1,0]
	v_pk_mul_f32 v[128:129], v[128:129], v[218:219] op_sel_hi:[1,0]
	v_pk_mul_f32 v[122:123], v[122:123], v[218:219] op_sel_hi:[1,0]
	v_mul_f32_e32 v126, 0xbfb8aa3b, v126
	v_mul_f32_e32 v127, 0xbfb8aa3b, v127
	v_pk_mul_f32 v[124:125], v[124:125], v[218:219] op_sel_hi:[1,0]
	v_mul_f32_e32 v128, 0xbfb8aa3b, v128
	v_mul_f32_e32 v129, 0xbfb8aa3b, v129
	v_mul_f32_e32 v122, 0xbfb8aa3b, v122
	v_mul_f32_e32 v123, 0xbfb8aa3b, v123
	v_exp_f32_e32 v126, v126
	v_exp_f32_e32 v127, v127
	v_mul_f32_e32 v124, 0xbfb8aa3b, v124
	v_mul_f32_e32 v125, 0xbfb8aa3b, v125
	v_exp_f32_e32 v128, v128
	v_exp_f32_e32 v129, v129
	v_exp_f32_e32 v122, v122
	v_exp_f32_e32 v123, v123
	v_exp_f32_e32 v124, v124
	v_exp_f32_e32 v125, v125
	v_add_f32_e32 v126, 1.0, v126
	v_add_f32_e32 v127, 1.0, v127
	v_add_f32_e32 v128, 1.0, v128
	v_add_f32_e32 v129, 1.0, v129
	v_add_f32_e32 v168, 1.0, v122
	v_add_f32_e32 v169, 1.0, v123
	v_rcp_f32_e32 v122, v126
	v_rcp_f32_e32 v123, v127
	v_add_f32_e32 v193, 1.0, v124
	v_add_f32_e32 v219, 1.0, v125
	v_rcp_f32_e32 v124, v128
	v_rcp_f32_e32 v125, v129
	v_rcp_f32_e32 v126, v168
	v_rcp_f32_e32 v127, v169
	v_rcp_f32_e32 v128, v193
	v_rcp_f32_e32 v129, v219
	v_pk_fma_f32 v[122:123], v[122:123], v[204:205], v[202:203]
	v_pk_fma_f32 v[124:125], v[124:125], v[206:207], v[200:201]
	v_pk_fma_f32 v[126:127], v[126:127], v[216:217], v[208:209]
	v_lshlrev_b32_e32 v200, 16, v233
	v_and_b32_e32 v201, 0xffff0000, v233
	v_cvt_pk_bf16_f32 v122, v122, v123
	v_pk_fma_f32 v[128:129], v[128:129], v[200:201], v[176:177]
	v_cvt_pk_bf16_f32 v123, v124, v125
	v_cvt_pk_bf16_f32 v124, v126, v127
	v_and_b32_e32 v127, 0xffff0000, v122
	v_pk_mul_f32 v[118:119], v[118:119], v[218:219] op_sel_hi:[1,0]
	v_cvt_pk_bf16_f32 v125, v128, v129
	v_lshlrev_b32_e32 v126, 16, v122
	v_mul_f32_e32 v127, v127, v127
	v_and_b32_e32 v128, 0xffff0000, v123
	v_mul_f32_e32 v118, 0xbfb8aa3b, v118
	v_mul_f32_e32 v119, 0xbfb8aa3b, v119
	v_fmac_f32_e32 v127, v126, v126
	v_lshlrev_b32_e32 v126, 16, v123
	v_mul_f32_e32 v128, v128, v128
	v_exp_f32_e32 v118, v118
	v_exp_f32_e32 v119, v119
	v_fmac_f32_e32 v128, v126, v126
	v_add_f32_e32 v126, v127, v128
	v_and_b32_e32 v128, 0xffff0000, v124
	v_pk_mul_f32 v[120:121], v[120:121], v[218:219] op_sel_hi:[1,0]
	v_lshlrev_b32_e32 v127, 16, v124
	v_mul_f32_e32 v128, v128, v128
	v_mul_f32_e32 v120, 0xbfb8aa3b, v120
	v_mul_f32_e32 v121, 0xbfb8aa3b, v121
	v_fmac_f32_e32 v128, v127, v127
	v_add_f32_e32 v118, 1.0, v118
	v_add_f32_e32 v119, 1.0, v119
	v_exp_f32_e32 v120, v120
	v_exp_f32_e32 v121, v121
	v_add_f32_e32 v126, v128, v126
	v_and_b32_e32 v128, 0xffff0000, v125
	v_rcp_f32_e32 v118, v118
	v_rcp_f32_e32 v119, v119
	v_lshlrev_b32_e32 v127, 16, v125
	v_mul_f32_e32 v128, v128, v128
	v_pk_mul_f32 v[114:115], v[114:115], v[218:219] op_sel_hi:[1,0]
	v_fmac_f32_e32 v128, v127, v127
	v_mul_f32_e32 v114, 0xbfb8aa3b, v114
	v_add_f32_e32 v168, v128, v126
	v_pk_mul_f32 v[116:117], v[116:117], v[218:219] op_sel_hi:[1,0]
	v_lshlrev_b32_e32 v126, 16, v146
	v_and_b32_e32 v127, 0xffff0000, v146
	v_lshlrev_b32_e32 v128, 16, v150
	v_and_b32_e32 v129, 0xffff0000, v150
	v_add_f32_e32 v120, 1.0, v120
	v_add_f32_e32 v121, 1.0, v121
	v_exp_f32_e32 v146, v114
	v_mul_f32_e32 v114, 0xbfb8aa3b, v115
	v_pk_fma_f32 v[118:119], v[118:119], v[128:129], v[126:127]
	v_rcp_f32_e32 v120, v120
	v_rcp_f32_e32 v121, v121
	v_lshlrev_b32_e32 v126, 16, v147
	v_and_b32_e32 v127, 0xffff0000, v147
	v_exp_f32_e32 v147, v114
	v_mul_f32_e32 v116, 0xbfb8aa3b, v116
	v_mul_f32_e32 v117, 0xbfb8aa3b, v117
	v_exp_f32_e32 v116, v116
	v_exp_f32_e32 v117, v117
	v_lshlrev_b32_e32 v128, 16, v151
	v_and_b32_e32 v129, 0xffff0000, v151
	v_pk_fma_f32 v[114:115], v[120:121], v[128:129], v[126:127]
	v_add_f32_e32 v120, 1.0, v146
	v_add_f32_e32 v121, 1.0, v147
	v_rcp_f32_e32 v120, v120
	v_rcp_f32_e32 v121, v121
	v_add_f32_e32 v116, 1.0, v116
	v_add_f32_e32 v117, 1.0, v117
	v_rcp_f32_e32 v116, v116
	v_rcp_f32_e32 v117, v117
	v_lshlrev_b32_e32 v126, 16, v148
	v_and_b32_e32 v127, 0xffff0000, v148
	v_lshlrev_b32_e32 v128, 16, v152
	v_and_b32_e32 v129, 0xffff0000, v152
	v_pk_fma_f32 v[120:121], v[120:121], v[128:129], v[126:127]
	v_lshlrev_b32_e32 v126, 16, v149
	v_and_b32_e32 v127, 0xffff0000, v149
	v_lshlrev_b32_e32 v128, 16, v153
	v_and_b32_e32 v129, 0xffff0000, v153
	v_pk_fma_f32 v[126:127], v[116:117], v[128:129], v[126:127]
	v_cvt_pk_bf16_f32 v116, v118, v119
	v_cvt_pk_bf16_f32 v117, v114, v115
	v_and_b32_e32 v115, 0xffff0000, v116
	v_lshlrev_b32_e32 v114, 16, v116
	v_mul_f32_e32 v115, v115, v115
	v_cvt_pk_bf16_f32 v118, v120, v121
	v_fmac_f32_e32 v115, v114, v114
	v_and_b32_e32 v120, 0xffff0000, v117
	v_add_f32_e32 v114, v115, v168
	v_lshlrev_b32_e32 v115, 16, v117
	v_mul_f32_e32 v120, v120, v120
	v_fmac_f32_e32 v120, v115, v115
	v_add_f32_e32 v114, v120, v114
	v_and_b32_e32 v120, 0xffff0000, v118
	v_lshlrev_b32_e32 v115, 16, v118
	v_mul_f32_e32 v120, v120, v120
	v_cvt_pk_bf16_f32 v119, v126, v127
	v_fmac_f32_e32 v120, v115, v115
	v_add_f32_e32 v114, v120, v114
	v_and_b32_e32 v120, 0xffff0000, v119
	v_lshlrev_b32_e32 v115, 16, v119
	v_mul_f32_e32 v120, v120, v120
	v_fmac_f32_e32 v120, v115, v115
	v_add_f32_e32 v114, v120, v114
	ds_bpermute_b32 v115, v199, v114
	v_lshlrev_b64 v[120:121], 11, v[184:185]
	v_lshl_add_u64 v[120:121], s[36:37], 0, v[120:121]
	v_cmp_gt_f32_e32 vcc, s39, v192
	v_lshl_add_u64 v[120:121], v[182:183], 1, v[120:121]
	s_waitcnt lgkmcnt(0)
	v_add_f32_e32 v114, v114, v115
	ds_bpermute_b32 v115, v198, v114
	global_store_dwordx4 v[120:121], v[122:125], off
	global_store_dwordx4 v[120:121], v[116:119], off offset:256
	s_and_saveexec_b64 s[30:31], s[40:41]
	s_cbranch_execz .LBB0_50
	v_lshl_add_u64 v[116:117], s[44:45], 0, v[190:191]
	v_lshl_add_u64 v[116:117], s[28:29], 2, v[116:117]
	s_lshl_b32 s4, s63, 2
	v_lshl_add_u64 v[116:117], v[116:117], 0, s[4:5]
	s_waitcnt lgkmcnt(0)
	v_add_f32_e32 v114, v114, v115
	global_store_dword v[116:117], v114, off

.LBB0_64:
	s_waitcnt vmcnt(0)
	s_mov_b32 s48, 0x6dc9c883
	s_cmpk_gt_u32 s0, 0xff
	s_mov_b32 s49, 0x3fc45f30
	s_cbranch_scc1 .LBB0_66
	s_nop 0

.LBB0_76:
	s_mov_b32 s4, s82
	v_mov_b32_e32 v16, v167
	s_andn2_b64 vcc, exec, s[90:91]
	v_readfirstlane_b32 s0, v16
	s_cbranch_vccnz .LBB0_88
	v_lshlrev_b32_e32 v0, 4, v16
	v_add_u32_e32 v2, 0x2000, v0
	s_waitcnt lgkmcnt(0)
	v_ashrrev_i32_e32 v3, 31, v2
	v_lshrrev_b32_e32 v3, 22, v3
	v_add_u32_e32 v3, v2, v3
	v_ashrrev_i32_e32 v10, 10, v3
	v_mul_i32_i24_e32 v3, 0x400, v10
	v_sub_u32_e32 v2, v2, v3
	v_lshrrev_b32_e32 v3, 4, v2
	v_bitop3_b32 v2, v3, v2, 32 bitop3:0x6c
	v_ashrrev_i32_e32 v3, 31, v2
	s_cmp_gt_i32 s4, 10
	v_lshrrev_b32_e32 v3, 26, v3
	s_cselect_b64 s[6:7], -1, 0
	v_add_u32_e32 v3, v2, v3
	v_lshlrev_b32_e32 v4, 3, v10
	s_and_b64 s[16:17], s[6:7], exec
	s_mov_b32 s1, 0x2800000
	v_ashrrev_i32_e32 v11, 6, v3
	v_and_b32_e32 v4, -16, v4
	s_cselect_b32 s1, s1, 0x1d00000
	v_add_u32_e32 v4, v11, v4
	s_add_u32 s4, s10, s1
	v_and_b32_e32 v5, 3, v11
	s_mov_b32 s1, 0x1fffe0
	v_lshrrev_b32_e32 v6, 2, v4
	v_lshlrev_b32_e32 v7, 1, v4
	v_and_b32_e32 v3, 0xc0, v3
	v_and_or_b32 v5, v4, s1, v5
	v_and_b32_e32 v6, 4, v6
	v_and_b32_e32 v7, 24, v7
	v_sub_u32_e32 v2, v2, v3
	v_or3_b32 v5, v5, v6, v7
	v_lshlrev_b32_e32 v6, 5, v10
	v_ashrrev_i16_sdwa v2, v211, sext(v2) dst_sel:DWORD dst_unused:UNUSED_PAD src0_sel:DWORD src1_sel:BYTE_0
	v_and_b32_e32 v6, 32, v6
	v_bfe_i32 v12, v2, 0, 16
	v_add_lshl_u32 v2, v6, v12, 1
	v_lshl_add_u32 v154, v5, 11, v2
	v_lshl_add_u32 v156, v4, 11, v2
	v_bfe_i32 v2, v16, 27, 1
	v_lshrrev_b32_e32 v2, 22, v2
	v_add_u32_e32 v2, v0, v2
	v_and_b32_e32 v2, 0xfffffc00, v2
	v_sub_u32_e32 v0, v0, v2
	v_lshrrev_b32_e32 v2, 4, v0
	v_ashrrev_i32_e32 v3, 31, v16
	v_bitop3_b32 v0, v2, v0, 32 bitop3:0x6c
	v_lshrrev_b32_e32 v3, 26, v3
	v_ashrrev_i32_e32 v2, 31, v0
	v_add_u32_e32 v3, v16, v3
	v_lshrrev_b32_e32 v2, 26, v2
	v_ashrrev_i32_e32 v14, 6, v3
	v_add_u32_e32 v2, v0, v2
	v_lshlrev_b32_e32 v3, 3, v14
	v_ashrrev_i32_e32 v13, 6, v2
	v_and_b32_e32 v3, -16, v3
	v_add_u32_e32 v3, v13, v3
	v_and_b32_e32 v4, 3, v13
	v_lshrrev_b32_e32 v5, 2, v3
	v_lshlrev_b32_e32 v6, 1, v3
	v_and_b32_e32 v2, 0xc0, v2
	s_addc_u32 s16, s11, 0
	s_ashr_i32 s20, s0, 6
	v_and_or_b32 v4, v3, s1, v4
	v_and_b32_e32 v5, 4, v5
	v_and_b32_e32 v6, 24, v6
	v_sub_u32_e32 v0, v0, v2
	s_ashr_i32 s21, s0, 8
	s_lshl_b32 s17, s20, 10
	v_or3_b32 v4, v4, v5, v6
	v_lshlrev_b32_e32 v5, 5, v14
	v_ashrrev_i16_sdwa v0, v211, sext(v0) dst_sel:DWORD dst_unused:UNUSED_PAD src0_sel:DWORD src1_sel:BYTE_0
	v_readlane_b32 s22, v253, 1
	v_and_b32_e32 v5, 32, v5
	v_bfe_i32 v15, v0, 0, 16
	v_readlane_b32 s23, v253, 2
	s_add_u32 s30, s4, s22
	v_add_lshl_u32 v2, v5, v15, 1
	s_addc_u32 s31, s16, s23
	s_add_i32 s46, s17, 0
	v_lshl_add_u32 v0, v4, 11, v2
	s_add_i32 m0, s46, 0x10000
	v_readlane_b32 s22, v253, 6
	global_load_lds_dwordx4 v0, s[30:31]
	s_add_i32 m0, s46, 0x12000
	v_readlane_b32 s23, v253, 7
	s_add_u32 s28, s96, s22
	v_lshl_add_u32 v158, v3, 11, v2
	global_load_lds_dwordx4 v154, s[30:31]
	s_addc_u32 s29, s97, s23
	s_mov_b32 m0, s46
	s_add_i32 s47, s46, 0x2000
	global_load_lds_dwordx4 v158, s[28:29]
	s_mov_b32 m0, s47
	s_add_u32 s22, s30, 0x40000
	global_load_lds_dwordx4 v156, s[28:29]
	s_addc_u32 s23, s31, 0
	s_add_i32 m0, s46, 0x14000
	v_mov_b32_e32 v155, v1
	global_load_lds_dwordx4 v0, s[22:23]
	s_add_i32 m0, s46, 0x16000
	v_mov_b32_e32 v159, v1
	global_load_lds_dwordx4 v154, s[22:23]
	s_add_u32 s22, s28, 0x40000
	s_addc_u32 s23, s29, 0
	s_add_i32 s48, s46, 0x4000
	s_mov_b32 m0, s48
	s_add_i32 s49, s46, 0x6000
	global_load_lds_dwordx4 v158, s[22:23]
	s_mov_b32 m0, s49
	v_mov_b32_e32 v157, v1
	global_load_lds_dwordx4 v156, s[22:23]
	s_mov_b64 s[62:63], s[56:57]
	v_lshl_add_u64 v[8:9], s[30:31], 0, v[0:1]
	v_lshl_add_u64 v[6:7], s[30:31], 0, v[154:155]
	v_lshl_add_u64 v[4:5], s[28:29], 0, v[158:159]
	s_cmp_lg_u32 s21, 1
	v_lshl_add_u64 v[2:3], s[28:29], 0, v[156:157]
	s_cbranch_scc1 .LBB0_79
	s_nop 0

.LBB0_82:
	s_ashr_i32 s27, s26, 31
	v_mov_b64_e32 v[2:3], 0xb00
	s_lshl_b64 s[22:23], s[26:27], 19
	v_cmp_lt_i64_e32 vcc, s[36:37], v[2:3]
	s_add_u32 s36, s96, s22
	s_addc_u32 s37, s97, s23
	s_and_b64 s[22:23], vcc, exec
	s_cselect_b32 s27, s37, s29
	s_cselect_b32 s56, s36, s28
	s_ashr_i32 s7, s6, 31
	s_lshl_b64 s[22:23], s[6:7], 19
	s_add_u32 s44, s4, s22
	s_addc_u32 s45, s16, s23
	s_and_b64 s[22:23], vcc, exec
	s_cselect_b32 s7, s45, s31
	s_cselect_b32 s57, s44, s30
	s_add_u32 s28, s28, 0x40080
	s_addc_u32 s29, s29, 0
	s_add_u32 s58, s30, 0x100
	v_mov_b32_e32 v2, 0
	s_addc_u32 s59, s31, 0
	s_mov_b32 s60, -2
	v_mov_b32_e32 v3, v2
	v_mov_b32_e32 v4, v2
	v_mov_b32_e32 v5, v2
	v_mov_b32_e32 v10, v2
	v_mov_b32_e32 v11, v2
	v_mov_b32_e32 v12, v2
	v_mov_b32_e32 v13, v2
	v_mov_b32_e32 v18, v2
	v_mov_b32_e32 v19, v2
	v_mov_b32_e32 v20, v2
	v_mov_b32_e32 v21, v2
	v_mov_b32_e32 v26, v2
	v_mov_b32_e32 v27, v2
	v_mov_b32_e32 v28, v2
	v_mov_b32_e32 v29, v2
	v_mov_b32_e32 v34, v2
	v_mov_b32_e32 v35, v2
	v_mov_b32_e32 v36, v2
	v_mov_b32_e32 v37, v2
	v_mov_b32_e32 v42, v2
	v_mov_b32_e32 v43, v2
	v_mov_b32_e32 v44, v2
	v_mov_b32_e32 v45, v2
	v_mov_b32_e32 v50, v2
	v_mov_b32_e32 v51, v2
	v_mov_b32_e32 v52, v2
	v_mov_b32_e32 v53, v2
	v_mov_b32_e32 v58, v2
	v_mov_b32_e32 v59, v2
	v_mov_b32_e32 v60, v2
	v_mov_b32_e32 v61, v2
	v_mov_b32_e32 v6, v2
	v_mov_b32_e32 v7, v2
	v_mov_b32_e32 v8, v2
	v_mov_b32_e32 v9, v2
	v_mov_b32_e32 v14, v2
	v_mov_b32_e32 v15, v2
	v_mov_b32_e32 v16, v2
	v_mov_b32_e32 v17, v2
	v_mov_b32_e32 v22, v2
	v_mov_b32_e32 v23, v2
	v_mov_b32_e32 v24, v2
	v_mov_b32_e32 v25, v2
	v_mov_b32_e32 v30, v2
	v_mov_b32_e32 v31, v2
	v_mov_b32_e32 v32, v2
	v_mov_b32_e32 v33, v2
	v_mov_b32_e32 v38, v2
	v_mov_b32_e32 v39, v2
	v_mov_b32_e32 v40, v2
	v_mov_b32_e32 v41, v2
	v_mov_b32_e32 v46, v2
	v_mov_b32_e32 v47, v2
	v_mov_b32_e32 v48, v2
	v_mov_b32_e32 v49, v2
	v_mov_b32_e32 v54, v2
	v_mov_b32_e32 v55, v2
	v_mov_b32_e32 v56, v2
	v_mov_b32_e32 v57, v2
	v_mov_b32_e32 v62, v2
	v_mov_b32_e32 v63, v2
	v_mov_b32_e32 v64, v2
	v_mov_b32_e32 v65, v2
	v_mov_b32_e32 v66, v2
	v_mov_b32_e32 v67, v2
	v_mov_b32_e32 v68, v2
	v_mov_b32_e32 v69, v2
	v_mov_b32_e32 v74, v2
	v_mov_b32_e32 v75, v2
	v_mov_b32_e32 v76, v2
	v_mov_b32_e32 v77, v2
	v_mov_b32_e32 v82, v2
	v_mov_b32_e32 v83, v2
	v_mov_b32_e32 v84, v2
	v_mov_b32_e32 v85, v2
	v_mov_b32_e32 v90, v2
	v_mov_b32_e32 v91, v2
	v_mov_b32_e32 v92, v2
	v_mov_b32_e32 v93, v2
	v_mov_b32_e32 v98, v2
	v_mov_b32_e32 v99, v2
	v_mov_b32_e32 v100, v2
	v_mov_b32_e32 v101, v2
	v_mov_b32_e32 v106, v2
	v_mov_b32_e32 v107, v2
	v_mov_b32_e32 v108, v2
	v_mov_b32_e32 v109, v2
	v_mov_b32_e32 v114, v2
	v_mov_b32_e32 v115, v2
	v_mov_b32_e32 v116, v2
	v_mov_b32_e32 v117, v2
	v_mov_b32_e32 v122, v2
	v_mov_b32_e32 v123, v2
	v_mov_b32_e32 v124, v2
	v_mov_b32_e32 v125, v2
	v_mov_b32_e32 v70, v2
	v_mov_b32_e32 v71, v2
	v_mov_b32_e32 v72, v2
	v_mov_b32_e32 v73, v2
	v_mov_b32_e32 v78, v2
	v_mov_b32_e32 v79, v2
	v_mov_b32_e32 v80, v2
	v_mov_b32_e32 v81, v2
	v_mov_b32_e32 v86, v2
	v_mov_b32_e32 v87, v2
	v_mov_b32_e32 v88, v2
	v_mov_b32_e32 v89, v2
	v_mov_b32_e32 v94, v2
	v_mov_b32_e32 v95, v2
	v_mov_b32_e32 v96, v2
	v_mov_b32_e32 v97, v2
	v_mov_b32_e32 v102, v2
	v_mov_b32_e32 v103, v2
	v_mov_b32_e32 v104, v2
	v_mov_b32_e32 v105, v2
	v_mov_b32_e32 v110, v2
	v_mov_b32_e32 v111, v2
	v_mov_b32_e32 v112, v2
	v_mov_b32_e32 v113, v2
	v_mov_b32_e32 v118, v2
	v_mov_b32_e32 v119, v2
	v_mov_b32_e32 v120, v2
	v_mov_b32_e32 v121, v2
	v_mov_b32_e32 v126, v2
	v_mov_b32_e32 v127, v2
	v_mov_b32_e32 v128, v2
	v_mov_b32_e32 v129, v2
	s_cmpk_gt_u32 s0, 0xff
	s_cbranch_scc0 .Lrs_i2_pre
	s_barrier
.Lrs_i2_pre:
.LBB0_83:
	s_add_u32 s1, s28, 0xfffc0080
	s_addc_u32 s22, s29, -1
	s_add_i32 s23, 0, 0x10000
	v_add_u32_e32 v142, s23, v201
	ds_read_b128 v[130:133], v142
	ds_read_b128 v[134:137], v142 offset:1024
	ds_read_b128 v[138:141], v142 offset:2048
	ds_read_b128 v[142:145], v142 offset:3072
	s_cmp_eq_u32 s60, 12
	s_cselect_b32 s43, s27, s22
	s_cselect_b32 s42, s56, s1
	s_cselect_b32 s31, s7, s59
	s_cselect_b32 s30, s57, s58
	v_lshl_add_u64 v[176:177], s[28:29], 0, v[178:179]
	s_add_i32 m0, s46, 0xc000
	ds_read_b128 v[146:149], v205
	ds_read_b128 v[150:153], v205 offset:1024
	ds_read_b128 v[182:185], v205 offset:2048
	ds_read_b128 v[186:189], v205 offset:3072
	ds_read_b128 v[190:193], v205 offset:4096
	ds_read_b128 v[194:197], v205 offset:5120
	ds_read_b128 v[206:209], v205 offset:6144
	ds_read_b128 v[216:219], v205 offset:7168
	global_load_lds_dwordx4 v[176:177], off
	v_lshl_add_u64 v[176:177], s[28:29], 0, v[180:181]
	s_add_i32 m0, s46, 0xe000
	s_nop 0
	global_load_lds_dwordx4 v[176:177], off
	s_add_i32 s1, 0, 0x14000
	v_add_u32_e32 v168, s1, v201
	ds_read_b128 v[230:233], v168
	ds_read_b128 v[234:237], v168 offset:1024
	ds_read_b128 v[238:241], v168 offset:2048
	ds_read_b128 v[242:245], v168 offset:3072
	s_waitcnt vmcnt(8)
	s_waitcnt lgkmcnt(0)
	s_barrier
	s_setprio 1
	v_mfma_f32_16x16x32_bf16 v[126:129], v[130:133], v[146:149], v[126:129]
	v_mfma_f32_16x16x32_bf16 v[118:121], v[138:141], v[146:149], v[118:121]
	v_mfma_f32_16x16x32_bf16 v[110:113], v[130:133], v[182:185], v[110:113]
	v_mfma_f32_16x16x32_bf16 v[102:105], v[138:141], v[182:185], v[102:105]
	v_mfma_f32_16x16x32_bf16 v[94:97], v[130:133], v[190:193], v[94:97]
	v_mfma_f32_16x16x32_bf16 v[86:89], v[138:141], v[190:193], v[86:89]
	v_mfma_f32_16x16x32_bf16 v[78:81], v[130:133], v[206:209], v[78:81]
	v_mfma_f32_16x16x32_bf16 v[70:73], v[138:141], v[206:209], v[70:73]
	v_mfma_f32_16x16x32_bf16 v[126:129], v[134:137], v[150:153], v[126:129]
	v_mfma_f32_16x16x32_bf16 v[118:121], v[142:145], v[150:153], v[118:121]
	v_mfma_f32_16x16x32_bf16 v[110:113], v[134:137], v[186:189], v[110:113]
	v_mfma_f32_16x16x32_bf16 v[102:105], v[142:145], v[186:189], v[102:105]
	v_mfma_f32_16x16x32_bf16 v[94:97], v[134:137], v[194:197], v[94:97]
	v_mfma_f32_16x16x32_bf16 v[86:89], v[142:145], v[194:197], v[86:89]
	v_mfma_f32_16x16x32_bf16 v[78:81], v[134:137], v[216:219], v[78:81]
	v_mfma_f32_16x16x32_bf16 v[70:73], v[142:145], v[216:219], v[70:73]
	v_mfma_f32_16x16x32_bf16 v[122:125], v[230:233], v[146:149], v[122:125]
	v_mfma_f32_16x16x32_bf16 v[114:117], v[238:241], v[146:149], v[114:117]
	v_mfma_f32_16x16x32_bf16 v[106:109], v[230:233], v[182:185], v[106:109]
	v_mfma_f32_16x16x32_bf16 v[98:101], v[238:241], v[182:185], v[98:101]
	v_mfma_f32_16x16x32_bf16 v[90:93], v[230:233], v[190:193], v[90:93]
	v_mfma_f32_16x16x32_bf16 v[82:85], v[238:241], v[190:193], v[82:85]
	v_mfma_f32_16x16x32_bf16 v[74:77], v[230:233], v[206:209], v[74:77]
	v_mfma_f32_16x16x32_bf16 v[66:69], v[238:241], v[206:209], v[66:69]
	v_mfma_f32_16x16x32_bf16 v[122:125], v[234:237], v[150:153], v[122:125]
	v_mfma_f32_16x16x32_bf16 v[114:117], v[242:245], v[150:153], v[114:117]
	v_mfma_f32_16x16x32_bf16 v[106:109], v[234:237], v[186:189], v[106:109]
	v_mfma_f32_16x16x32_bf16 v[98:101], v[242:245], v[186:189], v[98:101]
	v_mfma_f32_16x16x32_bf16 v[90:93], v[234:237], v[194:197], v[90:93]
	v_mfma_f32_16x16x32_bf16 v[82:85], v[242:245], v[194:197], v[82:85]
	v_mfma_f32_16x16x32_bf16 v[74:77], v[234:237], v[216:219], v[74:77]
	v_mfma_f32_16x16x32_bf16 v[66:69], v[242:245], v[216:219], v[66:69]
	s_setprio 0
	s_barrier
	ds_read_b128 v[146:149], v205 offset:16384
	ds_read_b128 v[150:153], v205 offset:17408
	ds_read_b128 v[182:185], v205 offset:18432
	ds_read_b128 v[186:189], v205 offset:19456
	ds_read_b128 v[190:193], v205 offset:20480
	ds_read_b128 v[194:197], v205 offset:21504
	ds_read_b128 v[206:209], v205 offset:22528
	ds_read_b128 v[216:219], v205 offset:23552
	s_add_i32 s22, s23, s17
	v_lshl_add_u64 v[176:177], s[30:31], 0, v[0:1]
	s_mov_b32 m0, s22
	s_nop 0
	global_load_lds_dwordx4 v[176:177], off
	v_lshl_add_u64 v[202:203], s[30:31], 0, v[154:155]
	s_add_i32 m0, s22, 0x2000
	s_nop 0
	global_load_lds_dwordx4 v[202:203], off
	s_mov_b32 m0, s46
	v_lshl_add_u64 v[220:221], s[42:43], 0, v[158:159]
	global_load_lds_dwordx4 v[220:221], off
	v_lshl_add_u64 v[246:247], s[42:43], 0, v[156:157]
	s_mov_b32 m0, s47
	s_nop 0
	global_load_lds_dwordx4 v[246:247], off
	s_add_u32 s22, s30, 0x40000
	s_addc_u32 s23, s31, 0
	s_add_i32 s1, s1, s17
	s_mov_b32 m0, s1
	s_nop 0
	global_load_lds_dwordx4 v0, s[22:23]
	s_add_i32 m0, s1, 0x2000
	s_nop 0
	global_load_lds_dwordx4 v154, s[22:23]
	s_waitcnt vmcnt(8)
	s_waitcnt lgkmcnt(0)
	s_barrier
	s_setprio 1
	v_mfma_f32_16x16x32_bf16 v[62:65], v[130:133], v[146:149], v[62:65]
	v_mfma_f32_16x16x32_bf16 v[54:57], v[138:141], v[146:149], v[54:57]
	v_mfma_f32_16x16x32_bf16 v[46:49], v[130:133], v[182:185], v[46:49]
	v_mfma_f32_16x16x32_bf16 v[38:41], v[138:141], v[182:185], v[38:41]
	v_mfma_f32_16x16x32_bf16 v[30:33], v[130:133], v[190:193], v[30:33]
	v_mfma_f32_16x16x32_bf16 v[22:25], v[138:141], v[190:193], v[22:25]
	v_mfma_f32_16x16x32_bf16 v[14:17], v[130:133], v[206:209], v[14:17]
	v_mfma_f32_16x16x32_bf16 v[6:9], v[138:141], v[206:209], v[6:9]
	v_mfma_f32_16x16x32_bf16 v[62:65], v[134:137], v[150:153], v[62:65]
	v_mfma_f32_16x16x32_bf16 v[54:57], v[142:145], v[150:153], v[54:57]
	v_mfma_f32_16x16x32_bf16 v[46:49], v[134:137], v[186:189], v[46:49]
	v_mfma_f32_16x16x32_bf16 v[38:41], v[142:145], v[186:189], v[38:41]
	v_mfma_f32_16x16x32_bf16 v[30:33], v[134:137], v[194:197], v[30:33]
	v_mfma_f32_16x16x32_bf16 v[22:25], v[142:145], v[194:197], v[22:25]
	v_mfma_f32_16x16x32_bf16 v[14:17], v[134:137], v[216:219], v[14:17]
	v_mfma_f32_16x16x32_bf16 v[6:9], v[142:145], v[216:219], v[6:9]
	v_mfma_f32_16x16x32_bf16 v[58:61], v[230:233], v[146:149], v[58:61]
	v_mfma_f32_16x16x32_bf16 v[50:53], v[238:241], v[146:149], v[50:53]
	v_mfma_f32_16x16x32_bf16 v[42:45], v[230:233], v[182:185], v[42:45]
	v_mfma_f32_16x16x32_bf16 v[34:37], v[238:241], v[182:185], v[34:37]
	v_mfma_f32_16x16x32_bf16 v[26:29], v[230:233], v[190:193], v[26:29]
	v_mfma_f32_16x16x32_bf16 v[18:21], v[238:241], v[190:193], v[18:21]
	v_mfma_f32_16x16x32_bf16 v[10:13], v[230:233], v[206:209], v[10:13]
	v_mfma_f32_16x16x32_bf16 v[2:5], v[238:241], v[206:209], v[2:5]
	v_mfma_f32_16x16x32_bf16 v[58:61], v[234:237], v[150:153], v[58:61]
	v_mfma_f32_16x16x32_bf16 v[50:53], v[242:245], v[150:153], v[50:53]
	v_mfma_f32_16x16x32_bf16 v[42:45], v[234:237], v[186:189], v[42:45]
	v_mfma_f32_16x16x32_bf16 v[34:37], v[242:245], v[186:189], v[34:37]
	v_mfma_f32_16x16x32_bf16 v[26:29], v[234:237], v[194:197], v[26:29]
	v_mfma_f32_16x16x32_bf16 v[18:21], v[242:245], v[194:197], v[18:21]
	v_mfma_f32_16x16x32_bf16 v[10:13], v[234:237], v[216:219], v[10:13]
	v_mfma_f32_16x16x32_bf16 v[2:5], v[242:245], v[216:219], v[2:5]
	s_setprio 0
	s_barrier
	s_add_i32 s1, 0, 0x18000
	v_add_u32_e32 v142, s1, v201
	ds_read_b128 v[130:133], v142
	ds_read_b128 v[134:137], v142 offset:1024
	ds_read_b128 v[138:141], v142 offset:2048
	ds_read_b128 v[142:145], v142 offset:3072
	s_add_u32 s22, s42, 0x40000
	s_addc_u32 s23, s43, 0
	s_mov_b32 m0, s48
	v_lshl_add_u64 v[230:231], s[22:23], 0, v[158:159]
	ds_read_b128 v[146:149], v205 offset:32768
	ds_read_b128 v[150:153], v205 offset:33792
	ds_read_b128 v[182:185], v205 offset:34816
	ds_read_b128 v[186:189], v205 offset:35840
	ds_read_b128 v[190:193], v205 offset:36864
	ds_read_b128 v[194:197], v205 offset:37888
	ds_read_b128 v[206:209], v205 offset:38912
	ds_read_b128 v[216:219], v205 offset:39936
	global_load_lds_dwordx4 v[230:231], off
	v_lshl_add_u64 v[230:231], s[22:23], 0, v[156:157]
	s_mov_b32 m0, s49
	s_nop 0
	global_load_lds_dwordx4 v[230:231], off
	s_add_i32 s33, 0, 0x1c000
	v_add_u32_e32 v168, s33, v201
	ds_read_b128 v[230:233], v168
	ds_read_b128 v[234:237], v168 offset:1024
	ds_read_b128 v[238:241], v168 offset:2048
	ds_read_b128 v[242:245], v168 offset:3072
	s_waitcnt vmcnt(8)
	s_waitcnt lgkmcnt(0)
	s_barrier
	s_setprio 1
	v_mfma_f32_16x16x32_bf16 v[126:129], v[130:133], v[146:149], v[126:129]
	v_mfma_f32_16x16x32_bf16 v[118:121], v[138:141], v[146:149], v[118:121]
	v_mfma_f32_16x16x32_bf16 v[110:113], v[130:133], v[182:185], v[110:113]
	v_mfma_f32_16x16x32_bf16 v[102:105], v[138:141], v[182:185], v[102:105]
	v_mfma_f32_16x16x32_bf16 v[94:97], v[130:133], v[190:193], v[94:97]
	v_mfma_f32_16x16x32_bf16 v[86:89], v[138:141], v[190:193], v[86:89]
	v_mfma_f32_16x16x32_bf16 v[78:81], v[130:133], v[206:209], v[78:81]
	v_mfma_f32_16x16x32_bf16 v[70:73], v[138:141], v[206:209], v[70:73]
	v_mfma_f32_16x16x32_bf16 v[126:129], v[134:137], v[150:153], v[126:129]
	v_mfma_f32_16x16x32_bf16 v[118:121], v[142:145], v[150:153], v[118:121]
	v_mfma_f32_16x16x32_bf16 v[110:113], v[134:137], v[186:189], v[110:113]
	v_mfma_f32_16x16x32_bf16 v[102:105], v[142:145], v[186:189], v[102:105]
	v_mfma_f32_16x16x32_bf16 v[94:97], v[134:137], v[194:197], v[94:97]
	v_mfma_f32_16x16x32_bf16 v[86:89], v[142:145], v[194:197], v[86:89]
	v_mfma_f32_16x16x32_bf16 v[78:81], v[134:137], v[216:219], v[78:81]
	v_mfma_f32_16x16x32_bf16 v[70:73], v[142:145], v[216:219], v[70:73]
	v_mfma_f32_16x16x32_bf16 v[122:125], v[230:233], v[146:149], v[122:125]
	v_mfma_f32_16x16x32_bf16 v[114:117], v[238:241], v[146:149], v[114:117]
	v_mfma_f32_16x16x32_bf16 v[106:109], v[230:233], v[182:185], v[106:109]
	v_mfma_f32_16x16x32_bf16 v[98:101], v[238:241], v[182:185], v[98:101]
	v_mfma_f32_16x16x32_bf16 v[90:93], v[230:233], v[190:193], v[90:93]
	v_mfma_f32_16x16x32_bf16 v[82:85], v[238:241], v[190:193], v[82:85]
	v_mfma_f32_16x16x32_bf16 v[74:77], v[230:233], v[206:209], v[74:77]
	v_mfma_f32_16x16x32_bf16 v[66:69], v[238:241], v[206:209], v[66:69]
	v_mfma_f32_16x16x32_bf16 v[122:125], v[234:237], v[150:153], v[122:125]
	v_mfma_f32_16x16x32_bf16 v[114:117], v[242:245], v[150:153], v[114:117]
	v_mfma_f32_16x16x32_bf16 v[106:109], v[234:237], v[186:189], v[106:109]
	v_mfma_f32_16x16x32_bf16 v[98:101], v[242:245], v[186:189], v[98:101]
	v_mfma_f32_16x16x32_bf16 v[90:93], v[234:237], v[194:197], v[90:93]
	v_mfma_f32_16x16x32_bf16 v[82:85], v[242:245], v[194:197], v[82:85]
	v_mfma_f32_16x16x32_bf16 v[74:77], v[234:237], v[216:219], v[74:77]
	v_mfma_f32_16x16x32_bf16 v[66:69], v[242:245], v[216:219], v[66:69]
	s_setprio 0
	s_barrier
	ds_read_b128 v[146:149], v205 offset:49152
	ds_read_b128 v[150:153], v205 offset:50176
	ds_read_b128 v[182:185], v205 offset:51200
	ds_read_b128 v[186:189], v205 offset:52224
	ds_read_b128 v[190:193], v205 offset:53248
	ds_read_b128 v[194:197], v205 offset:54272
	ds_read_b128 v[206:209], v205 offset:55296
	ds_read_b128 v[216:219], v205 offset:56320
	s_add_i32 s1, s1, s17
	v_lshl_add_u64 v[176:177], v[176:177], 0, s[12:13]
	s_mov_b32 m0, s1
	s_nop 0
	global_load_lds_dwordx4 v[176:177], off
	v_lshl_add_u64 v[176:177], v[202:203], 0, s[12:13]
	s_add_i32 m0, s1, 0x2000
	s_nop 0
	global_load_lds_dwordx4 v[176:177], off
	s_mov_b32 m0, s20
	v_lshl_add_u64 v[176:177], v[220:221], 0, s[12:13]
	global_load_lds_dwordx4 v[176:177], off
	v_lshl_add_u64 v[176:177], v[246:247], 0, s[12:13]
	s_mov_b32 m0, s21
	s_nop 0
	global_load_lds_dwordx4 v[176:177], off
	s_add_u32 s22, s30, 0x40080
	s_addc_u32 s23, s31, 0
	s_add_i32 s1, s33, s17
	s_mov_b32 m0, s1
	s_nop 0
	global_load_lds_dwordx4 v0, s[22:23]
	s_add_i32 m0, s1, 0x2000
	s_nop 0
	global_load_lds_dwordx4 v154, s[22:23]
	s_waitcnt vmcnt(8)
	s_waitcnt lgkmcnt(0)
	s_barrier
	s_setprio 1
	v_mfma_f32_16x16x32_bf16 v[62:65], v[130:133], v[146:149], v[62:65]
	v_mfma_f32_16x16x32_bf16 v[54:57], v[138:141], v[146:149], v[54:57]
	v_mfma_f32_16x16x32_bf16 v[46:49], v[130:133], v[182:185], v[46:49]
	v_mfma_f32_16x16x32_bf16 v[38:41], v[138:141], v[182:185], v[38:41]
	v_mfma_f32_16x16x32_bf16 v[30:33], v[130:133], v[190:193], v[30:33]
	v_mfma_f32_16x16x32_bf16 v[22:25], v[138:141], v[190:193], v[22:25]
	v_mfma_f32_16x16x32_bf16 v[14:17], v[130:133], v[206:209], v[14:17]
	v_mfma_f32_16x16x32_bf16 v[6:9], v[138:141], v[206:209], v[6:9]
	v_mfma_f32_16x16x32_bf16 v[62:65], v[134:137], v[150:153], v[62:65]
	v_mfma_f32_16x16x32_bf16 v[54:57], v[142:145], v[150:153], v[54:57]
	v_mfma_f32_16x16x32_bf16 v[46:49], v[134:137], v[186:189], v[46:49]
	v_mfma_f32_16x16x32_bf16 v[38:41], v[142:145], v[186:189], v[38:41]
	v_mfma_f32_16x16x32_bf16 v[30:33], v[134:137], v[194:197], v[30:33]
	v_mfma_f32_16x16x32_bf16 v[22:25], v[142:145], v[194:197], v[22:25]
	v_mfma_f32_16x16x32_bf16 v[14:17], v[134:137], v[216:219], v[14:17]
	v_mfma_f32_16x16x32_bf16 v[6:9], v[142:145], v[216:219], v[6:9]
	v_mfma_f32_16x16x32_bf16 v[58:61], v[230:233], v[146:149], v[58:61]
	v_mfma_f32_16x16x32_bf16 v[50:53], v[238:241], v[146:149], v[50:53]
	v_mfma_f32_16x16x32_bf16 v[42:45], v[230:233], v[182:185], v[42:45]
	v_mfma_f32_16x16x32_bf16 v[34:37], v[238:241], v[182:185], v[34:37]
	v_mfma_f32_16x16x32_bf16 v[26:29], v[230:233], v[190:193], v[26:29]
	v_mfma_f32_16x16x32_bf16 v[18:21], v[238:241], v[190:193], v[18:21]
	v_mfma_f32_16x16x32_bf16 v[10:13], v[230:233], v[206:209], v[10:13]
	v_mfma_f32_16x16x32_bf16 v[2:5], v[238:241], v[206:209], v[2:5]
	v_mfma_f32_16x16x32_bf16 v[58:61], v[234:237], v[150:153], v[58:61]
	v_mfma_f32_16x16x32_bf16 v[50:53], v[242:245], v[150:153], v[50:53]
	v_mfma_f32_16x16x32_bf16 v[42:45], v[234:237], v[186:189], v[42:45]
	v_mfma_f32_16x16x32_bf16 v[34:37], v[242:245], v[186:189], v[34:37]
	v_mfma_f32_16x16x32_bf16 v[26:29], v[234:237], v[194:197], v[26:29]
	v_mfma_f32_16x16x32_bf16 v[18:21], v[242:245], v[194:197], v[18:21]
	v_mfma_f32_16x16x32_bf16 v[10:13], v[234:237], v[216:219], v[10:13]
	v_mfma_f32_16x16x32_bf16 v[2:5], v[242:245], v[216:219], v[2:5]
	s_setprio 0
	s_add_i32 s60, s60, 2
	s_add_u32 s28, s28, 0x100
	s_addc_u32 s29, s29, 0
	s_add_u32 s58, s58, 0x100
	s_addc_u32 s59, s59, 0
	s_cmp_gt_u32 s60, 13
	s_barrier
	s_cbranch_scc0 .LBB0_83
	s_cmpk_gt_u32 s0, 0xff
	s_cbranch_scc1 .Lrs_i2_post
	s_barrier
.Lrs_i2_post:
	v_lshl_add_u32 v196, s55, 8, v199
	v_ashrrev_i32_e32 v197, 31, v196
	v_lshlrev_b64 v[130:131], 6, v[196:197]
	v_or_b32_e32 v194, 16, v196
	v_lshl_add_u64 v[130:131], v[160:161], 0, v[130:131]
	v_ashrrev_i32_e32 v195, 31, v194
	global_load_dwordx4 v[206:209], v[130:131], off
	v_lshlrev_b64 v[130:131], 6, v[194:195]
	v_lshl_add_u64 v[130:131], v[160:161], 0, v[130:131]
	global_load_dwordx4 v[216:219], v[130:131], off
	v_or_b32_e32 v192, 32, v196
	v_ashrrev_i32_e32 v193, 31, v192
	v_lshlrev_b64 v[130:131], 6, v[192:193]
	v_or_b32_e32 v190, 48, v196
	v_lshl_add_u64 v[130:131], v[160:161], 0, v[130:131]
	v_ashrrev_i32_e32 v191, 31, v190
	global_load_dwordx4 v[150:153], v[130:131], off
	v_lshlrev_b64 v[130:131], 6, v[190:191]
	v_lshl_add_u64 v[130:131], v[160:161], 0, v[130:131]
	global_load_dwordx4 v[146:149], v[130:131], off
	v_add_u32_e32 v188, 0x80, v196
	v_ashrrev_i32_e32 v189, 31, v188
	v_lshlrev_b64 v[130:131], 6, v[188:189]
	v_add_u32_e32 v186, 0x90, v196
	v_lshl_add_u64 v[130:131], v[160:161], 0, v[130:131]
	v_ashrrev_i32_e32 v187, 31, v186
	global_load_dwordx4 v[142:145], v[130:131], off
	v_lshlrev_b64 v[130:131], 6, v[186:187]
	v_lshl_add_u64 v[130:131], v[160:161], 0, v[130:131]
	global_load_dwordx4 v[138:141], v[130:131], off
	v_add_u32_e32 v184, 0xa0, v196
	v_ashrrev_i32_e32 v185, 31, v184
	v_lshlrev_b64 v[130:131], 6, v[184:185]
	v_add_u32_e32 v182, 0xb0, v196
	v_lshl_add_u64 v[130:131], v[160:161], 0, v[130:131]
	v_ashrrev_i32_e32 v183, 31, v182
	global_load_dwordx4 v[134:137], v[130:131], off
	v_lshlrev_b64 v[130:131], 6, v[182:183]
	v_lshl_add_u64 v[130:131], v[160:161], 0, v[130:131]
	global_load_dwordx4 v[130:133], v[130:131], off
	v_and_b32_e32 v169, 64, v212
	v_xor_b32_e32 v168, 16, v212
	v_add_u32_e32 v169, 64, v169
	v_cmp_lt_i32_e32 vcc, v168, v169
	s_mov_b32 s22, 0x358637bd
	s_mov_b32 s55, s26
	v_cndmask_b32_e32 v168, v212, v168, vcc
	v_lshlrev_b32_e32 v185, 2, v168
	v_xor_b32_e32 v168, 32, v212
	v_cmp_lt_i32_e32 vcc, v168, v169
	s_mov_b64 s[30:31], s[44:45]
	s_mov_b64 s[28:29], s[36:37]
	v_cndmask_b32_e32 v168, v212, v168, vcc
	v_lshlrev_b32_e32 v183, 2, v168
	s_waitcnt vmcnt(0)
	v_mov_b32_e32 v176, v207
	v_mov_b32_e32 v177, v208
	v_mov_b32_e32 v207, v209
	v_mov_b32_e32 v202, v217
	v_mov_b32_e32 v203, v218
	v_mov_b32_e32 v217, v219
	v_pk_add_f32 v[176:177], v[176:177], v[206:207]
	v_pk_add_f32 v[202:203], v[202:203], v[216:217]
	v_mov_b32_e32 v207, v176
	v_mov_b32_e32 v206, v202
	v_mov_b32_e32 v176, v203
	v_pk_add_f32 v[176:177], v[206:207], v[176:177]
	ds_bpermute_b32 v203, v185, v177
	ds_bpermute_b32 v202, v185, v176
	s_waitcnt lgkmcnt(0)
	v_pk_add_f32 v[176:177], v[176:177], v[202:203]
	ds_bpermute_b32 v203, v183, v177
	ds_bpermute_b32 v202, v183, v176
	s_waitcnt lgkmcnt(0)
	v_pk_add_f32 v[176:177], v[176:177], v[202:203]
	v_mov_b64_e32 v[202:203], s[22:23]
	s_mov_b32 s22, 0x3a800000
	v_pk_fma_f32 v[176:177], v[176:177], s[22:23], v[202:203] op_sel_hi:[1,0,0]
	s_nop 0
	v_mul_f32_e32 v168, 0x4b800000, v177
	v_cmp_gt_f32_e64 s[42:43], s39, v177
	v_cmp_gt_f32_e32 vcc, s39, v176
	s_nop 0
	v_cndmask_b32_e64 v168, v177, v168, s[42:43]
	v_rsq_f32_e32 v168, v168
	v_mov_b32_e32 v177, v152
	v_mov_b32_e32 v152, v147
	v_mov_b32_e32 v147, v149
	v_mul_f32_e32 v169, 0x45800000, v168
	v_cndmask_b32_e64 v200, v168, v169, s[42:43]
	v_mul_f32_e32 v168, 0x4b800000, v176
	v_cndmask_b32_e32 v168, v176, v168, vcc
	v_mov_b32_e32 v176, v151
	v_mov_b32_e32 v151, v153
	v_mov_b32_e32 v153, v148
	v_pk_add_f32 v[150:151], v[176:177], v[150:151]
	v_pk_add_f32 v[146:147], v[152:153], v[146:147]
	v_mov_b32_e32 v149, v150
	v_mov_b32_e32 v148, v146
	v_mov_b32_e32 v150, v147
	v_pk_add_f32 v[146:147], v[148:149], v[150:151]
	ds_bpermute_b32 v149, v185, v147
	ds_bpermute_b32 v148, v185, v146
	v_mov_b32_e32 v150, v143
	v_mov_b32_e32 v151, v144
	v_mov_b32_e32 v143, v145
	v_mov_b32_e32 v144, v139
	v_mov_b32_e32 v145, v140
	v_mov_b32_e32 v139, v141
	v_pk_add_f32 v[142:143], v[150:151], v[142:143]
	v_pk_add_f32 v[138:139], v[144:145], v[138:139]
	s_waitcnt lgkmcnt(0)
	v_pk_add_f32 v[146:147], v[146:147], v[148:149]
	v_mov_b32_e32 v140, v138
	v_mov_b32_e32 v141, v142
	v_mov_b32_e32 v142, v139
	ds_bpermute_b32 v149, v183, v147
	ds_bpermute_b32 v148, v183, v146
	v_pk_add_f32 v[138:139], v[140:141], v[142:143]
	ds_bpermute_b32 v141, v185, v139
	ds_bpermute_b32 v140, v185, v138
	v_mov_b32_e32 v142, v135
	v_mov_b32_e32 v143, v136
	v_mov_b32_e32 v135, v137
	v_mov_b32_e32 v136, v131
	v_mov_b32_e32 v137, v132
	v_mov_b32_e32 v131, v133
	s_waitcnt lgkmcnt(2)
	v_pk_add_f32 v[146:147], v[146:147], v[148:149]
	v_pk_add_f32 v[134:135], v[142:143], v[134:135]
	v_pk_add_f32 v[130:131], v[136:137], v[130:131]
	v_pk_fma_f32 v[146:147], v[146:147], s[22:23], v[202:203] op_sel_hi:[1,0,0]
	s_waitcnt lgkmcnt(0)
	v_pk_add_f32 v[138:139], v[138:139], v[140:141]
	v_mov_b32_e32 v132, v130
	v_mov_b32_e32 v133, v134
	v_mov_b32_e32 v134, v131
	v_mul_f32_e32 v148, 0x4b800000, v147
	v_cmp_gt_f32_e64 s[42:43], s39, v147
	ds_bpermute_b32 v141, v183, v139
	ds_bpermute_b32 v140, v183, v138
	v_pk_add_f32 v[130:131], v[132:133], v[134:135]
	v_cndmask_b32_e64 v147, v147, v148, s[42:43]
	ds_bpermute_b32 v133, v185, v131
	ds_bpermute_b32 v132, v185, v130
	v_rsq_f32_e32 v168, v168
	v_rsq_f32_e32 v147, v147
	s_waitcnt lgkmcnt(2)
	v_pk_add_f32 v[138:139], v[138:139], v[140:141]
	v_pk_mul_f32 v[126:127], v[126:127], v[200:201] op_sel_hi:[1,0]
	v_mul_f32_e32 v169, 0x45800000, v168
	v_mul_f32_e32 v148, 0x45800000, v147
	v_pk_fma_f32 v[138:139], v[138:139], s[22:23], v[202:203] op_sel_hi:[1,0,0]
	s_waitcnt lgkmcnt(0)
	v_pk_add_f32 v[130:131], v[130:131], v[132:133]
	v_cndmask_b32_e32 v198, v168, v169, vcc
	v_cmp_gt_f32_e32 vcc, s39, v146
	v_cndmask_b32_e64 v148, v147, v148, s[42:43]
	v_mul_f32_e32 v147, 0x4b800000, v146
	v_mul_f32_e32 v140, 0x4b800000, v139
	v_cmp_gt_f32_e64 s[42:43], s39, v139
	ds_bpermute_b32 v133, v183, v131
	ds_bpermute_b32 v132, v183, v130
	v_cndmask_b32_e32 v146, v146, v147, vcc
	v_cndmask_b32_e64 v139, v139, v140, s[42:43]
	v_rsq_f32_e32 v146, v146
	v_rsq_f32_e32 v139, v139
	s_waitcnt lgkmcnt(0)
	v_pk_add_f32 v[130:131], v[130:131], v[132:133]
	v_pk_mul_f32 v[122:123], v[122:123], v[200:201] op_sel_hi:[1,0]
	v_mul_f32_e32 v147, 0x45800000, v146
	v_mul_f32_e32 v140, 0x45800000, v139
	v_pk_fma_f32 v[130:131], v[130:131], s[22:23], v[202:203] op_sel_hi:[1,0,0]
	v_cndmask_b32_e32 v146, v146, v147, vcc
	v_cmp_gt_f32_e32 vcc, s39, v138
	v_cndmask_b32_e64 v140, v139, v140, s[42:43]
	v_mul_f32_e32 v139, 0x4b800000, v138
	v_mul_f32_e32 v132, 0x4b800000, v131
	v_cmp_gt_f32_e64 s[42:43], s39, v131
	v_cndmask_b32_e32 v138, v138, v139, vcc
	v_rsq_f32_e32 v138, v138
	v_cndmask_b32_e64 v131, v131, v132, s[42:43]
	v_rsq_f32_e32 v131, v131
	v_pk_mul_f32 v[124:125], v[124:125], v[200:201] op_sel_hi:[1,0]
	v_mul_f32_e32 v139, 0x45800000, v138
	v_cndmask_b32_e32 v138, v138, v139, vcc
	v_mul_f32_e32 v132, 0x45800000, v131
	v_cmp_gt_f32_e32 vcc, s39, v130
	v_cndmask_b32_e64 v132, v131, v132, s[42:43]
	v_mul_f32_e32 v131, 0x4b800000, v130
	v_cndmask_b32_e32 v130, v130, v131, vcc
	v_rsq_f32_e32 v130, v130
	v_pk_mul_f32 v[118:119], v[118:119], v[200:201] op_sel_hi:[1,0]
	v_pk_mul_f32 v[114:115], v[114:115], v[200:201] op_sel_hi:[1,0]
	v_lshl_or_b32 v134, s34, 7, v204
	v_mul_f32_e32 v131, 0x45800000, v130
	v_cndmask_b32_e32 v130, v130, v131, vcc
	v_mul_f32_e32 v131, 0xbfb8aa3b, v126
	v_exp_f32_e32 v131, v131
	v_pk_mul_f32 v[116:117], v[116:117], v[200:201] op_sel_hi:[1,0]
	v_ashrrev_i32_e32 v135, 31, v134
	v_pk_mul_f32 v[110:111], v[110:111], v[198:199] op_sel_hi:[1,0]
	v_add_f32_e32 v131, 1.0, v131
	v_rcp_f32_e32 v136, v131
	v_mul_f32_e32 v131, 0xbfb8aa3b, v127
	v_exp_f32_e32 v131, v131
	v_pk_mul_f32 v[106:107], v[106:107], v[198:199] op_sel_hi:[1,0]
	v_pk_mul_f32 v[108:109], v[108:109], v[198:199] op_sel_hi:[1,0]
	v_pk_mul_f32 v[102:103], v[102:103], v[198:199] op_sel_hi:[1,0]
	v_add_f32_e32 v131, 1.0, v131
	v_rcp_f32_e32 v137, v131
	v_pk_mul_f32 v[98:99], v[98:99], v[198:199] op_sel_hi:[1,0]
	v_pk_mul_f32 v[100:101], v[100:101], v[198:199] op_sel_hi:[1,0]
	v_pk_mul_f32 v[94:95], v[94:95], v[148:149] op_sel_hi:[1,0]
	v_pk_mul_f32 v[126:127], v[126:127], v[136:137]
	v_pk_mul_f32 v[90:91], v[90:91], v[148:149] op_sel_hi:[1,0]
	v_pk_mul_f32 v[122:123], v[122:123], v[126:127]
	v_pk_mul_f32 v[126:127], v[128:129], v[200:201] op_sel_hi:[1,0]
	v_cvt_pk_bf16_f32 v122, v122, v123
	v_mul_f32_e32 v128, 0xbfb8aa3b, v126
	v_mul_f32_e32 v129, 0xbfb8aa3b, v127
	v_exp_f32_e32 v128, v128
	v_exp_f32_e32 v129, v129
	v_pk_mul_f32 v[92:93], v[92:93], v[148:149] op_sel_hi:[1,0]
	v_pk_mul_f32 v[86:87], v[86:87], v[148:149] op_sel_hi:[1,0]
	v_add_f32_e32 v128, 1.0, v128
	v_add_f32_e32 v129, 1.0, v129
	v_rcp_f32_e32 v128, v128
	v_rcp_f32_e32 v129, v129
	v_pk_mul_f32 v[82:83], v[82:83], v[148:149] op_sel_hi:[1,0]
	v_pk_mul_f32 v[84:85], v[84:85], v[148:149] op_sel_hi:[1,0]
	v_pk_mul_f32 v[78:79], v[78:79], v[146:147] op_sel_hi:[1,0]
	v_pk_mul_f32 v[126:127], v[126:127], v[128:129]
	v_pk_mul_f32 v[74:75], v[74:75], v[146:147] op_sel_hi:[1,0]
	v_pk_mul_f32 v[124:125], v[124:125], v[126:127]
	v_pk_mul_f32 v[76:77], v[76:77], v[146:147] op_sel_hi:[1,0]
	v_cvt_pk_bf16_f32 v123, v124, v125
	v_mul_f32_e32 v124, 0xbfb8aa3b, v118
	v_mul_f32_e32 v125, 0xbfb8aa3b, v119
	v_exp_f32_e32 v124, v124
	v_exp_f32_e32 v125, v125
	v_pk_mul_f32 v[70:71], v[70:71], v[146:147] op_sel_hi:[1,0]
	v_pk_mul_f32 v[66:67], v[66:67], v[146:147] op_sel_hi:[1,0]
	v_add_f32_e32 v124, 1.0, v124
	v_add_f32_e32 v125, 1.0, v125
	v_rcp_f32_e32 v124, v124
	v_rcp_f32_e32 v125, v125
	v_pk_mul_f32 v[68:69], v[68:69], v[146:147] op_sel_hi:[1,0]
	v_pk_mul_f32 v[62:63], v[62:63], v[140:141] op_sel_hi:[1,0]
	v_pk_mul_f32 v[58:59], v[58:59], v[140:141] op_sel_hi:[1,0]
	v_pk_mul_f32 v[118:119], v[118:119], v[124:125]
	v_pk_mul_f32 v[60:61], v[60:61], v[140:141] op_sel_hi:[1,0]
	v_pk_mul_f32 v[114:115], v[114:115], v[118:119]
	v_pk_mul_f32 v[118:119], v[120:121], v[200:201] op_sel_hi:[1,0]
	v_cvt_pk_bf16_f32 v124, v114, v115
	v_mul_f32_e32 v120, 0xbfb8aa3b, v118
	v_mul_f32_e32 v121, 0xbfb8aa3b, v119
	v_exp_f32_e32 v120, v120
	v_exp_f32_e32 v121, v121
	v_mov_b64_e32 v[114:115], s[68:69]
	v_pk_mul_f32 v[54:55], v[54:55], v[140:141] op_sel_hi:[1,0]
	v_add_f32_e32 v120, 1.0, v120
	v_add_f32_e32 v121, 1.0, v121
	v_rcp_f32_e32 v120, v120
	v_rcp_f32_e32 v121, v121
	v_pk_mul_f32 v[50:51], v[50:51], v[140:141] op_sel_hi:[1,0]
	v_pk_mul_f32 v[52:53], v[52:53], v[140:141] op_sel_hi:[1,0]
	v_pk_mul_f32 v[46:47], v[46:47], v[138:139] op_sel_hi:[1,0]
	v_pk_mul_f32 v[118:119], v[118:119], v[120:121]
	v_pk_mul_f32 v[42:43], v[42:43], v[138:139] op_sel_hi:[1,0]
	v_pk_mul_f32 v[116:117], v[116:117], v[118:119]
	v_mad_i64_i32 v[118:119], s[22:23], v196, s38, v[114:115]
	v_cvt_pk_bf16_f32 v125, v116, v117
	v_lshlrev_b64 v[116:117], 1, v[134:135]
	v_lshl_add_u64 v[118:119], v[118:119], 0, v[116:117]
	global_store_dwordx4 v[118:119], v[122:125], off
	v_mul_f32_e32 v118, 0xbfb8aa3b, v110
	v_mul_f32_e32 v119, 0xbfb8aa3b, v111
	v_exp_f32_e32 v118, v118
	v_exp_f32_e32 v119, v119
	v_pk_mul_f32 v[44:45], v[44:45], v[138:139] op_sel_hi:[1,0]
	v_pk_mul_f32 v[38:39], v[38:39], v[138:139] op_sel_hi:[1,0]
	v_add_f32_e32 v118, 1.0, v118
	v_add_f32_e32 v119, 1.0, v119
	v_rcp_f32_e32 v118, v118
	v_rcp_f32_e32 v119, v119
	v_pk_mul_f32 v[34:35], v[34:35], v[138:139] op_sel_hi:[1,0]
	v_pk_mul_f32 v[36:37], v[36:37], v[138:139] op_sel_hi:[1,0]
	v_pk_mul_f32 v[30:31], v[30:31], v[132:133] op_sel_hi:[1,0]
	v_pk_mul_f32 v[110:111], v[110:111], v[118:119]
	v_pk_mul_f32 v[26:27], v[26:27], v[132:133] op_sel_hi:[1,0]
	v_pk_mul_f32 v[106:107], v[106:107], v[110:111]
	v_pk_mul_f32 v[110:111], v[112:113], v[198:199] op_sel_hi:[1,0]
	v_cvt_pk_bf16_f32 v106, v106, v107
	v_mul_f32_e32 v112, 0xbfb8aa3b, v110
	v_mul_f32_e32 v113, 0xbfb8aa3b, v111
	v_exp_f32_e32 v112, v112
	v_exp_f32_e32 v113, v113
	v_pk_mul_f32 v[28:29], v[28:29], v[132:133] op_sel_hi:[1,0]
	v_pk_mul_f32 v[22:23], v[22:23], v[132:133] op_sel_hi:[1,0]
	v_add_f32_e32 v112, 1.0, v112
	v_add_f32_e32 v113, 1.0, v113
	v_rcp_f32_e32 v112, v112
	v_rcp_f32_e32 v113, v113
	v_pk_mul_f32 v[18:19], v[18:19], v[132:133] op_sel_hi:[1,0]
	v_pk_mul_f32 v[20:21], v[20:21], v[132:133] op_sel_hi:[1,0]
	v_pk_mul_f32 v[14:15], v[14:15], v[130:131] op_sel_hi:[1,0]
	v_pk_mul_f32 v[110:111], v[110:111], v[112:113]
	v_pk_mul_f32 v[10:11], v[10:11], v[130:131] op_sel_hi:[1,0]
	v_pk_mul_f32 v[108:109], v[108:109], v[110:111]
	v_pk_mul_f32 v[12:13], v[12:13], v[130:131] op_sel_hi:[1,0]
	v_cvt_pk_bf16_f32 v107, v108, v109
	v_mul_f32_e32 v108, 0xbfb8aa3b, v102
	v_mul_f32_e32 v109, 0xbfb8aa3b, v103
	v_exp_f32_e32 v108, v108
	v_exp_f32_e32 v109, v109
	v_pk_mul_f32 v[6:7], v[6:7], v[130:131] op_sel_hi:[1,0]
	v_pk_mul_f32 v[2:3], v[2:3], v[130:131] op_sel_hi:[1,0]
	v_add_f32_e32 v108, 1.0, v108
	v_add_f32_e32 v109, 1.0, v109
	v_rcp_f32_e32 v108, v108
	v_rcp_f32_e32 v109, v109
	v_pk_mul_f32 v[4:5], v[4:5], v[130:131] op_sel_hi:[1,0]
	s_and_b64 vcc, exec, s[40:41]
	s_mov_b32 s34, s6
	v_pk_mul_f32 v[102:103], v[102:103], v[108:109]
	s_nop 0
	v_pk_mul_f32 v[98:99], v[98:99], v[102:103]
	v_pk_mul_f32 v[102:103], v[104:105], v[198:199] op_sel_hi:[1,0]
	v_cvt_pk_bf16_f32 v108, v98, v99
	v_mul_f32_e32 v104, 0xbfb8aa3b, v102
	v_mul_f32_e32 v105, 0xbfb8aa3b, v103
	v_exp_f32_e32 v104, v104
	v_exp_f32_e32 v105, v105
	v_mad_i64_i32 v[98:99], s[22:23], v194, s38, v[114:115]
	v_add_f32_e32 v104, 1.0, v104
	v_add_f32_e32 v105, 1.0, v105
	v_rcp_f32_e32 v104, v104
	v_rcp_f32_e32 v105, v105
	v_lshl_add_u64 v[98:99], v[98:99], 0, v[116:117]
	v_pk_mul_f32 v[102:103], v[102:103], v[104:105]
	s_nop 0
	v_pk_mul_f32 v[100:101], v[100:101], v[102:103]
	s_nop 0
	v_cvt_pk_bf16_f32 v109, v100, v101
	global_store_dwordx4 v[98:99], v[106:109], off
	v_mul_f32_e32 v98, 0xbfb8aa3b, v94
	v_mul_f32_e32 v99, 0xbfb8aa3b, v95
	v_exp_f32_e32 v98, v98
	v_exp_f32_e32 v99, v99
	v_add_f32_e32 v98, 1.0, v98
	v_add_f32_e32 v99, 1.0, v99
	v_rcp_f32_e32 v98, v98
	v_rcp_f32_e32 v99, v99
	s_nop 0
	v_pk_mul_f32 v[94:95], v[94:95], v[98:99]
	s_nop 0
	v_pk_mul_f32 v[90:91], v[90:91], v[94:95]
	v_pk_mul_f32 v[94:95], v[96:97], v[148:149] op_sel_hi:[1,0]
	v_cvt_pk_bf16_f32 v90, v90, v91
	v_mul_f32_e32 v96, 0xbfb8aa3b, v94
	v_mul_f32_e32 v97, 0xbfb8aa3b, v95
	v_exp_f32_e32 v96, v96
	v_exp_f32_e32 v97, v97
	v_add_f32_e32 v96, 1.0, v96
	v_add_f32_e32 v97, 1.0, v97
	v_rcp_f32_e32 v96, v96
	v_rcp_f32_e32 v97, v97
	s_nop 0
	v_pk_mul_f32 v[94:95], v[94:95], v[96:97]
	s_nop 0
	v_pk_mul_f32 v[92:93], v[92:93], v[94:95]
	s_nop 0
	v_cvt_pk_bf16_f32 v91, v92, v93
	v_mul_f32_e32 v92, 0xbfb8aa3b, v86
	v_mul_f32_e32 v93, 0xbfb8aa3b, v87
	v_exp_f32_e32 v92, v92
	v_exp_f32_e32 v93, v93
	v_add_f32_e32 v92, 1.0, v92
	v_add_f32_e32 v93, 1.0, v93
	v_rcp_f32_e32 v92, v92
	v_rcp_f32_e32 v93, v93
	s_nop 0
	v_pk_mul_f32 v[86:87], v[86:87], v[92:93]
	s_nop 0
	v_pk_mul_f32 v[82:83], v[82:83], v[86:87]
	v_pk_mul_f32 v[86:87], v[88:89], v[148:149] op_sel_hi:[1,0]
	v_cvt_pk_bf16_f32 v92, v82, v83
	v_mul_f32_e32 v88, 0xbfb8aa3b, v86
	v_mul_f32_e32 v89, 0xbfb8aa3b, v87
	v_exp_f32_e32 v88, v88
	v_exp_f32_e32 v89, v89
	v_mad_i64_i32 v[82:83], s[22:23], v192, s38, v[114:115]
	v_add_f32_e32 v88, 1.0, v88
	v_add_f32_e32 v89, 1.0, v89
	v_rcp_f32_e32 v88, v88
	v_rcp_f32_e32 v89, v89
	v_lshl_add_u64 v[82:83], v[82:83], 0, v[116:117]
	v_pk_mul_f32 v[86:87], v[86:87], v[88:89]
	s_nop 0
	v_pk_mul_f32 v[84:85], v[84:85], v[86:87]
	s_nop 0
	v_cvt_pk_bf16_f32 v93, v84, v85
	global_store_dwordx4 v[82:83], v[90:93], off
	v_mul_f32_e32 v82, 0xbfb8aa3b, v78
	v_mul_f32_e32 v83, 0xbfb8aa3b, v79
	v_exp_f32_e32 v82, v82
	v_exp_f32_e32 v83, v83
	v_add_f32_e32 v82, 1.0, v82
	v_add_f32_e32 v83, 1.0, v83
	v_rcp_f32_e32 v82, v82
	v_rcp_f32_e32 v83, v83
	s_nop 0
	v_pk_mul_f32 v[78:79], v[78:79], v[82:83]
	s_nop 0
	v_pk_mul_f32 v[74:75], v[74:75], v[78:79]
	v_pk_mul_f32 v[78:79], v[80:81], v[146:147] op_sel_hi:[1,0]
	v_cvt_pk_bf16_f32 v74, v74, v75
	v_mul_f32_e32 v80, 0xbfb8aa3b, v78
	v_mul_f32_e32 v81, 0xbfb8aa3b, v79
	v_exp_f32_e32 v80, v80
	v_exp_f32_e32 v81, v81
	v_add_f32_e32 v80, 1.0, v80
	v_add_f32_e32 v81, 1.0, v81
	v_rcp_f32_e32 v80, v80
	v_rcp_f32_e32 v81, v81
	s_nop 0
	v_pk_mul_f32 v[78:79], v[78:79], v[80:81]
	s_nop 0
	v_pk_mul_f32 v[76:77], v[76:77], v[78:79]
	s_nop 0
	v_cvt_pk_bf16_f32 v75, v76, v77
	v_mul_f32_e32 v76, 0xbfb8aa3b, v70
	v_mul_f32_e32 v77, 0xbfb8aa3b, v71
	v_exp_f32_e32 v76, v76
	v_exp_f32_e32 v77, v77
	v_add_f32_e32 v76, 1.0, v76
	v_add_f32_e32 v77, 1.0, v77
	v_rcp_f32_e32 v76, v76
	v_rcp_f32_e32 v77, v77
	s_nop 0
	v_pk_mul_f32 v[70:71], v[70:71], v[76:77]
	s_nop 0
	v_pk_mul_f32 v[66:67], v[66:67], v[70:71]
	v_pk_mul_f32 v[70:71], v[72:73], v[146:147] op_sel_hi:[1,0]
	v_cvt_pk_bf16_f32 v76, v66, v67
	v_mul_f32_e32 v72, 0xbfb8aa3b, v70
	v_mul_f32_e32 v73, 0xbfb8aa3b, v71
	v_exp_f32_e32 v72, v72
	v_exp_f32_e32 v73, v73
	v_mad_i64_i32 v[66:67], s[22:23], v190, s38, v[114:115]
	v_add_f32_e32 v72, 1.0, v72
	v_add_f32_e32 v73, 1.0, v73
	v_rcp_f32_e32 v72, v72
	v_rcp_f32_e32 v73, v73
	v_lshl_add_u64 v[66:67], v[66:67], 0, v[116:117]
	v_pk_mul_f32 v[70:71], v[70:71], v[72:73]
	s_nop 0
	v_pk_mul_f32 v[68:69], v[68:69], v[70:71]
	s_nop 0
	v_cvt_pk_bf16_f32 v77, v68, v69
	global_store_dwordx4 v[66:67], v[74:77], off
	v_mul_f32_e32 v66, 0xbfb8aa3b, v62
	v_mul_f32_e32 v67, 0xbfb8aa3b, v63
	v_exp_f32_e32 v66, v66
	v_exp_f32_e32 v67, v67
	v_add_f32_e32 v66, 1.0, v66
	v_add_f32_e32 v67, 1.0, v67
	v_rcp_f32_e32 v66, v66
	v_rcp_f32_e32 v67, v67
	s_nop 0
	v_pk_mul_f32 v[62:63], v[62:63], v[66:67]
	s_nop 0
	v_pk_mul_f32 v[58:59], v[58:59], v[62:63]
	v_pk_mul_f32 v[62:63], v[64:65], v[140:141] op_sel_hi:[1,0]
	v_cvt_pk_bf16_f32 v58, v58, v59
	v_mul_f32_e32 v64, 0xbfb8aa3b, v62
	v_mul_f32_e32 v65, 0xbfb8aa3b, v63
	v_exp_f32_e32 v64, v64
	v_exp_f32_e32 v65, v65
	v_add_f32_e32 v64, 1.0, v64
	v_add_f32_e32 v65, 1.0, v65
	v_rcp_f32_e32 v64, v64
	v_rcp_f32_e32 v65, v65
	s_nop 0
	v_pk_mul_f32 v[62:63], v[62:63], v[64:65]
	s_nop 0
	v_pk_mul_f32 v[60:61], v[60:61], v[62:63]
	s_nop 0
	v_cvt_pk_bf16_f32 v59, v60, v61
	v_mul_f32_e32 v60, 0xbfb8aa3b, v54
	v_mul_f32_e32 v61, 0xbfb8aa3b, v55
	v_exp_f32_e32 v60, v60
	v_exp_f32_e32 v61, v61
	v_add_f32_e32 v60, 1.0, v60
	v_add_f32_e32 v61, 1.0, v61
	v_rcp_f32_e32 v60, v60
	v_rcp_f32_e32 v61, v61
	s_nop 0
	v_pk_mul_f32 v[54:55], v[54:55], v[60:61]
	s_nop 0
	v_pk_mul_f32 v[50:51], v[50:51], v[54:55]
	v_pk_mul_f32 v[54:55], v[56:57], v[140:141] op_sel_hi:[1,0]
	v_cvt_pk_bf16_f32 v60, v50, v51
	v_mul_f32_e32 v56, 0xbfb8aa3b, v54
	v_mul_f32_e32 v57, 0xbfb8aa3b, v55
	v_exp_f32_e32 v56, v56
	v_exp_f32_e32 v57, v57
	v_mad_i64_i32 v[50:51], s[22:23], v188, s38, v[114:115]
	v_add_f32_e32 v56, 1.0, v56
	v_add_f32_e32 v57, 1.0, v57
	v_rcp_f32_e32 v56, v56
	v_rcp_f32_e32 v57, v57
	v_lshl_add_u64 v[50:51], v[50:51], 0, v[116:117]
	v_pk_mul_f32 v[54:55], v[54:55], v[56:57]
	s_nop 0
	v_pk_mul_f32 v[52:53], v[52:53], v[54:55]
	s_nop 0
	v_cvt_pk_bf16_f32 v61, v52, v53
	global_store_dwordx4 v[50:51], v[58:61], off
	v_mul_f32_e32 v50, 0xbfb8aa3b, v46
	v_mul_f32_e32 v51, 0xbfb8aa3b, v47
	v_exp_f32_e32 v50, v50
	v_exp_f32_e32 v51, v51
	v_add_f32_e32 v50, 1.0, v50
	v_add_f32_e32 v51, 1.0, v51
	v_rcp_f32_e32 v50, v50
	v_rcp_f32_e32 v51, v51
	s_nop 0
	v_pk_mul_f32 v[46:47], v[46:47], v[50:51]
	s_nop 0
	v_pk_mul_f32 v[42:43], v[42:43], v[46:47]
	v_pk_mul_f32 v[46:47], v[48:49], v[138:139] op_sel_hi:[1,0]
	v_cvt_pk_bf16_f32 v42, v42, v43
	v_mul_f32_e32 v48, 0xbfb8aa3b, v46
	v_mul_f32_e32 v49, 0xbfb8aa3b, v47
	v_exp_f32_e32 v48, v48
	v_exp_f32_e32 v49, v49
	v_add_f32_e32 v48, 1.0, v48
	v_add_f32_e32 v49, 1.0, v49
	v_rcp_f32_e32 v48, v48
	v_rcp_f32_e32 v49, v49
	s_nop 0
	v_pk_mul_f32 v[46:47], v[46:47], v[48:49]
	s_nop 0
	v_pk_mul_f32 v[44:45], v[44:45], v[46:47]
	s_nop 0
	v_cvt_pk_bf16_f32 v43, v44, v45
	v_mul_f32_e32 v44, 0xbfb8aa3b, v38
	v_mul_f32_e32 v45, 0xbfb8aa3b, v39
	v_exp_f32_e32 v44, v44
	v_exp_f32_e32 v45, v45
	v_add_f32_e32 v44, 1.0, v44
	v_add_f32_e32 v45, 1.0, v45
	v_rcp_f32_e32 v44, v44
	v_rcp_f32_e32 v45, v45
	s_nop 0
	v_pk_mul_f32 v[38:39], v[38:39], v[44:45]
	s_nop 0
	v_pk_mul_f32 v[34:35], v[34:35], v[38:39]
	v_pk_mul_f32 v[38:39], v[40:41], v[138:139] op_sel_hi:[1,0]
	v_cvt_pk_bf16_f32 v44, v34, v35
	v_mul_f32_e32 v40, 0xbfb8aa3b, v38
	v_mul_f32_e32 v41, 0xbfb8aa3b, v39
	v_exp_f32_e32 v40, v40
	v_exp_f32_e32 v41, v41
	v_mad_i64_i32 v[34:35], s[22:23], v186, s38, v[114:115]
	v_add_f32_e32 v40, 1.0, v40
	v_add_f32_e32 v41, 1.0, v41
	v_rcp_f32_e32 v40, v40
	v_rcp_f32_e32 v41, v41
	v_lshl_add_u64 v[34:35], v[34:35], 0, v[116:117]
	v_pk_mul_f32 v[38:39], v[38:39], v[40:41]
	s_nop 0
	v_pk_mul_f32 v[36:37], v[36:37], v[38:39]
	s_nop 0
	v_cvt_pk_bf16_f32 v45, v36, v37
	global_store_dwordx4 v[34:35], v[42:45], off
	v_mul_f32_e32 v34, 0xbfb8aa3b, v30
	v_mul_f32_e32 v35, 0xbfb8aa3b, v31
	v_exp_f32_e32 v34, v34
	v_exp_f32_e32 v35, v35
	v_add_f32_e32 v34, 1.0, v34
	v_add_f32_e32 v35, 1.0, v35
	v_rcp_f32_e32 v34, v34
	v_rcp_f32_e32 v35, v35
	s_nop 0
	v_pk_mul_f32 v[30:31], v[30:31], v[34:35]
	s_nop 0
	v_pk_mul_f32 v[26:27], v[26:27], v[30:31]
	v_pk_mul_f32 v[30:31], v[32:33], v[132:133] op_sel_hi:[1,0]
	v_cvt_pk_bf16_f32 v26, v26, v27
	v_mul_f32_e32 v32, 0xbfb8aa3b, v30
	v_mul_f32_e32 v33, 0xbfb8aa3b, v31
	v_exp_f32_e32 v32, v32
	v_exp_f32_e32 v33, v33
	v_add_f32_e32 v32, 1.0, v32
	v_add_f32_e32 v33, 1.0, v33
	v_rcp_f32_e32 v32, v32
	v_rcp_f32_e32 v33, v33
	s_nop 0
	v_pk_mul_f32 v[30:31], v[30:31], v[32:33]
	s_nop 0
	v_pk_mul_f32 v[28:29], v[28:29], v[30:31]
	s_nop 0
	v_cvt_pk_bf16_f32 v27, v28, v29
	v_mul_f32_e32 v28, 0xbfb8aa3b, v22
	v_mul_f32_e32 v29, 0xbfb8aa3b, v23
	v_exp_f32_e32 v28, v28
	v_exp_f32_e32 v29, v29
	v_add_f32_e32 v28, 1.0, v28
	v_add_f32_e32 v29, 1.0, v29
	v_rcp_f32_e32 v28, v28
	v_rcp_f32_e32 v29, v29
	s_nop 0
	v_pk_mul_f32 v[22:23], v[22:23], v[28:29]
	s_nop 0
	v_pk_mul_f32 v[18:19], v[18:19], v[22:23]
	v_pk_mul_f32 v[22:23], v[24:25], v[132:133] op_sel_hi:[1,0]
	v_cvt_pk_bf16_f32 v28, v18, v19
	v_mul_f32_e32 v24, 0xbfb8aa3b, v22
	v_mul_f32_e32 v25, 0xbfb8aa3b, v23
	v_exp_f32_e32 v24, v24
	v_exp_f32_e32 v25, v25
	v_mad_i64_i32 v[18:19], s[22:23], v184, s38, v[114:115]
	v_add_f32_e32 v24, 1.0, v24
	v_add_f32_e32 v25, 1.0, v25
	v_rcp_f32_e32 v24, v24
	v_rcp_f32_e32 v25, v25
	v_lshl_add_u64 v[18:19], v[18:19], 0, v[116:117]
	v_pk_mul_f32 v[22:23], v[22:23], v[24:25]
	s_nop 0
	v_pk_mul_f32 v[20:21], v[20:21], v[22:23]
	s_nop 0
	v_cvt_pk_bf16_f32 v29, v20, v21
	global_store_dwordx4 v[18:19], v[26:29], off
	v_mul_f32_e32 v18, 0xbfb8aa3b, v14
	v_mul_f32_e32 v19, 0xbfb8aa3b, v15
	v_exp_f32_e32 v18, v18
	v_exp_f32_e32 v19, v19
	v_add_f32_e32 v18, 1.0, v18
	v_add_f32_e32 v19, 1.0, v19
	v_rcp_f32_e32 v18, v18
	v_rcp_f32_e32 v19, v19
	s_nop 0
	v_pk_mul_f32 v[14:15], v[14:15], v[18:19]
	s_nop 0
	v_pk_mul_f32 v[10:11], v[10:11], v[14:15]
	v_pk_mul_f32 v[14:15], v[16:17], v[130:131] op_sel_hi:[1,0]
	v_cvt_pk_bf16_f32 v10, v10, v11
	v_mul_f32_e32 v16, 0xbfb8aa3b, v14
	v_mul_f32_e32 v17, 0xbfb8aa3b, v15
	v_exp_f32_e32 v16, v16
	v_exp_f32_e32 v17, v17
	v_add_f32_e32 v16, 1.0, v16
	v_add_f32_e32 v17, 1.0, v17
	v_rcp_f32_e32 v16, v16
	v_rcp_f32_e32 v17, v17
	s_nop 0
	v_pk_mul_f32 v[14:15], v[14:15], v[16:17]
	s_nop 0
	v_pk_mul_f32 v[12:13], v[12:13], v[14:15]
	s_nop 0
	v_cvt_pk_bf16_f32 v11, v12, v13
	v_mul_f32_e32 v12, 0xbfb8aa3b, v6
	v_mul_f32_e32 v13, 0xbfb8aa3b, v7
	v_exp_f32_e32 v12, v12
	v_exp_f32_e32 v13, v13
	v_add_f32_e32 v12, 1.0, v12
	v_add_f32_e32 v13, 1.0, v13
	v_rcp_f32_e32 v12, v12
	v_rcp_f32_e32 v13, v13
	s_nop 0
	v_pk_mul_f32 v[6:7], v[6:7], v[12:13]
	s_nop 0
	v_pk_mul_f32 v[2:3], v[2:3], v[6:7]
	v_pk_mul_f32 v[6:7], v[8:9], v[130:131] op_sel_hi:[1,0]
	v_cvt_pk_bf16_f32 v12, v2, v3
	v_mul_f32_e32 v8, 0xbfb8aa3b, v6
	v_mul_f32_e32 v9, 0xbfb8aa3b, v7
	v_exp_f32_e32 v8, v8
	v_exp_f32_e32 v9, v9
	v_mad_i64_i32 v[2:3], s[22:23], v182, s38, v[114:115]
	v_add_f32_e32 v8, 1.0, v8
	v_add_f32_e32 v9, 1.0, v9
	v_rcp_f32_e32 v8, v8
	v_rcp_f32_e32 v9, v9
	v_lshl_add_u64 v[2:3], v[2:3], 0, v[116:117]
	v_pk_mul_f32 v[6:7], v[6:7], v[8:9]
	s_nop 0
	v_pk_mul_f32 v[4:5], v[4:5], v[6:7]
	s_nop 0
	v_cvt_pk_bf16_f32 v13, v4, v5
	global_store_dwordx4 v[2:3], v[10:13], off
	s_cbranch_vccz .LBB0_80
	s_waitcnt vmcnt(0)
	s_cmpk_gt_u32 s0, 0xff
	s_cbranch_scc1 .LBB0_87
	s_nop 0

.LBB0_103:
	s_cmp_eq_u32 s60, 17
	s_cselect_b64 s[6:7], -1, 0
	s_cmp_eq_u32 s60, 4
	s_cselect_b64 s[16:17], -1, 0
	s_or_b64 s[6:7], s[16:17], s[6:7]
	s_and_b64 s[6:7], s[6:7], exec
	v_readlane_b32 s6, v254, 37
	v_readlane_b32 s16, v254, 39
	v_readlane_b32 s7, v254, 38
	v_readlane_b32 s17, v254, 40
	s_cselect_b32 s58, s16, s6
	s_cselect_b32 s59, s17, s7
	s_add_u32 s61, s10, s4
	s_addc_u32 s62, s11, s5
	s_cmp_lg_u32 s60, 4
	s_mov_b64 s[6:7], -1
	v_cmp_ne_u32_e64 s[40:41], 1, v210
	s_cbranch_scc0 .LBB0_142
	v_mov_b32_e32 v2, v167
	s_and_b64 vcc, exec, s[40:41]
	v_readfirstlane_b32 s16, v2
	s_cbranch_vccnz .LBB0_141
	v_lshlrev_b32_e32 v0, 4, v2
	s_waitcnt lgkmcnt(0)
	v_add_u32_e32 v3, 0x2000, v0
	v_ashrrev_i32_e32 v4, 31, v3
	v_lshrrev_b32_e32 v4, 22, v4
	v_add_u32_e32 v4, v3, v4
	v_ashrrev_i32_e32 v4, 10, v4
	v_mul_i32_i24_e32 v5, 0x400, v4
	v_sub_u32_e32 v3, v3, v5
	v_lshrrev_b32_e32 v5, 4, v3
	v_bitop3_b32 v5, v5, v3, 32 bitop3:0x6c
	v_ashrrev_i32_e32 v3, 31, v5
	v_lshrrev_b32_e32 v3, 26, v3
	v_add_u32_e32 v6, v5, v3
	v_lshlrev_b32_e32 v7, 3, v4
	v_ashrrev_i32_e32 v3, 6, v6
	v_and_b32_e32 v7, -16, v7
	v_add_u32_e32 v7, v3, v7
	v_and_b32_e32 v3, 3, v3
	s_mov_b32 s1, 0x7fffffe0
	v_lshrrev_b32_e32 v8, 2, v7
	v_lshlrev_b32_e32 v9, 1, v7
	v_and_or_b32 v3, v7, s1, v3
	v_and_b32_e32 v8, 4, v8
	v_and_b32_e32 v9, 24, v9
	v_or3_b32 v3, v3, v8, v9
	v_mul_lo_u32 v8, v3, s0
	v_lshlrev_b32_e32 v3, 5, v4
	v_and_b32_e32 v4, 0xc0, v6
	v_sub_u32_e32 v4, v5, v4
	v_ashrrev_i16_sdwa v4, v211, sext(v4) dst_sel:DWORD dst_unused:UNUSED_PAD src0_sel:DWORD src1_sel:BYTE_0
	v_and_b32_e32 v3, 32, v3
	v_bfe_i32 v4, v4, 0, 16
	v_add_u32_e32 v6, v3, v4
	v_mul_lo_u32 v5, v7, s0
	v_add_lshl_u32 v158, v8, v6, 1
	v_add_lshl_u32 v160, v6, v5, 1
	v_bfe_i32 v6, v2, 27, 1
	v_lshrrev_b32_e32 v6, 22, v6
	v_add_u32_e32 v6, v0, v6
	v_and_b32_e32 v6, 0xfffffc00, v6
	v_sub_u32_e32 v0, v0, v6
	v_lshrrev_b32_e32 v6, 4, v0
	v_ashrrev_i32_e32 v8, 31, v2
	v_bitop3_b32 v0, v6, v0, 32 bitop3:0x6c
	v_lshrrev_b32_e32 v8, 26, v8
	v_ashrrev_i32_e32 v6, 31, v0
	v_add_u32_e32 v8, v2, v8
	v_lshrrev_b32_e32 v6, 26, v6
	v_ashrrev_i32_e32 v8, 6, v8
	v_add_u32_e32 v7, v0, v6
	v_lshlrev_b32_e32 v9, 3, v8
	v_ashrrev_i32_e32 v6, 6, v7
	v_and_b32_e32 v9, -16, v9
	v_add_u32_e32 v9, v6, v9
	v_and_b32_e32 v6, 3, v6
	v_lshrrev_b32_e32 v10, 2, v9
	v_lshlrev_b32_e32 v11, 1, v9
	v_readlane_b32 s26, v253, 35
	s_lshl_b32 s17, s0, 9
	v_and_or_b32 v6, v9, s1, v6
	v_and_b32_e32 v10, 4, v10
	v_and_b32_e32 v11, 24, v11
	v_and_b32_e32 v7, 0xc0, v7
	v_readlane_b32 s27, v253, 36
	s_ashr_i32 s22, s16, 6
	v_or3_b32 v6, v6, v10, v11
	v_sub_u32_e32 v0, v0, v7
	s_mul_hi_i32 s1, s17, s26
	s_mul_i32 s7, s17, s26
	v_readlane_b32 s26, v253, 39
	s_ashr_i32 s4, s16, 8
	s_lshl_b32 s6, s0, 8
	s_lshl_b32 s20, s22, 10
	v_mul_lo_u32 v10, v6, s0
	v_lshlrev_b32_e32 v6, 5, v8
	v_ashrrev_i16_sdwa v0, v211, sext(v0) dst_sel:DWORD dst_unused:UNUSED_PAD src0_sel:DWORD src1_sel:BYTE_0
	s_mul_i32 s23, s17, s26
	v_and_b32_e32 v6, 32, v6
	v_bfe_i32 v7, v0, 0, 16
	s_mul_hi_i32 s21, s17, s26
	s_add_u32 s30, s61, s23
	v_add_u32_e32 v11, v6, v7
	s_addc_u32 s31, s62, s21
	s_add_i32 s21, s20, 0
	v_add_lshl_u32 v0, v10, v11, 1
	s_add_i32 m0, s21, 0x10000
	v_mul_lo_u32 v8, v9, s0
	global_load_lds_dwordx4 v0, s[30:31]
	s_add_i32 m0, s21, 0x12000
	s_add_u32 s36, s56, s7
	v_add_lshl_u32 v178, v11, v8, 1
	global_load_lds_dwordx4 v158, s[30:31]
	s_addc_u32 s37, s57, s1
	s_mov_b32 m0, s21
	s_add_i32 s34, s21, 0x2000
	v_readlane_b32 s27, v253, 40
	global_load_lds_dwordx4 v178, s[36:37]
	s_mov_b32 m0, s34
	s_add_u32 s26, s30, s6
	global_load_lds_dwordx4 v160, s[36:37]
	s_addc_u32 s27, s31, 0
	s_add_i32 m0, s21, 0x14000
	s_mov_b32 s7, s5
	global_load_lds_dwordx4 v0, s[26:27]
	s_add_i32 m0, s21, 0x16000
	s_add_u32 s28, s36, s6
	s_addc_u32 s29, s37, 0
	s_add_i32 s63, s21, 0x4000
	global_load_lds_dwordx4 v158, s[26:27]
	s_mov_b32 m0, s63
	s_add_i32 s64, s21, 0x6000
	global_load_lds_dwordx4 v178, s[28:29]
	s_mov_b32 m0, s64
	s_cmp_lg_u32 s4, 1
	global_load_lds_dwordx4 v160, s[28:29]
	s_cbranch_scc1 .LBB0_107
	s_nop 0

.LBB0_119:
	s_add_u32 s36, s36, 0x80
	s_addc_u32 s37, s37, 0
	s_add_u32 s48, s30, 0x100
	v_mov_b32_e32 v2, 0
	s_addc_u32 s49, s31, 0
	s_mov_b32 s22, 0
	s_waitcnt lgkmcnt(0)
	v_mov_b32_e32 v3, v2
	v_mov_b32_e32 v4, v2
	v_mov_b32_e32 v5, v2
	v_mov_b32_e32 v6, v2
	v_mov_b32_e32 v7, v2
	v_mov_b32_e32 v8, v2
	v_mov_b32_e32 v9, v2
	v_mov_b32_e32 v18, v2
	v_mov_b32_e32 v19, v2
	v_mov_b32_e32 v20, v2
	v_mov_b32_e32 v21, v2
	v_mov_b32_e32 v22, v2
	v_mov_b32_e32 v23, v2
	v_mov_b32_e32 v24, v2
	v_mov_b32_e32 v25, v2
	v_mov_b32_e32 v34, v2
	v_mov_b32_e32 v35, v2
	v_mov_b32_e32 v36, v2
	v_mov_b32_e32 v37, v2
	v_mov_b32_e32 v38, v2
	v_mov_b32_e32 v39, v2
	v_mov_b32_e32 v40, v2
	v_mov_b32_e32 v41, v2
	v_mov_b32_e32 v50, v2
	v_mov_b32_e32 v51, v2
	v_mov_b32_e32 v52, v2
	v_mov_b32_e32 v53, v2
	v_mov_b32_e32 v54, v2
	v_mov_b32_e32 v55, v2
	v_mov_b32_e32 v56, v2
	v_mov_b32_e32 v57, v2
	v_mov_b32_e32 v10, v2
	v_mov_b32_e32 v11, v2
	v_mov_b32_e32 v12, v2
	v_mov_b32_e32 v13, v2
	v_mov_b32_e32 v14, v2
	v_mov_b32_e32 v15, v2
	v_mov_b32_e32 v16, v2
	v_mov_b32_e32 v17, v2
	v_mov_b32_e32 v26, v2
	v_mov_b32_e32 v27, v2
	v_mov_b32_e32 v28, v2
	v_mov_b32_e32 v29, v2
	v_mov_b32_e32 v30, v2
	v_mov_b32_e32 v31, v2
	v_mov_b32_e32 v32, v2
	v_mov_b32_e32 v33, v2
	v_mov_b32_e32 v42, v2
	v_mov_b32_e32 v43, v2
	v_mov_b32_e32 v44, v2
	v_mov_b32_e32 v45, v2
	v_mov_b32_e32 v46, v2
	v_mov_b32_e32 v47, v2
	v_mov_b32_e32 v48, v2
	v_mov_b32_e32 v49, v2
	v_mov_b32_e32 v58, v2
	v_mov_b32_e32 v59, v2
	v_mov_b32_e32 v60, v2
	v_mov_b32_e32 v61, v2
	v_mov_b32_e32 v62, v2
	v_mov_b32_e32 v63, v2
	v_mov_b32_e32 v64, v2
	v_mov_b32_e32 v65, v2
	v_mov_b32_e32 v66, v2
	v_mov_b32_e32 v67, v2
	v_mov_b32_e32 v68, v2
	v_mov_b32_e32 v69, v2
	v_mov_b32_e32 v70, v2
	v_mov_b32_e32 v71, v2
	v_mov_b32_e32 v72, v2
	v_mov_b32_e32 v73, v2
	v_mov_b32_e32 v82, v2
	v_mov_b32_e32 v83, v2
	v_mov_b32_e32 v84, v2
	v_mov_b32_e32 v85, v2
	v_mov_b32_e32 v86, v2
	v_mov_b32_e32 v87, v2
	v_mov_b32_e32 v88, v2
	v_mov_b32_e32 v89, v2
	v_mov_b32_e32 v98, v2
	v_mov_b32_e32 v99, v2
	v_mov_b32_e32 v100, v2
	v_mov_b32_e32 v101, v2
	v_mov_b32_e32 v102, v2
	v_mov_b32_e32 v103, v2
	v_mov_b32_e32 v104, v2
	v_mov_b32_e32 v105, v2
	v_mov_b32_e32 v114, v2
	v_mov_b32_e32 v115, v2
	v_mov_b32_e32 v116, v2
	v_mov_b32_e32 v117, v2
	v_mov_b32_e32 v118, v2
	v_mov_b32_e32 v119, v2
	v_mov_b32_e32 v120, v2
	v_mov_b32_e32 v121, v2
	v_mov_b32_e32 v74, v2
	v_mov_b32_e32 v75, v2
	v_mov_b32_e32 v76, v2
	v_mov_b32_e32 v77, v2
	v_mov_b32_e32 v78, v2
	v_mov_b32_e32 v79, v2
	v_mov_b32_e32 v80, v2
	v_mov_b32_e32 v81, v2
	v_mov_b32_e32 v90, v2
	v_mov_b32_e32 v91, v2
	v_mov_b32_e32 v92, v2
	v_mov_b32_e32 v93, v2
	v_mov_b32_e32 v94, v2
	v_mov_b32_e32 v95, v2
	v_mov_b32_e32 v96, v2
	v_mov_b32_e32 v97, v2
	v_mov_b32_e32 v106, v2
	v_mov_b32_e32 v107, v2
	v_mov_b32_e32 v108, v2
	v_mov_b32_e32 v109, v2
	v_mov_b32_e32 v110, v2
	v_mov_b32_e32 v111, v2
	v_mov_b32_e32 v112, v2
	v_mov_b32_e32 v113, v2
	v_mov_b32_e32 v122, v2
	v_mov_b32_e32 v123, v2
	v_mov_b32_e32 v124, v2
	v_mov_b32_e32 v125, v2
	v_mov_b32_e32 v126, v2
	v_mov_b32_e32 v127, v2
	v_mov_b32_e32 v128, v2
	v_mov_b32_e32 v129, v2
	s_cmpk_gt_u32 s16, 0xff
	s_cbranch_scc0 .Lrs_i3_pre
	s_barrier
.Lrs_i3_pre:
.LBB0_120:
	s_add_i32 s23, s22, 2
	s_add_u32 s1, s36, 0x80
	s_addc_u32 s30, s37, 0
	s_add_i32 s33, 0, 0x10000
	v_add_u32_e32 v142, s33, v203
	ds_read_b128 v[130:133], v142
	ds_read_b128 v[134:137], v142 offset:1024
	ds_read_b128 v[138:141], v142 offset:2048
	ds_read_b128 v[142:145], v142 offset:3072
	s_cmp_eq_u32 s69, s22
	s_cselect_b32 s31, s27, s30
	s_cselect_b32 s30, s26, s1
	s_cselect_b32 s47, s29, s49
	s_cselect_b32 s46, s28, s48
	v_lshl_add_u64 v[176:177], s[36:37], 0, v[180:181]
	s_add_i32 m0, s21, 0xc000
	ds_read_b128 v[146:149], v205
	ds_read_b128 v[150:153], v205 offset:1024
	ds_read_b128 v[154:157], v205 offset:2048
	ds_read_b128 v[184:187], v205 offset:3072
	ds_read_b128 v[188:191], v205 offset:4096
	ds_read_b128 v[192:195], v205 offset:5120
	ds_read_b128 v[196:199], v205 offset:6144
	ds_read_b128 v[206:209], v205 offset:7168
	global_load_lds_dwordx4 v[176:177], off
	v_lshl_add_u64 v[176:177], s[36:37], 0, v[182:183]
	s_add_i32 m0, s21, 0xe000
	s_nop 0
	global_load_lds_dwordx4 v[176:177], off
	s_add_i32 s1, 0, 0x14000
	v_add_u32_e32 v168, s1, v203
	ds_read_b128 v[216:219], v168
	ds_read_b128 v[230:233], v168 offset:1024
	ds_read_b128 v[234:237], v168 offset:2048
	ds_read_b128 v[238:241], v168 offset:3072
	s_waitcnt vmcnt(8)
	s_waitcnt lgkmcnt(0)
	s_barrier
	s_setprio 1
	v_mfma_f32_16x16x32_bf16 v[126:129], v[130:133], v[146:149], v[126:129]
	v_mfma_f32_16x16x32_bf16 v[122:125], v[138:141], v[146:149], v[122:125]
	v_mfma_f32_16x16x32_bf16 v[110:113], v[130:133], v[154:157], v[110:113]
	v_mfma_f32_16x16x32_bf16 v[106:109], v[138:141], v[154:157], v[106:109]
	v_mfma_f32_16x16x32_bf16 v[94:97], v[130:133], v[188:191], v[94:97]
	v_mfma_f32_16x16x32_bf16 v[90:93], v[138:141], v[188:191], v[90:93]
	v_mfma_f32_16x16x32_bf16 v[78:81], v[130:133], v[196:199], v[78:81]
	v_mfma_f32_16x16x32_bf16 v[74:77], v[138:141], v[196:199], v[74:77]
	v_mfma_f32_16x16x32_bf16 v[126:129], v[134:137], v[150:153], v[126:129]
	v_mfma_f32_16x16x32_bf16 v[122:125], v[142:145], v[150:153], v[122:125]
	v_mfma_f32_16x16x32_bf16 v[110:113], v[134:137], v[184:187], v[110:113]
	v_mfma_f32_16x16x32_bf16 v[106:109], v[142:145], v[184:187], v[106:109]
	v_mfma_f32_16x16x32_bf16 v[94:97], v[134:137], v[192:195], v[94:97]
	v_mfma_f32_16x16x32_bf16 v[90:93], v[142:145], v[192:195], v[90:93]
	v_mfma_f32_16x16x32_bf16 v[78:81], v[134:137], v[206:209], v[78:81]
	v_mfma_f32_16x16x32_bf16 v[74:77], v[142:145], v[206:209], v[74:77]
	v_mfma_f32_16x16x32_bf16 v[118:121], v[216:219], v[146:149], v[118:121]
	v_mfma_f32_16x16x32_bf16 v[114:117], v[234:237], v[146:149], v[114:117]
	v_mfma_f32_16x16x32_bf16 v[102:105], v[216:219], v[154:157], v[102:105]
	v_mfma_f32_16x16x32_bf16 v[98:101], v[234:237], v[154:157], v[98:101]
	v_mfma_f32_16x16x32_bf16 v[86:89], v[216:219], v[188:191], v[86:89]
	v_mfma_f32_16x16x32_bf16 v[82:85], v[234:237], v[188:191], v[82:85]
	v_mfma_f32_16x16x32_bf16 v[70:73], v[216:219], v[196:199], v[70:73]
	v_mfma_f32_16x16x32_bf16 v[66:69], v[234:237], v[196:199], v[66:69]
	v_mfma_f32_16x16x32_bf16 v[118:121], v[230:233], v[150:153], v[118:121]
	v_mfma_f32_16x16x32_bf16 v[114:117], v[238:241], v[150:153], v[114:117]
	v_mfma_f32_16x16x32_bf16 v[102:105], v[230:233], v[184:187], v[102:105]
	v_mfma_f32_16x16x32_bf16 v[98:101], v[238:241], v[184:187], v[98:101]
	v_mfma_f32_16x16x32_bf16 v[86:89], v[230:233], v[192:195], v[86:89]
	v_mfma_f32_16x16x32_bf16 v[82:85], v[238:241], v[192:195], v[82:85]
	v_mfma_f32_16x16x32_bf16 v[70:73], v[230:233], v[206:209], v[70:73]
	v_mfma_f32_16x16x32_bf16 v[66:69], v[238:241], v[206:209], v[66:69]
	s_setprio 0
	s_barrier
	ds_read_b128 v[146:149], v205 offset:16384
	ds_read_b128 v[150:153], v205 offset:17408
	ds_read_b128 v[154:157], v205 offset:18432
	ds_read_b128 v[184:187], v205 offset:19456
	ds_read_b128 v[188:191], v205 offset:20480
	ds_read_b128 v[192:195], v205 offset:21504
	ds_read_b128 v[196:199], v205 offset:22528
	ds_read_b128 v[206:209], v205 offset:23552
	s_add_i32 s22, s33, s20
	v_lshl_add_u64 v[176:177], s[46:47], 0, v[0:1]
	s_mov_b32 m0, s22
	s_nop 0
	global_load_lds_dwordx4 v[176:177], off
	v_lshl_add_u64 v[200:201], s[46:47], 0, v[158:159]
	s_add_i32 m0, s22, 0x2000
	s_nop 0
	global_load_lds_dwordx4 v[200:201], off
	s_mov_b32 m0, s21
	v_lshl_add_u64 v[220:221], s[30:31], 0, v[178:179]
	global_load_lds_dwordx4 v[220:221], off
	v_lshl_add_u64 v[242:243], s[30:31], 0, v[160:161]
	s_mov_b32 m0, s34
	s_nop 0
	global_load_lds_dwordx4 v[242:243], off
	s_add_u32 s46, s46, s6
	s_addc_u32 s47, s47, 0
	s_add_i32 s1, s1, s20
	v_lshl_add_u64 v[244:245], s[46:47], 0, v[0:1]
	s_mov_b32 m0, s1
	v_lshl_add_u64 v[246:247], s[46:47], 0, v[158:159]
	global_load_lds_dwordx4 v[244:245], off
	s_add_i32 m0, s1, 0x2000
	s_nop 0
	global_load_lds_dwordx4 v[246:247], off
	s_waitcnt vmcnt(8)
	s_waitcnt lgkmcnt(0)
	s_barrier
	s_setprio 1
	v_mfma_f32_16x16x32_bf16 v[62:65], v[130:133], v[146:149], v[62:65]
	v_mfma_f32_16x16x32_bf16 v[58:61], v[138:141], v[146:149], v[58:61]
	v_mfma_f32_16x16x32_bf16 v[46:49], v[130:133], v[154:157], v[46:49]
	v_mfma_f32_16x16x32_bf16 v[42:45], v[138:141], v[154:157], v[42:45]
	v_mfma_f32_16x16x32_bf16 v[30:33], v[130:133], v[188:191], v[30:33]
	v_mfma_f32_16x16x32_bf16 v[26:29], v[138:141], v[188:191], v[26:29]
	v_mfma_f32_16x16x32_bf16 v[14:17], v[130:133], v[196:199], v[14:17]
	v_mfma_f32_16x16x32_bf16 v[10:13], v[138:141], v[196:199], v[10:13]
	v_mfma_f32_16x16x32_bf16 v[62:65], v[134:137], v[150:153], v[62:65]
	v_mfma_f32_16x16x32_bf16 v[58:61], v[142:145], v[150:153], v[58:61]
	v_mfma_f32_16x16x32_bf16 v[46:49], v[134:137], v[184:187], v[46:49]
	v_mfma_f32_16x16x32_bf16 v[42:45], v[142:145], v[184:187], v[42:45]
	v_mfma_f32_16x16x32_bf16 v[30:33], v[134:137], v[192:195], v[30:33]
	v_mfma_f32_16x16x32_bf16 v[26:29], v[142:145], v[192:195], v[26:29]
	v_mfma_f32_16x16x32_bf16 v[14:17], v[134:137], v[206:209], v[14:17]
	v_mfma_f32_16x16x32_bf16 v[10:13], v[142:145], v[206:209], v[10:13]
	v_mfma_f32_16x16x32_bf16 v[54:57], v[216:219], v[146:149], v[54:57]
	v_mfma_f32_16x16x32_bf16 v[50:53], v[234:237], v[146:149], v[50:53]
	v_mfma_f32_16x16x32_bf16 v[38:41], v[216:219], v[154:157], v[38:41]
	v_mfma_f32_16x16x32_bf16 v[34:37], v[234:237], v[154:157], v[34:37]
	v_mfma_f32_16x16x32_bf16 v[22:25], v[216:219], v[188:191], v[22:25]
	v_mfma_f32_16x16x32_bf16 v[18:21], v[234:237], v[188:191], v[18:21]
	v_mfma_f32_16x16x32_bf16 v[6:9], v[216:219], v[196:199], v[6:9]
	v_mfma_f32_16x16x32_bf16 v[2:5], v[234:237], v[196:199], v[2:5]
	v_mfma_f32_16x16x32_bf16 v[54:57], v[230:233], v[150:153], v[54:57]
	v_mfma_f32_16x16x32_bf16 v[50:53], v[238:241], v[150:153], v[50:53]
	v_mfma_f32_16x16x32_bf16 v[38:41], v[230:233], v[184:187], v[38:41]
	v_mfma_f32_16x16x32_bf16 v[34:37], v[238:241], v[184:187], v[34:37]
	v_mfma_f32_16x16x32_bf16 v[22:25], v[230:233], v[192:195], v[22:25]
	v_mfma_f32_16x16x32_bf16 v[18:21], v[238:241], v[192:195], v[18:21]
	v_mfma_f32_16x16x32_bf16 v[6:9], v[230:233], v[206:209], v[6:9]
	v_mfma_f32_16x16x32_bf16 v[2:5], v[238:241], v[206:209], v[2:5]
	s_setprio 0
	s_barrier
	s_add_i32 s1, 0, 0x18000
	v_add_u32_e32 v142, s1, v203
	ds_read_b128 v[130:133], v142
	ds_read_b128 v[134:137], v142 offset:1024
	ds_read_b128 v[138:141], v142 offset:2048
	ds_read_b128 v[142:145], v142 offset:3072
	s_add_u32 s30, s30, s6
	s_addc_u32 s31, s31, 0
	s_mov_b32 m0, s63
	v_lshl_add_u64 v[216:217], s[30:31], 0, v[178:179]
	ds_read_b128 v[146:149], v205 offset:32768
	ds_read_b128 v[150:153], v205 offset:33792
	ds_read_b128 v[154:157], v205 offset:34816
	ds_read_b128 v[184:187], v205 offset:35840
	ds_read_b128 v[188:191], v205 offset:36864
	ds_read_b128 v[192:195], v205 offset:37888
	ds_read_b128 v[196:199], v205 offset:38912
	ds_read_b128 v[206:209], v205 offset:39936
	global_load_lds_dwordx4 v[216:217], off
	v_lshl_add_u64 v[216:217], s[30:31], 0, v[160:161]
	s_mov_b32 m0, s64
	s_nop 0
	global_load_lds_dwordx4 v[216:217], off
	s_add_i32 s22, 0, 0x1c000
	v_add_u32_e32 v168, s22, v203
	ds_read_b128 v[216:219], v168
	ds_read_b128 v[230:233], v168 offset:1024
	ds_read_b128 v[234:237], v168 offset:2048
	ds_read_b128 v[238:241], v168 offset:3072
	s_waitcnt vmcnt(8)
	s_waitcnt lgkmcnt(0)
	s_barrier
	s_setprio 1
	v_mfma_f32_16x16x32_bf16 v[126:129], v[130:133], v[146:149], v[126:129]
	v_mfma_f32_16x16x32_bf16 v[122:125], v[138:141], v[146:149], v[122:125]
	v_mfma_f32_16x16x32_bf16 v[110:113], v[130:133], v[154:157], v[110:113]
	v_mfma_f32_16x16x32_bf16 v[106:109], v[138:141], v[154:157], v[106:109]
	v_mfma_f32_16x16x32_bf16 v[94:97], v[130:133], v[188:191], v[94:97]
	v_mfma_f32_16x16x32_bf16 v[90:93], v[138:141], v[188:191], v[90:93]
	v_mfma_f32_16x16x32_bf16 v[78:81], v[130:133], v[196:199], v[78:81]
	v_mfma_f32_16x16x32_bf16 v[74:77], v[138:141], v[196:199], v[74:77]
	v_mfma_f32_16x16x32_bf16 v[126:129], v[134:137], v[150:153], v[126:129]
	v_mfma_f32_16x16x32_bf16 v[122:125], v[142:145], v[150:153], v[122:125]
	v_mfma_f32_16x16x32_bf16 v[110:113], v[134:137], v[184:187], v[110:113]
	v_mfma_f32_16x16x32_bf16 v[106:109], v[142:145], v[184:187], v[106:109]
	v_mfma_f32_16x16x32_bf16 v[94:97], v[134:137], v[192:195], v[94:97]
	v_mfma_f32_16x16x32_bf16 v[90:93], v[142:145], v[192:195], v[90:93]
	v_mfma_f32_16x16x32_bf16 v[78:81], v[134:137], v[206:209], v[78:81]
	v_mfma_f32_16x16x32_bf16 v[74:77], v[142:145], v[206:209], v[74:77]
	v_mfma_f32_16x16x32_bf16 v[118:121], v[216:219], v[146:149], v[118:121]
	v_mfma_f32_16x16x32_bf16 v[114:117], v[234:237], v[146:149], v[114:117]
	v_mfma_f32_16x16x32_bf16 v[102:105], v[216:219], v[154:157], v[102:105]
	v_mfma_f32_16x16x32_bf16 v[98:101], v[234:237], v[154:157], v[98:101]
	v_mfma_f32_16x16x32_bf16 v[86:89], v[216:219], v[188:191], v[86:89]
	v_mfma_f32_16x16x32_bf16 v[82:85], v[234:237], v[188:191], v[82:85]
	v_mfma_f32_16x16x32_bf16 v[70:73], v[216:219], v[196:199], v[70:73]
	v_mfma_f32_16x16x32_bf16 v[66:69], v[234:237], v[196:199], v[66:69]
	v_mfma_f32_16x16x32_bf16 v[118:121], v[230:233], v[150:153], v[118:121]
	v_mfma_f32_16x16x32_bf16 v[114:117], v[238:241], v[150:153], v[114:117]
	v_mfma_f32_16x16x32_bf16 v[102:105], v[230:233], v[184:187], v[102:105]
	v_mfma_f32_16x16x32_bf16 v[98:101], v[238:241], v[184:187], v[98:101]
	v_mfma_f32_16x16x32_bf16 v[86:89], v[230:233], v[192:195], v[86:89]
	v_mfma_f32_16x16x32_bf16 v[82:85], v[238:241], v[192:195], v[82:85]
	v_mfma_f32_16x16x32_bf16 v[70:73], v[230:233], v[206:209], v[70:73]
	v_mfma_f32_16x16x32_bf16 v[66:69], v[238:241], v[206:209], v[66:69]
	s_setprio 0
	s_barrier
	ds_read_b128 v[146:149], v205 offset:49152
	ds_read_b128 v[150:153], v205 offset:50176
	ds_read_b128 v[154:157], v205 offset:51200
	ds_read_b128 v[184:187], v205 offset:52224
	ds_read_b128 v[188:191], v205 offset:53248
	ds_read_b128 v[192:195], v205 offset:54272
	ds_read_b128 v[196:199], v205 offset:55296
	ds_read_b128 v[206:209], v205 offset:56320
	s_add_i32 s1, s1, s20
	v_lshl_add_u64 v[176:177], v[176:177], 0, s[12:13]
	s_mov_b32 m0, s1
	s_nop 0
	global_load_lds_dwordx4 v[176:177], off
	v_lshl_add_u64 v[176:177], v[200:201], 0, s[12:13]
	s_add_i32 m0, s1, 0x2000
	s_nop 0
	global_load_lds_dwordx4 v[176:177], off
	s_mov_b32 m0, s65
	v_lshl_add_u64 v[176:177], v[220:221], 0, s[12:13]
	global_load_lds_dwordx4 v[176:177], off
	v_lshl_add_u64 v[176:177], v[242:243], 0, s[12:13]
	s_mov_b32 m0, s66
	s_nop 0
	global_load_lds_dwordx4 v[176:177], off
	s_add_i32 s1, s22, s20
	v_lshl_add_u64 v[176:177], v[244:245], 0, s[12:13]
	s_mov_b32 m0, s1
	s_nop 0
	global_load_lds_dwordx4 v[176:177], off
	v_lshl_add_u64 v[176:177], v[246:247], 0, s[12:13]
	s_add_i32 m0, s1, 0x2000
	s_nop 0
	global_load_lds_dwordx4 v[176:177], off
	s_waitcnt vmcnt(8)
	s_waitcnt lgkmcnt(0)
	s_barrier
	s_setprio 1
	v_mfma_f32_16x16x32_bf16 v[62:65], v[130:133], v[146:149], v[62:65]
	v_mfma_f32_16x16x32_bf16 v[58:61], v[138:141], v[146:149], v[58:61]
	v_mfma_f32_16x16x32_bf16 v[46:49], v[130:133], v[154:157], v[46:49]
	v_mfma_f32_16x16x32_bf16 v[42:45], v[138:141], v[154:157], v[42:45]
	v_mfma_f32_16x16x32_bf16 v[30:33], v[130:133], v[188:191], v[30:33]
	v_mfma_f32_16x16x32_bf16 v[26:29], v[138:141], v[188:191], v[26:29]
	v_mfma_f32_16x16x32_bf16 v[14:17], v[130:133], v[196:199], v[14:17]
	v_mfma_f32_16x16x32_bf16 v[10:13], v[138:141], v[196:199], v[10:13]
	v_mfma_f32_16x16x32_bf16 v[62:65], v[134:137], v[150:153], v[62:65]
	v_mfma_f32_16x16x32_bf16 v[58:61], v[142:145], v[150:153], v[58:61]
	v_mfma_f32_16x16x32_bf16 v[46:49], v[134:137], v[184:187], v[46:49]
	v_mfma_f32_16x16x32_bf16 v[42:45], v[142:145], v[184:187], v[42:45]
	v_mfma_f32_16x16x32_bf16 v[30:33], v[134:137], v[192:195], v[30:33]
	v_mfma_f32_16x16x32_bf16 v[26:29], v[142:145], v[192:195], v[26:29]
	v_mfma_f32_16x16x32_bf16 v[14:17], v[134:137], v[206:209], v[14:17]
	v_mfma_f32_16x16x32_bf16 v[10:13], v[142:145], v[206:209], v[10:13]
	v_mfma_f32_16x16x32_bf16 v[54:57], v[216:219], v[146:149], v[54:57]
	v_mfma_f32_16x16x32_bf16 v[50:53], v[234:237], v[146:149], v[50:53]
	v_mfma_f32_16x16x32_bf16 v[38:41], v[216:219], v[154:157], v[38:41]
	v_mfma_f32_16x16x32_bf16 v[34:37], v[234:237], v[154:157], v[34:37]
	v_mfma_f32_16x16x32_bf16 v[22:25], v[216:219], v[188:191], v[22:25]
	v_mfma_f32_16x16x32_bf16 v[18:21], v[234:237], v[188:191], v[18:21]
	v_mfma_f32_16x16x32_bf16 v[6:9], v[216:219], v[196:199], v[6:9]
	v_mfma_f32_16x16x32_bf16 v[2:5], v[234:237], v[196:199], v[2:5]
	v_mfma_f32_16x16x32_bf16 v[54:57], v[230:233], v[150:153], v[54:57]
	v_mfma_f32_16x16x32_bf16 v[50:53], v[238:241], v[150:153], v[50:53]
	v_mfma_f32_16x16x32_bf16 v[38:41], v[230:233], v[184:187], v[38:41]
	v_mfma_f32_16x16x32_bf16 v[34:37], v[238:241], v[184:187], v[34:37]
	v_mfma_f32_16x16x32_bf16 v[22:25], v[230:233], v[192:195], v[22:25]
	v_mfma_f32_16x16x32_bf16 v[18:21], v[238:241], v[192:195], v[18:21]
	v_mfma_f32_16x16x32_bf16 v[6:9], v[230:233], v[206:209], v[6:9]
	v_mfma_f32_16x16x32_bf16 v[2:5], v[238:241], v[206:209], v[2:5]
	s_setprio 0
	s_add_u32 s36, s36, 0x100
	s_addc_u32 s37, s37, 0
	s_add_u32 s48, s48, 0x100
	s_addc_u32 s49, s49, 0
	s_cmp_ge_u32 s23, s68
	s_mov_b32 s22, s23
	s_barrier
	s_cbranch_scc0 .LBB0_120
	s_cmpk_gt_u32 s16, 0xff
	s_cbranch_scc1 .Lrs_i3_post
	s_barrier
.Lrs_i3_post:
	v_and_b32_e32 v131, 64, v212
	v_xor_b32_e32 v130, 16, v212
	v_add_u32_e32 v131, 64, v131
	v_cmp_lt_i32_e32 vcc, v130, v131
	v_lshl_or_b32 v184, s4, 8, v204
	v_lshl_add_u32 v186, s72, 8, v202
	v_cndmask_b32_e32 v130, v212, v130, vcc
	v_ashrrev_i32_e32 v185, 31, v184
	v_lshlrev_b32_e32 v206, 2, v130
	v_xor_b32_e32 v130, 32, v212
	v_cmp_lt_i32_e32 vcc, v130, v131
	v_lshlrev_b64 v[176:177], 1, v[184:185]
	v_ashrrev_i32_e32 v187, 31, v186
	v_cndmask_b32_e32 v130, v212, v130, vcc
	v_lshl_add_u64 v[188:189], s[96:97], 0, v[176:177]
	v_lshlrev_b64 v[208:209], 11, v[186:187]
	v_lshlrev_b32_e32 v207, 2, v130
	v_lshl_add_u64 v[130:131], v[188:189], 0, v[208:209]
	global_load_dwordx4 v[216:219], v[130:131], off
	global_load_dwordx4 v[154:157], v[130:131], off offset:256
	v_or_b32_e32 v198, 16, v186
	v_ashrrev_i32_e32 v199, 31, v198
	v_or_b32_e32 v194, 32, v186
	v_lshlrev_b64 v[200:201], 11, v[198:199]
	v_ashrrev_i32_e32 v195, 31, v194
	v_or_b32_e32 v190, 48, v186
	v_lshl_add_u64 v[130:131], v[188:189], 0, v[200:201]
	v_lshlrev_b64 v[196:197], 11, v[194:195]
	v_ashrrev_i32_e32 v191, 31, v190
	global_load_dwordx4 v[150:153], v[130:131], off
	global_load_dwordx4 v[146:149], v[130:131], off offset:256
	v_lshl_add_u64 v[130:131], v[188:189], 0, v[196:197]
	v_lshlrev_b64 v[192:193], 11, v[190:191]
	global_load_dwordx4 v[142:145], v[130:131], off
	global_load_dwordx4 v[134:137], v[130:131], off offset:256
	v_lshl_add_u64 v[130:131], v[188:189], 0, v[192:193]
	global_load_dwordx4 v[138:141], v[130:131], off
	s_nop 0
	global_load_dwordx4 v[130:133], v[130:131], off offset:256
	s_lshl_b32 s36, s4, 2
	s_ashr_i32 s37, s36, 31
	s_waitcnt vmcnt(0)
	v_lshlrev_b32_e32 v220, 16, v216
	v_and_b32_e32 v221, 0xffff0000, v216
	v_lshlrev_b32_e32 v216, 16, v217
	v_and_b32_e32 v217, 0xffff0000, v217
	v_pk_add_f32 v[128:129], v[128:129], v[216:217]
	v_pk_add_f32 v[126:127], v[126:127], v[220:221]
	v_lshlrev_b32_e32 v216, 16, v218
	v_and_b32_e32 v217, 0xffff0000, v218
	v_lshlrev_b32_e32 v218, 16, v219
	v_and_b32_e32 v219, 0xffff0000, v219
	v_pk_add_f32 v[218:219], v[124:125], v[218:219]
	v_pk_add_f32 v[124:125], v[122:123], v[216:217]
	v_cvt_pk_bf16_f32 v122, v126, v127
	v_lshl_add_u64 v[126:127], s[96:97], 0, v[208:209]
	v_cvt_pk_bf16_f32 v123, v128, v129
	v_cvt_pk_bf16_f32 v124, v124, v125
	v_cvt_pk_bf16_f32 v125, v218, v219
	v_lshl_add_u64 v[126:127], v[126:127], 0, v[176:177]
	global_store_dwordx4 v[126:127], v[122:125], off
	v_lshlrev_b32_e32 v128, 16, v122
	s_nop 0
	v_and_b32_e32 v122, 0xffff0000, v122
	v_mul_f32_e32 v122, v122, v122
	v_fmac_f32_e32 v122, v128, v128
	v_lshlrev_b32_e32 v128, 16, v123
	v_and_b32_e32 v123, 0xffff0000, v123
	v_mul_f32_e32 v123, v123, v123
	v_fmac_f32_e32 v123, v128, v128
	v_add_f32_e32 v122, v122, v123
	v_lshlrev_b32_e32 v123, 16, v124
	v_and_b32_e32 v124, 0xffff0000, v124
	v_mul_f32_e32 v124, v124, v124
	v_fmac_f32_e32 v124, v123, v123
	v_add_f32_e32 v122, v124, v122
	v_and_b32_e32 v124, 0xffff0000, v125
	v_lshlrev_b32_e32 v123, 16, v125
	v_mul_f32_e32 v124, v124, v124
	v_fmac_f32_e32 v124, v123, v123
	v_add_f32_e32 v128, v124, v122
	v_lshlrev_b32_e32 v122, 16, v154
	v_and_b32_e32 v123, 0xffff0000, v154
	v_lshlrev_b32_e32 v124, 16, v155
	v_and_b32_e32 v125, 0xffff0000, v155
	v_pk_add_f32 v[120:121], v[120:121], v[124:125]
	v_pk_add_f32 v[118:119], v[118:119], v[122:123]
	v_lshlrev_b32_e32 v122, 16, v156
	v_and_b32_e32 v123, 0xffff0000, v156
	v_lshlrev_b32_e32 v124, 16, v157
	v_and_b32_e32 v125, 0xffff0000, v157
	v_pk_add_f32 v[124:125], v[116:117], v[124:125]
	v_pk_add_f32 v[116:117], v[114:115], v[122:123]
	v_cvt_pk_bf16_f32 v114, v118, v119
	v_cvt_pk_bf16_f32 v115, v120, v121
	v_cvt_pk_bf16_f32 v116, v116, v117
	v_cvt_pk_bf16_f32 v117, v124, v125
	global_store_dwordx4 v[126:127], v[114:117], off offset:256
	v_lshlrev_b32_e32 v118, 16, v114
	s_nop 0
	v_and_b32_e32 v114, 0xffff0000, v114
	v_mul_f32_e32 v114, v114, v114
	v_fmac_f32_e32 v114, v118, v118
	v_lshlrev_b32_e32 v118, 16, v115
	v_and_b32_e32 v115, 0xffff0000, v115
	v_mul_f32_e32 v115, v115, v115
	v_add_f32_e32 v114, v114, v128
	v_fmac_f32_e32 v115, v118, v118
	v_add_f32_e32 v114, v115, v114
	v_lshlrev_b32_e32 v115, 16, v116
	v_and_b32_e32 v116, 0xffff0000, v116
	v_mul_f32_e32 v116, v116, v116
	v_fmac_f32_e32 v116, v115, v115
	v_add_f32_e32 v114, v116, v114
	v_and_b32_e32 v116, 0xffff0000, v117
	v_lshlrev_b32_e32 v115, 16, v117
	v_mul_f32_e32 v116, v116, v116
	v_fmac_f32_e32 v116, v115, v115
	v_add_f32_e32 v114, v116, v114
	ds_bpermute_b32 v115, v206, v114
	s_waitcnt lgkmcnt(0)
	v_add_f32_e32 v114, v114, v115
	ds_bpermute_b32 v115, v207, v114
	s_and_saveexec_b64 s[30:31], s[42:43]
	s_cbranch_execz .LBB0_123
	v_lshlrev_b64 v[116:117], 6, v[186:187]
	v_lshl_add_u64 v[116:117], s[58:59], 0, v[116:117]
	v_lshl_add_u64 v[116:117], s[36:37], 2, v[116:117]
	s_lshl_b32 s4, s67, 2
	v_lshl_add_u64 v[116:117], v[116:117], 0, s[4:5]
	s_waitcnt lgkmcnt(0)
	v_add_f32_e32 v114, v114, v115
	global_store_dword v[116:117], v114, off

.LBB0_138:
	s_waitcnt vmcnt(0)
	v_readlane_b32 s70, v253, 62
	v_readlane_b32 s68, v254, 48
	s_cmpk_gt_u32 s16, 0xff
	v_readlane_b32 s71, v253, 63
	v_readlane_b32 s72, v254, 0
	v_readlane_b32 s69, v254, 49
	s_cbranch_scc1 .LBB0_140
	s_nop 0

.LBB0_142:
	s_andn2_b64 vcc, exec, s[6:7]
	s_cbranch_vccnz .LBB0_179
	v_mov_b32_e32 v2, v167
	s_and_b64 vcc, exec, s[40:41]
	v_readfirstlane_b32 s16, v2
	s_cbranch_vccnz .LBB0_179
	v_lshlrev_b32_e32 v0, 4, v2
	s_waitcnt lgkmcnt(0)
	v_add_u32_e32 v3, 0x2000, v0
	v_ashrrev_i32_e32 v4, 31, v3
	v_lshrrev_b32_e32 v4, 22, v4
	v_add_u32_e32 v4, v3, v4
	v_ashrrev_i32_e32 v4, 10, v4
	v_mul_i32_i24_e32 v5, 0x400, v4
	v_sub_u32_e32 v3, v3, v5
	v_lshrrev_b32_e32 v5, 4, v3
	v_bitop3_b32 v5, v5, v3, 32 bitop3:0x6c
	v_ashrrev_i32_e32 v3, 31, v5
	v_lshrrev_b32_e32 v3, 26, v3
	v_add_u32_e32 v6, v5, v3
	v_lshlrev_b32_e32 v7, 3, v4
	v_ashrrev_i32_e32 v3, 6, v6
	v_and_b32_e32 v7, -16, v7
	v_add_u32_e32 v7, v3, v7
	v_and_b32_e32 v3, 3, v3
	s_mov_b32 s1, 0x7fffffe0
	v_lshrrev_b32_e32 v8, 2, v7
	v_lshlrev_b32_e32 v9, 1, v7
	v_and_or_b32 v3, v7, s1, v3
	v_and_b32_e32 v8, 4, v8
	v_and_b32_e32 v9, 24, v9
	v_or3_b32 v3, v3, v8, v9
	v_mul_lo_u32 v8, v3, s0
	v_lshlrev_b32_e32 v3, 5, v4
	v_and_b32_e32 v4, 0xc0, v6
	v_sub_u32_e32 v4, v5, v4
	v_ashrrev_i16_sdwa v4, v211, sext(v4) dst_sel:DWORD dst_unused:UNUSED_PAD src0_sel:DWORD src1_sel:BYTE_0
	v_and_b32_e32 v3, 32, v3
	v_bfe_i32 v4, v4, 0, 16
	v_add_u32_e32 v6, v3, v4
	v_mul_lo_u32 v5, v7, s0
	v_add_lshl_u32 v146, v8, v6, 1
	v_add_lshl_u32 v148, v6, v5, 1
	v_bfe_i32 v6, v2, 27, 1
	v_lshrrev_b32_e32 v6, 22, v6
	v_add_u32_e32 v6, v0, v6
	v_and_b32_e32 v6, 0xfffffc00, v6
	v_sub_u32_e32 v0, v0, v6
	v_lshrrev_b32_e32 v6, 4, v0
	v_ashrrev_i32_e32 v8, 31, v2
	v_bitop3_b32 v0, v6, v0, 32 bitop3:0x6c
	v_lshrrev_b32_e32 v8, 26, v8
	v_ashrrev_i32_e32 v6, 31, v0
	v_add_u32_e32 v8, v2, v8
	v_lshrrev_b32_e32 v6, 26, v6
	v_ashrrev_i32_e32 v8, 6, v8
	v_add_u32_e32 v7, v0, v6
	v_lshlrev_b32_e32 v9, 3, v8
	v_ashrrev_i32_e32 v6, 6, v7
	v_and_b32_e32 v9, -16, v9
	v_add_u32_e32 v9, v6, v9
	v_and_b32_e32 v6, 3, v6
	v_lshrrev_b32_e32 v10, 2, v9
	v_lshlrev_b32_e32 v11, 1, v9
	v_readlane_b32 s26, v253, 35
	s_lshl_b32 s17, s0, 9
	v_and_or_b32 v6, v9, s1, v6
	v_and_b32_e32 v10, 4, v10
	v_and_b32_e32 v11, 24, v11
	v_and_b32_e32 v7, 0xc0, v7
	v_readlane_b32 s27, v253, 36
	s_ashr_i32 s22, s16, 6
	v_or3_b32 v6, v6, v10, v11
	v_sub_u32_e32 v0, v0, v7
	s_mul_hi_i32 s1, s17, s26
	s_mul_i32 s7, s17, s26
	v_readlane_b32 s26, v253, 39
	s_ashr_i32 s4, s16, 8
	s_lshl_b32 s6, s0, 8
	s_lshl_b32 s20, s22, 10
	v_mul_lo_u32 v10, v6, s0
	v_lshlrev_b32_e32 v6, 5, v8
	v_ashrrev_i16_sdwa v0, v211, sext(v0) dst_sel:DWORD dst_unused:UNUSED_PAD src0_sel:DWORD src1_sel:BYTE_0
	s_mul_i32 s23, s17, s26
	v_and_b32_e32 v6, 32, v6
	v_bfe_i32 v7, v0, 0, 16
	s_mul_hi_i32 s21, s17, s26
	s_add_u32 s30, s61, s23
	v_add_u32_e32 v11, v6, v7
	s_addc_u32 s31, s62, s21
	s_add_i32 s21, s20, 0
	v_add_lshl_u32 v0, v10, v11, 1
	s_add_i32 m0, s21, 0x10000
	v_mul_lo_u32 v8, v9, s0
	global_load_lds_dwordx4 v0, s[30:31]
	s_add_i32 m0, s21, 0x12000
	s_add_u32 s36, s56, s7
	v_add_lshl_u32 v150, v11, v8, 1
	global_load_lds_dwordx4 v146, s[30:31]
	s_addc_u32 s37, s57, s1
	s_mov_b32 m0, s21
	s_add_i32 s34, s21, 0x2000
	v_readlane_b32 s27, v253, 40
	global_load_lds_dwordx4 v150, s[36:37]
	s_mov_b32 m0, s34
	s_add_u32 s26, s30, s6
	global_load_lds_dwordx4 v148, s[36:37]
	s_addc_u32 s27, s31, 0
	s_add_i32 m0, s21, 0x14000
	s_mov_b32 s7, s5
	global_load_lds_dwordx4 v0, s[26:27]
	s_add_i32 m0, s21, 0x16000
	s_add_u32 s28, s36, s6
	s_addc_u32 s29, s37, 0
	s_add_i32 s63, s21, 0x4000
	global_load_lds_dwordx4 v146, s[26:27]
	s_mov_b32 m0, s63
	s_add_i32 s64, s21, 0x6000
	global_load_lds_dwordx4 v150, s[28:29]
	s_mov_b32 m0, s64
	s_cmp_lg_u32 s4, 1
	global_load_lds_dwordx4 v148, s[28:29]
	s_cbranch_scc1 .LBB0_146
	s_nop 0

.Lrs_i4_pre:
.LBB0_159:
	s_add_i32 s23, s22, 2
	s_add_u32 s1, s36, 0x80
	s_addc_u32 s30, s37, 0
	s_add_i32 s33, 0, 0x10000
	v_add_u32_e32 v142, s33, v181
	ds_read_b128 v[130:133], v142
	ds_read_b128 v[134:137], v142 offset:1024
	ds_read_b128 v[138:141], v142 offset:2048
	ds_read_b128 v[142:145], v142 offset:3072
	s_cmp_eq_u32 s68, s22
	s_cselect_b32 s31, s27, s30
	s_cselect_b32 s30, s26, s1
	s_cselect_b32 s47, s29, s49
	s_cselect_b32 s46, s28, s48
	v_lshl_add_u64 v[160:161], s[36:37], 0, v[152:153]
	s_add_i32 m0, s21, 0xc000
	ds_read_b128 v[156:159], v183
	ds_read_b128 v[184:187], v183 offset:1024
	ds_read_b128 v[188:191], v183 offset:2048
	ds_read_b128 v[192:195], v183 offset:3072
	ds_read_b128 v[196:199], v183 offset:4096
	ds_read_b128 v[200:203], v183 offset:5120
	ds_read_b128 v[204:207], v183 offset:6144
	ds_read_b128 v[216:219], v183 offset:7168
	global_load_lds_dwordx4 v[160:161], off
	v_lshl_add_u64 v[160:161], s[36:37], 0, v[154:155]
	s_add_i32 m0, s21, 0xe000
	s_nop 0
	global_load_lds_dwordx4 v[160:161], off
	s_add_i32 s1, 0, 0x14000
	v_add_u32_e32 v160, s1, v181
	ds_read_b128 v[230:233], v160
	ds_read_b128 v[234:237], v160 offset:1024
	ds_read_b128 v[238:241], v160 offset:2048
	ds_read_b128 v[242:245], v160 offset:3072
	s_waitcnt vmcnt(8)
	s_waitcnt lgkmcnt(0)
	s_barrier
	s_setprio 1
	v_mfma_f32_16x16x32_bf16 v[126:129], v[130:133], v[156:159], v[126:129]
	v_mfma_f32_16x16x32_bf16 v[122:125], v[138:141], v[156:159], v[122:125]
	v_mfma_f32_16x16x32_bf16 v[110:113], v[130:133], v[188:191], v[110:113]
	v_mfma_f32_16x16x32_bf16 v[106:109], v[138:141], v[188:191], v[106:109]
	v_mfma_f32_16x16x32_bf16 v[94:97], v[130:133], v[196:199], v[94:97]
	v_mfma_f32_16x16x32_bf16 v[90:93], v[138:141], v[196:199], v[90:93]
	v_mfma_f32_16x16x32_bf16 v[78:81], v[130:133], v[204:207], v[78:81]
	v_mfma_f32_16x16x32_bf16 v[74:77], v[138:141], v[204:207], v[74:77]
	v_mfma_f32_16x16x32_bf16 v[126:129], v[134:137], v[184:187], v[126:129]
	v_mfma_f32_16x16x32_bf16 v[122:125], v[142:145], v[184:187], v[122:125]
	v_mfma_f32_16x16x32_bf16 v[110:113], v[134:137], v[192:195], v[110:113]
	v_mfma_f32_16x16x32_bf16 v[106:109], v[142:145], v[192:195], v[106:109]
	v_mfma_f32_16x16x32_bf16 v[94:97], v[134:137], v[200:203], v[94:97]
	v_mfma_f32_16x16x32_bf16 v[90:93], v[142:145], v[200:203], v[90:93]
	v_mfma_f32_16x16x32_bf16 v[78:81], v[134:137], v[216:219], v[78:81]
	v_mfma_f32_16x16x32_bf16 v[74:77], v[142:145], v[216:219], v[74:77]
	v_mfma_f32_16x16x32_bf16 v[118:121], v[230:233], v[156:159], v[118:121]
	v_mfma_f32_16x16x32_bf16 v[114:117], v[238:241], v[156:159], v[114:117]
	v_mfma_f32_16x16x32_bf16 v[102:105], v[230:233], v[188:191], v[102:105]
	v_mfma_f32_16x16x32_bf16 v[98:101], v[238:241], v[188:191], v[98:101]
	v_mfma_f32_16x16x32_bf16 v[86:89], v[230:233], v[196:199], v[86:89]
	v_mfma_f32_16x16x32_bf16 v[82:85], v[238:241], v[196:199], v[82:85]
	v_mfma_f32_16x16x32_bf16 v[70:73], v[230:233], v[204:207], v[70:73]
	v_mfma_f32_16x16x32_bf16 v[66:69], v[238:241], v[204:207], v[66:69]
	v_mfma_f32_16x16x32_bf16 v[118:121], v[234:237], v[184:187], v[118:121]
	v_mfma_f32_16x16x32_bf16 v[114:117], v[242:245], v[184:187], v[114:117]
	v_mfma_f32_16x16x32_bf16 v[102:105], v[234:237], v[192:195], v[102:105]
	v_mfma_f32_16x16x32_bf16 v[98:101], v[242:245], v[192:195], v[98:101]
	v_mfma_f32_16x16x32_bf16 v[86:89], v[234:237], v[200:203], v[86:89]
	v_mfma_f32_16x16x32_bf16 v[82:85], v[242:245], v[200:203], v[82:85]
	v_mfma_f32_16x16x32_bf16 v[70:73], v[234:237], v[216:219], v[70:73]
	v_mfma_f32_16x16x32_bf16 v[66:69], v[242:245], v[216:219], v[66:69]
	s_setprio 0
	s_barrier
	ds_read_b128 v[156:159], v183 offset:16384
	ds_read_b128 v[184:187], v183 offset:17408
	ds_read_b128 v[188:191], v183 offset:18432
	ds_read_b128 v[192:195], v183 offset:19456
	ds_read_b128 v[196:199], v183 offset:20480
	ds_read_b128 v[200:203], v183 offset:21504
	ds_read_b128 v[204:207], v183 offset:22528
	ds_read_b128 v[216:219], v183 offset:23552
	s_add_i32 s22, s33, s20
	v_lshl_add_u64 v[160:161], s[46:47], 0, v[0:1]
	s_mov_b32 m0, s22
	v_lshl_add_u64 v[176:177], s[46:47], 0, v[146:147]
	global_load_lds_dwordx4 v[160:161], off
	s_add_i32 m0, s22, 0x2000
	s_nop 0
	global_load_lds_dwordx4 v[176:177], off
	s_mov_b32 m0, s21
	v_lshl_add_u64 v[178:179], s[30:31], 0, v[150:151]
	global_load_lds_dwordx4 v[178:179], off
	v_lshl_add_u64 v[208:209], s[30:31], 0, v[148:149]
	s_mov_b32 m0, s34
	s_nop 0
	global_load_lds_dwordx4 v[208:209], off
	s_add_u32 s46, s46, s6
	s_addc_u32 s47, s47, 0
	s_add_i32 s1, s1, s20
	v_lshl_add_u64 v[220:221], s[46:47], 0, v[0:1]
	s_mov_b32 m0, s1
	v_lshl_add_u64 v[246:247], s[46:47], 0, v[146:147]
	global_load_lds_dwordx4 v[220:221], off
	s_add_i32 m0, s1, 0x2000
	s_nop 0
	global_load_lds_dwordx4 v[246:247], off
	s_waitcnt vmcnt(8)
	s_waitcnt lgkmcnt(0)
	s_barrier
	s_setprio 1
	v_mfma_f32_16x16x32_bf16 v[62:65], v[130:133], v[156:159], v[62:65]
	v_mfma_f32_16x16x32_bf16 v[58:61], v[138:141], v[156:159], v[58:61]
	v_mfma_f32_16x16x32_bf16 v[46:49], v[130:133], v[188:191], v[46:49]
	v_mfma_f32_16x16x32_bf16 v[42:45], v[138:141], v[188:191], v[42:45]
	v_mfma_f32_16x16x32_bf16 v[30:33], v[130:133], v[196:199], v[30:33]
	v_mfma_f32_16x16x32_bf16 v[26:29], v[138:141], v[196:199], v[26:29]
	v_mfma_f32_16x16x32_bf16 v[14:17], v[130:133], v[204:207], v[14:17]
	v_mfma_f32_16x16x32_bf16 v[10:13], v[138:141], v[204:207], v[10:13]
	v_mfma_f32_16x16x32_bf16 v[62:65], v[134:137], v[184:187], v[62:65]
	v_mfma_f32_16x16x32_bf16 v[58:61], v[142:145], v[184:187], v[58:61]
	v_mfma_f32_16x16x32_bf16 v[46:49], v[134:137], v[192:195], v[46:49]
	v_mfma_f32_16x16x32_bf16 v[42:45], v[142:145], v[192:195], v[42:45]
	v_mfma_f32_16x16x32_bf16 v[30:33], v[134:137], v[200:203], v[30:33]
	v_mfma_f32_16x16x32_bf16 v[26:29], v[142:145], v[200:203], v[26:29]
	v_mfma_f32_16x16x32_bf16 v[14:17], v[134:137], v[216:219], v[14:17]
	v_mfma_f32_16x16x32_bf16 v[10:13], v[142:145], v[216:219], v[10:13]
	v_mfma_f32_16x16x32_bf16 v[54:57], v[230:233], v[156:159], v[54:57]
	v_mfma_f32_16x16x32_bf16 v[50:53], v[238:241], v[156:159], v[50:53]
	v_mfma_f32_16x16x32_bf16 v[38:41], v[230:233], v[188:191], v[38:41]
	v_mfma_f32_16x16x32_bf16 v[34:37], v[238:241], v[188:191], v[34:37]
	v_mfma_f32_16x16x32_bf16 v[22:25], v[230:233], v[196:199], v[22:25]
	v_mfma_f32_16x16x32_bf16 v[18:21], v[238:241], v[196:199], v[18:21]
	v_mfma_f32_16x16x32_bf16 v[6:9], v[230:233], v[204:207], v[6:9]
	v_mfma_f32_16x16x32_bf16 v[2:5], v[238:241], v[204:207], v[2:5]
	v_mfma_f32_16x16x32_bf16 v[54:57], v[234:237], v[184:187], v[54:57]
	v_mfma_f32_16x16x32_bf16 v[50:53], v[242:245], v[184:187], v[50:53]
	v_mfma_f32_16x16x32_bf16 v[38:41], v[234:237], v[192:195], v[38:41]
	v_mfma_f32_16x16x32_bf16 v[34:37], v[242:245], v[192:195], v[34:37]
	v_mfma_f32_16x16x32_bf16 v[22:25], v[234:237], v[200:203], v[22:25]
	v_mfma_f32_16x16x32_bf16 v[18:21], v[242:245], v[200:203], v[18:21]
	v_mfma_f32_16x16x32_bf16 v[6:9], v[234:237], v[216:219], v[6:9]
	v_mfma_f32_16x16x32_bf16 v[2:5], v[242:245], v[216:219], v[2:5]
	s_setprio 0
	s_barrier
	s_add_i32 s1, 0, 0x18000
	v_add_u32_e32 v142, s1, v181
	ds_read_b128 v[130:133], v142
	ds_read_b128 v[134:137], v142 offset:1024
	ds_read_b128 v[138:141], v142 offset:2048
	ds_read_b128 v[142:145], v142 offset:3072
	s_add_u32 s30, s30, s6
	s_addc_u32 s31, s31, 0
	s_mov_b32 m0, s63
	v_lshl_add_u64 v[230:231], s[30:31], 0, v[150:151]
	ds_read_b128 v[156:159], v183 offset:32768
	ds_read_b128 v[184:187], v183 offset:33792
	ds_read_b128 v[188:191], v183 offset:34816
	ds_read_b128 v[192:195], v183 offset:35840
	ds_read_b128 v[196:199], v183 offset:36864
	ds_read_b128 v[200:203], v183 offset:37888
	ds_read_b128 v[204:207], v183 offset:38912
	ds_read_b128 v[216:219], v183 offset:39936
	global_load_lds_dwordx4 v[230:231], off
	v_lshl_add_u64 v[230:231], s[30:31], 0, v[148:149]
	s_mov_b32 m0, s64
	s_nop 0
	global_load_lds_dwordx4 v[230:231], off
	s_add_i32 s22, 0, 0x1c000
	v_add_u32_e32 v168, s22, v181
	ds_read_b128 v[230:233], v168
	ds_read_b128 v[234:237], v168 offset:1024
	ds_read_b128 v[238:241], v168 offset:2048
	ds_read_b128 v[242:245], v168 offset:3072
	s_waitcnt vmcnt(8)
	s_waitcnt lgkmcnt(0)
	s_barrier
	s_setprio 1
	v_mfma_f32_16x16x32_bf16 v[126:129], v[130:133], v[156:159], v[126:129]
	v_mfma_f32_16x16x32_bf16 v[122:125], v[138:141], v[156:159], v[122:125]
	v_mfma_f32_16x16x32_bf16 v[110:113], v[130:133], v[188:191], v[110:113]
	v_mfma_f32_16x16x32_bf16 v[106:109], v[138:141], v[188:191], v[106:109]
	v_mfma_f32_16x16x32_bf16 v[94:97], v[130:133], v[196:199], v[94:97]
	v_mfma_f32_16x16x32_bf16 v[90:93], v[138:141], v[196:199], v[90:93]
	v_mfma_f32_16x16x32_bf16 v[78:81], v[130:133], v[204:207], v[78:81]
	v_mfma_f32_16x16x32_bf16 v[74:77], v[138:141], v[204:207], v[74:77]
	v_mfma_f32_16x16x32_bf16 v[126:129], v[134:137], v[184:187], v[126:129]
	v_mfma_f32_16x16x32_bf16 v[122:125], v[142:145], v[184:187], v[122:125]
	v_mfma_f32_16x16x32_bf16 v[110:113], v[134:137], v[192:195], v[110:113]
	v_mfma_f32_16x16x32_bf16 v[106:109], v[142:145], v[192:195], v[106:109]
	v_mfma_f32_16x16x32_bf16 v[94:97], v[134:137], v[200:203], v[94:97]
	v_mfma_f32_16x16x32_bf16 v[90:93], v[142:145], v[200:203], v[90:93]
	v_mfma_f32_16x16x32_bf16 v[78:81], v[134:137], v[216:219], v[78:81]
	v_mfma_f32_16x16x32_bf16 v[74:77], v[142:145], v[216:219], v[74:77]
	v_mfma_f32_16x16x32_bf16 v[118:121], v[230:233], v[156:159], v[118:121]
	v_mfma_f32_16x16x32_bf16 v[114:117], v[238:241], v[156:159], v[114:117]
	v_mfma_f32_16x16x32_bf16 v[102:105], v[230:233], v[188:191], v[102:105]
	v_mfma_f32_16x16x32_bf16 v[98:101], v[238:241], v[188:191], v[98:101]
	v_mfma_f32_16x16x32_bf16 v[86:89], v[230:233], v[196:199], v[86:89]
	v_mfma_f32_16x16x32_bf16 v[82:85], v[238:241], v[196:199], v[82:85]
	v_mfma_f32_16x16x32_bf16 v[70:73], v[230:233], v[204:207], v[70:73]
	v_mfma_f32_16x16x32_bf16 v[66:69], v[238:241], v[204:207], v[66:69]
	v_mfma_f32_16x16x32_bf16 v[118:121], v[234:237], v[184:187], v[118:121]
	v_mfma_f32_16x16x32_bf16 v[114:117], v[242:245], v[184:187], v[114:117]
	v_mfma_f32_16x16x32_bf16 v[102:105], v[234:237], v[192:195], v[102:105]
	v_mfma_f32_16x16x32_bf16 v[98:101], v[242:245], v[192:195], v[98:101]
	v_mfma_f32_16x16x32_bf16 v[86:89], v[234:237], v[200:203], v[86:89]
	v_mfma_f32_16x16x32_bf16 v[82:85], v[242:245], v[200:203], v[82:85]
	v_mfma_f32_16x16x32_bf16 v[70:73], v[234:237], v[216:219], v[70:73]
	v_mfma_f32_16x16x32_bf16 v[66:69], v[242:245], v[216:219], v[66:69]
	s_setprio 0
	s_barrier
	ds_read_b128 v[156:159], v183 offset:49152
	ds_read_b128 v[184:187], v183 offset:50176
	ds_read_b128 v[188:191], v183 offset:51200
	ds_read_b128 v[192:195], v183 offset:52224
	ds_read_b128 v[196:199], v183 offset:53248
	ds_read_b128 v[200:203], v183 offset:54272
	ds_read_b128 v[204:207], v183 offset:55296
	ds_read_b128 v[216:219], v183 offset:56320
	s_add_i32 s1, s1, s20
	v_lshl_add_u64 v[160:161], v[160:161], 0, s[12:13]
	s_mov_b32 m0, s1
	s_nop 0
	global_load_lds_dwordx4 v[160:161], off
	v_lshl_add_u64 v[160:161], v[176:177], 0, s[12:13]
	s_add_i32 m0, s1, 0x2000
	s_nop 0
	global_load_lds_dwordx4 v[160:161], off
	s_mov_b32 m0, s65
	v_lshl_add_u64 v[160:161], v[178:179], 0, s[12:13]
	global_load_lds_dwordx4 v[160:161], off
	v_lshl_add_u64 v[160:161], v[208:209], 0, s[12:13]
	s_mov_b32 m0, s66
	s_nop 0
	global_load_lds_dwordx4 v[160:161], off
	s_add_i32 s1, s22, s20
	v_lshl_add_u64 v[160:161], v[220:221], 0, s[12:13]
	s_mov_b32 m0, s1
	s_nop 0
	global_load_lds_dwordx4 v[160:161], off
	v_lshl_add_u64 v[160:161], v[246:247], 0, s[12:13]
	s_add_i32 m0, s1, 0x2000
	s_nop 0
	global_load_lds_dwordx4 v[160:161], off
	s_waitcnt vmcnt(8)
	s_waitcnt lgkmcnt(0)
	s_barrier
	s_setprio 1
	v_mfma_f32_16x16x32_bf16 v[62:65], v[130:133], v[156:159], v[62:65]
	v_mfma_f32_16x16x32_bf16 v[58:61], v[138:141], v[156:159], v[58:61]
	v_mfma_f32_16x16x32_bf16 v[46:49], v[130:133], v[188:191], v[46:49]
	v_mfma_f32_16x16x32_bf16 v[42:45], v[138:141], v[188:191], v[42:45]
	v_mfma_f32_16x16x32_bf16 v[30:33], v[130:133], v[196:199], v[30:33]
	v_mfma_f32_16x16x32_bf16 v[26:29], v[138:141], v[196:199], v[26:29]
	v_mfma_f32_16x16x32_bf16 v[14:17], v[130:133], v[204:207], v[14:17]
	v_mfma_f32_16x16x32_bf16 v[10:13], v[138:141], v[204:207], v[10:13]
	v_mfma_f32_16x16x32_bf16 v[62:65], v[134:137], v[184:187], v[62:65]
	v_mfma_f32_16x16x32_bf16 v[58:61], v[142:145], v[184:187], v[58:61]
	v_mfma_f32_16x16x32_bf16 v[46:49], v[134:137], v[192:195], v[46:49]
	v_mfma_f32_16x16x32_bf16 v[42:45], v[142:145], v[192:195], v[42:45]
	v_mfma_f32_16x16x32_bf16 v[30:33], v[134:137], v[200:203], v[30:33]
	v_mfma_f32_16x16x32_bf16 v[26:29], v[142:145], v[200:203], v[26:29]
	v_mfma_f32_16x16x32_bf16 v[14:17], v[134:137], v[216:219], v[14:17]
	v_mfma_f32_16x16x32_bf16 v[10:13], v[142:145], v[216:219], v[10:13]
	v_mfma_f32_16x16x32_bf16 v[54:57], v[230:233], v[156:159], v[54:57]
	v_mfma_f32_16x16x32_bf16 v[50:53], v[238:241], v[156:159], v[50:53]
	v_mfma_f32_16x16x32_bf16 v[38:41], v[230:233], v[188:191], v[38:41]
	v_mfma_f32_16x16x32_bf16 v[34:37], v[238:241], v[188:191], v[34:37]
	v_mfma_f32_16x16x32_bf16 v[22:25], v[230:233], v[196:199], v[22:25]
	v_mfma_f32_16x16x32_bf16 v[18:21], v[238:241], v[196:199], v[18:21]
	v_mfma_f32_16x16x32_bf16 v[6:9], v[230:233], v[204:207], v[6:9]
	v_mfma_f32_16x16x32_bf16 v[2:5], v[238:241], v[204:207], v[2:5]
	v_mfma_f32_16x16x32_bf16 v[54:57], v[234:237], v[184:187], v[54:57]
	v_mfma_f32_16x16x32_bf16 v[50:53], v[242:245], v[184:187], v[50:53]
	v_mfma_f32_16x16x32_bf16 v[38:41], v[234:237], v[192:195], v[38:41]
	v_mfma_f32_16x16x32_bf16 v[34:37], v[242:245], v[192:195], v[34:37]
	v_mfma_f32_16x16x32_bf16 v[22:25], v[234:237], v[200:203], v[22:25]
	v_mfma_f32_16x16x32_bf16 v[18:21], v[242:245], v[200:203], v[18:21]
	v_mfma_f32_16x16x32_bf16 v[6:9], v[234:237], v[216:219], v[6:9]
	v_mfma_f32_16x16x32_bf16 v[2:5], v[242:245], v[216:219], v[2:5]
	s_setprio 0
	s_add_u32 s36, s36, 0x100
	s_addc_u32 s37, s37, 0
	s_add_u32 s48, s48, 0x100
	s_addc_u32 s49, s49, 0
	s_cmp_ge_u32 s23, s0
	s_mov_b32 s22, s23
	s_barrier
	s_cbranch_scc0 .LBB0_159
	s_cmpk_gt_u32 s16, 0xff
	s_cbranch_scc1 .Lrs_i4_post
	s_barrier
.Lrs_i4_post:
	v_readlane_b32 s22, v254, 31
	v_readlane_b32 s23, v254, 32
	s_load_dwordx2 s[22:23], s[22:23], 0x0
	v_lshl_add_u32 v158, s71, 8, v180
	v_lshl_or_b32 v156, s4, 8, v182
	v_ashrrev_i32_e32 v157, 31, v156
	v_ashrrev_i32_e32 v159, 31, v158
	s_waitcnt lgkmcnt(0)
	v_lshl_add_u64 v[160:161], v[156:157], 2, s[22:23]
	v_lshlrev_b64 v[130:131], 12, v[158:159]
	v_lshl_add_u64 v[130:131], v[160:161], 0, v[130:131]
	global_load_dwordx4 v[186:189], v[130:131], off
	global_load_dwordx4 v[190:193], v[130:131], off offset:16
	global_load_dwordx4 v[194:197], v[130:131], off offset:512
	global_load_dwordx4 v[198:201], v[130:131], off offset:528
	v_or_b32_e32 v178, 16, v158
	v_ashrrev_i32_e32 v179, 31, v178
	v_lshlrev_b64 v[130:131], 12, v[178:179]
	v_lshl_add_u64 v[134:135], v[160:161], 0, v[130:131]
	global_load_dwordx4 v[138:141], v[134:135], off offset:16
	global_load_dwordx4 v[142:145], v[134:135], off
	global_load_dwordx4 v[130:133], v[134:135], off offset:528
	s_nop 0
	global_load_dwordx4 v[134:137], v[134:135], off offset:512
	v_and_b32_e32 v169, 64, v212
	v_xor_b32_e32 v168, 16, v212
	v_add_u32_e32 v169, 64, v169
	v_xor_b32_e32 v176, 32, v212
	v_cmp_lt_i32_e32 vcc, v168, v169
	s_lshl_b32 s36, s4, 2
	s_ashr_i32 s37, s36, 31
	v_cndmask_b32_e32 v168, v212, v168, vcc
	v_cmp_lt_i32_e32 vcc, v176, v169
	v_lshlrev_b32_e32 v184, 2, v168
	s_waitcnt vmcnt(0)
	v_pk_add_f32 v[128:129], v[128:129], v[188:189]
	v_pk_add_f32 v[126:127], v[126:127], v[186:187]
	v_cndmask_b32_e32 v169, v212, v176, vcc
	v_pk_add_f32 v[122:123], v[122:123], v[190:191]
	v_pk_add_f32 v[176:177], v[120:121], v[196:197]
	v_pk_add_f32 v[116:117], v[116:117], v[200:201]
	v_pk_add_f32 v[114:115], v[114:115], v[198:199]
	v_cvt_pk_bf16_f32 v120, v126, v127
	v_cvt_pk_bf16_f32 v121, v128, v129
	v_pk_add_f32 v[124:125], v[124:125], v[192:193]
	v_pk_add_f32 v[118:119], v[118:119], v[194:195]
	v_cvt_pk_bf16_f32 v122, v122, v123
	v_cvt_pk_bf16_f32 v126, v114, v115
	v_cvt_pk_bf16_f32 v127, v116, v117
	v_and_b32_e32 v115, 0xffff0000, v120
	v_and_b32_e32 v117, 0xffff0000, v121
	v_cvt_pk_bf16_f32 v123, v124, v125
	v_cvt_pk_bf16_f32 v124, v118, v119
	v_lshlrev_b32_e32 v114, 16, v120
	v_lshlrev_b32_e32 v116, 16, v121
	v_and_b32_e32 v119, 0xffff0000, v122
	v_mul_f32_e32 v115, v115, v115
	v_mul_f32_e32 v117, v117, v117
	v_lshlrev_b32_e32 v118, 16, v122
	v_and_b32_e32 v129, 0xffff0000, v123
	v_mul_f32_e32 v119, v119, v119
	v_fmac_f32_e32 v115, v114, v114
	v_fmac_f32_e32 v117, v116, v116
	v_cvt_pk_bf16_f32 v125, v176, v177
	v_lshlrev_b32_e32 v128, 16, v123
	v_and_b32_e32 v176, 0xffff0000, v124
	v_mul_f32_e32 v129, v129, v129
	v_fmac_f32_e32 v119, v118, v118
	v_add_f32_e32 v114, v115, v117
	v_lshlrev_b32_e32 v168, 16, v124
	v_and_b32_e32 v185, 0xffff0000, v125
	v_mul_f32_e32 v176, v176, v176
	v_fmac_f32_e32 v129, v128, v128
	v_add_f32_e32 v114, v114, v119
	v_lshlrev_b32_e32 v177, 16, v125
	v_and_b32_e32 v187, 0xffff0000, v126
	v_mul_f32_e32 v185, v185, v185
	v_fmac_f32_e32 v176, v168, v168
	v_add_f32_e32 v114, v129, v114
	v_lshlrev_b32_e32 v186, 16, v126
	v_and_b32_e32 v189, 0xffff0000, v127
	v_mul_f32_e32 v187, v187, v187
	v_fmac_f32_e32 v185, v177, v177
	v_add_f32_e32 v114, v176, v114
	v_lshlrev_b32_e32 v188, 16, v127
	v_mul_f32_e32 v189, v189, v189
	v_fmac_f32_e32 v187, v186, v186
	v_add_f32_e32 v114, v185, v114
	v_add_f32_e32 v114, v187, v114
	v_fmac_f32_e32 v189, v188, v188
	v_add_f32_e32 v114, v189, v114
	ds_bpermute_b32 v115, v184, v114
	v_lshlrev_b32_e32 v118, 2, v169
	v_lshlrev_b64 v[116:117], 11, v[158:159]
	v_lshl_add_u64 v[116:117], s[96:97], 0, v[116:117]
	v_lshl_add_u64 v[116:117], v[156:157], 1, v[116:117]
	s_waitcnt lgkmcnt(0)
	v_add_f32_e32 v114, v114, v115
	ds_bpermute_b32 v115, v118, v114
	global_store_dwordx4 v[116:117], v[120:123], off
	global_store_dwordx4 v[116:117], v[124:127], off offset:256
	s_and_saveexec_b64 s[30:31], s[42:43]
	s_cbranch_execz .LBB0_162
	v_lshlrev_b64 v[116:117], 6, v[158:159]
	v_lshl_add_u64 v[116:117], s[58:59], 0, v[116:117]
	v_lshl_add_u64 v[116:117], s[36:37], 2, v[116:117]
	s_lshl_b32 s4, s67, 2
	v_lshl_add_u64 v[116:117], v[116:117], 0, s[4:5]
	s_waitcnt lgkmcnt(0)
	v_add_f32_e32 v114, v114, v115
	global_store_dword v[116:117], v114, off

.LBB0_176:
	s_waitcnt vmcnt(0)
	v_readlane_b32 s70, v253, 62
	v_readlane_b32 s68, v254, 48
	s_cmpk_gt_u32 s16, 0xff
	v_readlane_b32 s71, v253, 63
	v_readlane_b32 s69, v254, 49
	s_cbranch_scc1 .LBB0_178
	s_nop 0

.LBB0_280:
	s_andn2_b64 vcc, exec, s[26:27]
	s_cbranch_vccnz .LBB0_305
	v_readlane_b32 s0, v252, 0
	v_mov_b32_e32 v13, v167
	v_readlane_b32 s1, v252, 1
	s_andn2_b64 vcc, exec, s[0:1]
	v_readfirstlane_b32 s0, v13
	s_cbranch_vccnz .LBB0_305
	v_lshlrev_b32_e32 v0, 4, v13
	v_add_u32_e32 v2, 0x2000, v0
	s_waitcnt lgkmcnt(0)
	v_ashrrev_i32_e32 v3, 31, v2
	v_lshrrev_b32_e32 v3, 22, v3
	v_add_u32_e32 v3, v2, v3
	v_ashrrev_i32_e32 v10, 10, v3
	v_mul_i32_i24_e32 v3, 0x400, v10
	v_sub_u32_e32 v2, v2, v3
	v_lshrrev_b32_e32 v3, 4, v2
	v_bitop3_b32 v2, v3, v2, 32 bitop3:0x6c
	v_ashrrev_i32_e32 v3, 31, v2
	v_lshrrev_b32_e32 v3, 26, v3
	v_add_u32_e32 v3, v2, v3
	v_lshlrev_b32_e32 v4, 3, v10
	v_ashrrev_i32_e32 v11, 6, v3
	v_and_b32_e32 v4, -16, v4
	v_add_u32_e32 v4, v11, v4
	v_and_b32_e32 v5, 3, v11
	s_mov_b32 s1, 0x1fffe0
	v_lshrrev_b32_e32 v6, 2, v4
	v_lshlrev_b32_e32 v7, 1, v4
	v_and_b32_e32 v3, 0xc0, v3
	v_and_or_b32 v5, v4, s1, v5
	v_and_b32_e32 v6, 4, v6
	v_and_b32_e32 v7, 24, v7
	v_sub_u32_e32 v2, v2, v3
	v_or3_b32 v5, v5, v6, v7
	v_lshlrev_b32_e32 v6, 5, v10
	v_ashrrev_i16_sdwa v2, v211, sext(v2) dst_sel:DWORD dst_unused:UNUSED_PAD src0_sel:DWORD src1_sel:BYTE_0
	v_and_b32_e32 v6, 32, v6
	v_bfe_i32 v12, v2, 0, 16
	v_add_lshl_u32 v2, v6, v12, 1
	v_lshl_add_u32 v178, v5, 11, v2
	v_lshl_add_u32 v180, v4, 11, v2
	v_bfe_i32 v2, v13, 27, 1
	v_lshrrev_b32_e32 v2, 22, v2
	v_add_u32_e32 v2, v0, v2
	v_and_b32_e32 v2, 0xfffffc00, v2
	v_sub_u32_e32 v0, v0, v2
	v_lshrrev_b32_e32 v2, 4, v0
	v_ashrrev_i32_e32 v3, 31, v13
	v_bitop3_b32 v0, v2, v0, 32 bitop3:0x6c
	v_lshrrev_b32_e32 v3, 26, v3
	v_ashrrev_i32_e32 v2, 31, v0
	v_add_u32_e32 v3, v13, v3
	v_lshrrev_b32_e32 v2, 26, v2
	v_ashrrev_i32_e32 v15, 6, v3
	v_add_u32_e32 v2, v0, v2
	v_lshlrev_b32_e32 v3, 3, v15
	v_ashrrev_i32_e32 v14, 6, v2
	v_and_b32_e32 v3, -16, v3
	v_add_u32_e32 v3, v14, v3
	v_and_b32_e32 v4, 3, v14
	v_lshrrev_b32_e32 v5, 2, v3
	v_lshlrev_b32_e32 v6, 1, v3
	v_and_b32_e32 v2, 0xc0, v2
	s_ashr_i32 s7, s0, 6
	v_and_or_b32 v4, v3, s1, v4
	v_and_b32_e32 v5, 4, v5
	v_and_b32_e32 v6, 24, v6
	v_sub_u32_e32 v0, v0, v2
	s_ashr_i32 s6, s0, 8
	s_lshl_b32 s4, s7, 10
	v_or3_b32 v4, v4, v5, v6
	v_lshlrev_b32_e32 v5, 5, v15
	v_ashrrev_i16_sdwa v0, v211, sext(v0) dst_sel:DWORD dst_unused:UNUSED_PAD src0_sel:DWORD src1_sel:BYTE_0
	v_readlane_b32 s16, v253, 15
	v_and_b32_e32 v5, 32, v5
	v_bfe_i32 v16, v0, 0, 16
	v_readlane_b32 s17, v253, 16
	s_add_u32 s30, s10, s16
	v_add_lshl_u32 v2, v5, v16, 1
	s_addc_u32 s31, s11, s17
	s_add_i32 s16, s4, 0
	v_lshl_add_u32 v0, v4, 11, v2
	s_add_i32 m0, s16, 0x10000
	v_readlane_b32 s20, v253, 19
	global_load_lds_dwordx4 v0, s[30:31]
	s_add_i32 m0, s16, 0x12000
	v_readlane_b32 s21, v253, 20
	s_add_u32 s42, s96, s20
	v_lshl_add_u32 v182, v3, 11, v2
	global_load_lds_dwordx4 v178, s[30:31]
	s_addc_u32 s43, s97, s21
	s_mov_b32 m0, s16
	s_add_i32 s17, s16, 0x2000
	global_load_lds_dwordx4 v182, s[42:43]
	s_mov_b32 m0, s17
	s_add_u32 s20, s30, 0x40000
	global_load_lds_dwordx4 v180, s[42:43]
	s_addc_u32 s21, s31, 0
	s_add_i32 m0, s16, 0x14000
	v_mov_b32_e32 v179, v1
	global_load_lds_dwordx4 v0, s[20:21]
	s_add_i32 m0, s16, 0x16000
	s_add_u32 s22, s42, 0x40000
	global_load_lds_dwordx4 v178, s[20:21]
	s_addc_u32 s23, s43, 0
	s_add_i32 s20, s16, 0x4000
	s_mov_b32 m0, s20
	s_add_i32 s21, s16, 0x6000
	global_load_lds_dwordx4 v182, s[22:23]
	s_mov_b32 m0, s21
	v_mov_b32_e32 v183, v1
	global_load_lds_dwordx4 v180, s[22:23]
	v_mov_b32_e32 v181, v1
	v_lshl_add_u64 v[8:9], s[30:31], 0, v[0:1]
	v_lshl_add_u64 v[6:7], s[30:31], 0, v[178:179]
	v_lshl_add_u64 v[4:5], s[42:43], 0, v[182:183]
	s_cmp_lg_u32 s6, 1
	v_lshl_add_u64 v[2:3], s[42:43], 0, v[180:181]
	s_cbranch_scc1 .LBB0_284
	s_nop 0

.LBB0_288:
	s_ashr_i32 s27, s26, 31
	s_lshl_b64 s[22:23], s[26:27], 19
	v_cmp_lt_i64_e32 vcc, s[28:29], v[170:171]
	s_add_u32 s28, s96, s22
	s_addc_u32 s29, s97, s23
	s_and_b64 s[22:23], vcc, exec
	s_cselect_b32 s27, s29, s43
	s_cselect_b32 s50, s28, s42
	s_ashr_i32 s7, s6, 31
	s_lshl_b64 s[22:23], s[6:7], 19
	s_add_u32 s36, s10, s22
	s_addc_u32 s37, s11, s23
	s_and_b64 s[22:23], vcc, exec
	s_cselect_b32 s7, s37, s31
	s_cselect_b32 s51, s36, s30
	s_add_u32 s42, s42, 0x40080
	s_addc_u32 s43, s43, 0
	s_add_u32 s52, s30, 0x100
	v_mov_b32_e32 v2, 0
	s_addc_u32 s53, s31, 0
	s_mov_b32 s54, -2
	v_mov_b32_e32 v3, v2
	v_mov_b32_e32 v4, v2
	v_mov_b32_e32 v5, v2
	v_mov_b32_e32 v6, v2
	v_mov_b32_e32 v7, v2
	v_mov_b32_e32 v8, v2
	v_mov_b32_e32 v9, v2
	v_mov_b32_e32 v10, v2
	v_mov_b32_e32 v11, v2
	v_mov_b32_e32 v12, v2
	v_mov_b32_e32 v13, v2
	v_mov_b32_e32 v18, v2
	v_mov_b32_e32 v19, v2
	v_mov_b32_e32 v20, v2
	v_mov_b32_e32 v21, v2
	v_mov_b32_e32 v26, v2
	v_mov_b32_e32 v27, v2
	v_mov_b32_e32 v28, v2
	v_mov_b32_e32 v29, v2
	v_mov_b32_e32 v34, v2
	v_mov_b32_e32 v35, v2
	v_mov_b32_e32 v36, v2
	v_mov_b32_e32 v37, v2
	v_mov_b32_e32 v42, v2
	v_mov_b32_e32 v43, v2
	v_mov_b32_e32 v44, v2
	v_mov_b32_e32 v45, v2
	v_mov_b32_e32 v50, v2
	v_mov_b32_e32 v51, v2
	v_mov_b32_e32 v52, v2
	v_mov_b32_e32 v53, v2
	v_mov_b32_e32 v14, v2
	v_mov_b32_e32 v15, v2
	v_mov_b32_e32 v16, v2
	v_mov_b32_e32 v17, v2
	v_mov_b32_e32 v22, v2
	v_mov_b32_e32 v23, v2
	v_mov_b32_e32 v24, v2
	v_mov_b32_e32 v25, v2
	v_mov_b32_e32 v30, v2
	v_mov_b32_e32 v31, v2
	v_mov_b32_e32 v32, v2
	v_mov_b32_e32 v33, v2
	v_mov_b32_e32 v38, v2
	v_mov_b32_e32 v39, v2
	v_mov_b32_e32 v40, v2
	v_mov_b32_e32 v41, v2
	v_mov_b32_e32 v46, v2
	v_mov_b32_e32 v47, v2
	v_mov_b32_e32 v48, v2
	v_mov_b32_e32 v49, v2
	v_mov_b32_e32 v54, v2
	v_mov_b32_e32 v55, v2
	v_mov_b32_e32 v56, v2
	v_mov_b32_e32 v57, v2
	v_mov_b32_e32 v58, v2
	v_mov_b32_e32 v59, v2
	v_mov_b32_e32 v60, v2
	v_mov_b32_e32 v61, v2
	v_mov_b32_e32 v62, v2
	v_mov_b32_e32 v63, v2
	v_mov_b32_e32 v64, v2
	v_mov_b32_e32 v65, v2
	v_mov_b32_e32 v66, v2
	v_mov_b32_e32 v67, v2
	v_mov_b32_e32 v68, v2
	v_mov_b32_e32 v69, v2
	v_mov_b32_e32 v70, v2
	v_mov_b32_e32 v71, v2
	v_mov_b32_e32 v72, v2
	v_mov_b32_e32 v73, v2
	v_mov_b32_e32 v74, v2
	v_mov_b32_e32 v75, v2
	v_mov_b32_e32 v76, v2
	v_mov_b32_e32 v77, v2
	v_mov_b32_e32 v82, v2
	v_mov_b32_e32 v83, v2
	v_mov_b32_e32 v84, v2
	v_mov_b32_e32 v85, v2
	v_mov_b32_e32 v90, v2
	v_mov_b32_e32 v91, v2
	v_mov_b32_e32 v92, v2
	v_mov_b32_e32 v93, v2
	v_mov_b32_e32 v98, v2
	v_mov_b32_e32 v99, v2
	v_mov_b32_e32 v100, v2
	v_mov_b32_e32 v101, v2
	v_mov_b32_e32 v106, v2
	v_mov_b32_e32 v107, v2
	v_mov_b32_e32 v108, v2
	v_mov_b32_e32 v109, v2
	v_mov_b32_e32 v114, v2
	v_mov_b32_e32 v115, v2
	v_mov_b32_e32 v116, v2
	v_mov_b32_e32 v117, v2
	v_mov_b32_e32 v78, v2
	v_mov_b32_e32 v79, v2
	v_mov_b32_e32 v80, v2
	v_mov_b32_e32 v81, v2
	v_mov_b32_e32 v86, v2
	v_mov_b32_e32 v87, v2
	v_mov_b32_e32 v88, v2
	v_mov_b32_e32 v89, v2
	v_mov_b32_e32 v94, v2
	v_mov_b32_e32 v95, v2
	v_mov_b32_e32 v96, v2
	v_mov_b32_e32 v97, v2
	v_mov_b32_e32 v102, v2
	v_mov_b32_e32 v103, v2
	v_mov_b32_e32 v104, v2
	v_mov_b32_e32 v105, v2
	v_mov_b32_e32 v110, v2
	v_mov_b32_e32 v111, v2
	v_mov_b32_e32 v112, v2
	v_mov_b32_e32 v113, v2
	v_mov_b32_e32 v118, v2
	v_mov_b32_e32 v119, v2
	v_mov_b32_e32 v120, v2
	v_mov_b32_e32 v121, v2
	v_mov_b32_e32 v122, v2
	v_mov_b32_e32 v123, v2
	v_mov_b32_e32 v124, v2
	v_mov_b32_e32 v125, v2
	v_mov_b32_e32 v126, v2
	v_mov_b32_e32 v127, v2
	v_mov_b32_e32 v128, v2
	v_mov_b32_e32 v129, v2
	s_cmpk_gt_u32 s0, 0xff
	s_cbranch_scc0 .Lrs_proj0_pre
	s_barrier
.Lrs_proj0_pre:
.LBB0_289:
	s_add_u32 s1, s42, 0xfffc0080
	s_addc_u32 s22, s43, -1
	s_add_i32 s23, 0, 0x10000
	v_add_u32_e32 v142, s23, v217
	ds_read_b128 v[130:133], v142
	ds_read_b128 v[134:137], v142 offset:1024
	ds_read_b128 v[138:141], v142 offset:2048
	ds_read_b128 v[142:145], v142 offset:3072
	s_cmp_eq_u32 s54, 12
	s_cselect_b32 s45, s27, s22
	s_cselect_b32 s44, s50, s1
	s_cselect_b32 s31, s7, s53
	s_cselect_b32 s30, s51, s52
	v_lshl_add_u64 v[176:177], s[42:43], 0, v[190:191]
	s_add_i32 m0, s16, 0xc000
	ds_read_b128 v[146:149], v219
	ds_read_b128 v[150:153], v219 offset:1024
	ds_read_b128 v[154:157], v219 offset:2048
	ds_read_b128 v[158:161], v219 offset:3072
	ds_read_b128 v[194:197], v219 offset:4096
	ds_read_b128 v[198:201], v219 offset:5120
	ds_read_b128 v[202:205], v219 offset:6144
	ds_read_b128 v[206:209], v219 offset:7168
	global_load_lds_dwordx4 v[176:177], off
	v_lshl_add_u64 v[176:177], s[42:43], 0, v[192:193]
	s_add_i32 m0, s16, 0xe000
	s_nop 0
	global_load_lds_dwordx4 v[176:177], off
	s_add_i32 s1, 0, 0x14000
	v_add_u32_e32 v168, s1, v217
	ds_read_b128 v[230:233], v168
	ds_read_b128 v[234:237], v168 offset:1024
	ds_read_b128 v[238:241], v168 offset:2048
	ds_read_b128 v[242:245], v168 offset:3072
	s_waitcnt vmcnt(8)
	s_waitcnt lgkmcnt(0)
	s_barrier
	s_setprio 1
	v_mfma_f32_16x16x32_bf16 v[126:129], v[130:133], v[146:149], v[126:129]
	v_mfma_f32_16x16x32_bf16 v[122:125], v[138:141], v[146:149], v[122:125]
	v_mfma_f32_16x16x32_bf16 v[118:121], v[130:133], v[154:157], v[118:121]
	v_mfma_f32_16x16x32_bf16 v[110:113], v[138:141], v[154:157], v[110:113]
	v_mfma_f32_16x16x32_bf16 v[102:105], v[130:133], v[194:197], v[102:105]
	v_mfma_f32_16x16x32_bf16 v[94:97], v[138:141], v[194:197], v[94:97]
	v_mfma_f32_16x16x32_bf16 v[86:89], v[130:133], v[202:205], v[86:89]
	v_mfma_f32_16x16x32_bf16 v[78:81], v[138:141], v[202:205], v[78:81]
	v_mfma_f32_16x16x32_bf16 v[126:129], v[134:137], v[150:153], v[126:129]
	v_mfma_f32_16x16x32_bf16 v[122:125], v[142:145], v[150:153], v[122:125]
	v_mfma_f32_16x16x32_bf16 v[118:121], v[134:137], v[158:161], v[118:121]
	v_mfma_f32_16x16x32_bf16 v[110:113], v[142:145], v[158:161], v[110:113]
	v_mfma_f32_16x16x32_bf16 v[102:105], v[134:137], v[198:201], v[102:105]
	v_mfma_f32_16x16x32_bf16 v[94:97], v[142:145], v[198:201], v[94:97]
	v_mfma_f32_16x16x32_bf16 v[86:89], v[134:137], v[206:209], v[86:89]
	v_mfma_f32_16x16x32_bf16 v[78:81], v[142:145], v[206:209], v[78:81]
	v_mfma_f32_16x16x32_bf16 v[114:117], v[230:233], v[146:149], v[114:117]
	v_mfma_f32_16x16x32_bf16 v[106:109], v[238:241], v[146:149], v[106:109]
	v_mfma_f32_16x16x32_bf16 v[98:101], v[230:233], v[154:157], v[98:101]
	v_mfma_f32_16x16x32_bf16 v[90:93], v[238:241], v[154:157], v[90:93]
	v_mfma_f32_16x16x32_bf16 v[82:85], v[230:233], v[194:197], v[82:85]
	v_mfma_f32_16x16x32_bf16 v[74:77], v[238:241], v[194:197], v[74:77]
	v_mfma_f32_16x16x32_bf16 v[70:73], v[230:233], v[202:205], v[70:73]
	v_mfma_f32_16x16x32_bf16 v[66:69], v[238:241], v[202:205], v[66:69]
	v_mfma_f32_16x16x32_bf16 v[114:117], v[234:237], v[150:153], v[114:117]
	v_mfma_f32_16x16x32_bf16 v[106:109], v[242:245], v[150:153], v[106:109]
	v_mfma_f32_16x16x32_bf16 v[98:101], v[234:237], v[158:161], v[98:101]
	v_mfma_f32_16x16x32_bf16 v[90:93], v[242:245], v[158:161], v[90:93]
	v_mfma_f32_16x16x32_bf16 v[82:85], v[234:237], v[198:201], v[82:85]
	v_mfma_f32_16x16x32_bf16 v[74:77], v[242:245], v[198:201], v[74:77]
	v_mfma_f32_16x16x32_bf16 v[70:73], v[234:237], v[206:209], v[70:73]
	v_mfma_f32_16x16x32_bf16 v[66:69], v[242:245], v[206:209], v[66:69]
	s_setprio 0
	s_barrier
	ds_read_b128 v[146:149], v219 offset:16384
	ds_read_b128 v[150:153], v219 offset:17408
	ds_read_b128 v[154:157], v219 offset:18432
	ds_read_b128 v[158:161], v219 offset:19456
	ds_read_b128 v[194:197], v219 offset:20480
	ds_read_b128 v[198:201], v219 offset:21504
	ds_read_b128 v[202:205], v219 offset:22528
	ds_read_b128 v[206:209], v219 offset:23552
	s_add_i32 s22, s23, s4
	v_lshl_add_u64 v[176:177], s[30:31], 0, v[0:1]
	s_mov_b32 m0, s22
	s_nop 0
	global_load_lds_dwordx4 v[176:177], off
	v_lshl_add_u64 v[220:221], s[30:31], 0, v[178:179]
	s_add_i32 m0, s22, 0x2000
	s_nop 0
	global_load_lds_dwordx4 v[220:221], off
	s_mov_b32 m0, s16
	v_lshl_add_u64 v[246:247], s[44:45], 0, v[182:183]
	global_load_lds_dwordx4 v[246:247], off
	v_lshl_add_u64 v[248:249], s[44:45], 0, v[180:181]
	s_mov_b32 m0, s17
	s_nop 0
	global_load_lds_dwordx4 v[248:249], off
	s_add_u32 s22, s30, 0x40000
	s_addc_u32 s23, s31, 0
	s_add_i32 s1, s1, s4
	s_mov_b32 m0, s1
	s_nop 0
	global_load_lds_dwordx4 v0, s[22:23]
	s_add_i32 m0, s1, 0x2000
	s_nop 0
	global_load_lds_dwordx4 v178, s[22:23]
	s_waitcnt vmcnt(8)
	s_waitcnt lgkmcnt(0)
	s_barrier
	s_setprio 1
	v_mfma_f32_16x16x32_bf16 v[62:65], v[130:133], v[146:149], v[62:65]
	v_mfma_f32_16x16x32_bf16 v[58:61], v[138:141], v[146:149], v[58:61]
	v_mfma_f32_16x16x32_bf16 v[54:57], v[130:133], v[154:157], v[54:57]
	v_mfma_f32_16x16x32_bf16 v[46:49], v[138:141], v[154:157], v[46:49]
	v_mfma_f32_16x16x32_bf16 v[38:41], v[130:133], v[194:197], v[38:41]
	v_mfma_f32_16x16x32_bf16 v[30:33], v[138:141], v[194:197], v[30:33]
	v_mfma_f32_16x16x32_bf16 v[22:25], v[130:133], v[202:205], v[22:25]
	v_mfma_f32_16x16x32_bf16 v[14:17], v[138:141], v[202:205], v[14:17]
	v_mfma_f32_16x16x32_bf16 v[62:65], v[134:137], v[150:153], v[62:65]
	v_mfma_f32_16x16x32_bf16 v[58:61], v[142:145], v[150:153], v[58:61]
	v_mfma_f32_16x16x32_bf16 v[54:57], v[134:137], v[158:161], v[54:57]
	v_mfma_f32_16x16x32_bf16 v[46:49], v[142:145], v[158:161], v[46:49]
	v_mfma_f32_16x16x32_bf16 v[38:41], v[134:137], v[198:201], v[38:41]
	v_mfma_f32_16x16x32_bf16 v[30:33], v[142:145], v[198:201], v[30:33]
	v_mfma_f32_16x16x32_bf16 v[22:25], v[134:137], v[206:209], v[22:25]
	v_mfma_f32_16x16x32_bf16 v[14:17], v[142:145], v[206:209], v[14:17]
	v_mfma_f32_16x16x32_bf16 v[50:53], v[230:233], v[146:149], v[50:53]
	v_mfma_f32_16x16x32_bf16 v[42:45], v[238:241], v[146:149], v[42:45]
	v_mfma_f32_16x16x32_bf16 v[34:37], v[230:233], v[154:157], v[34:37]
	v_mfma_f32_16x16x32_bf16 v[26:29], v[238:241], v[154:157], v[26:29]
	v_mfma_f32_16x16x32_bf16 v[18:21], v[230:233], v[194:197], v[18:21]
	v_mfma_f32_16x16x32_bf16 v[10:13], v[238:241], v[194:197], v[10:13]
	v_mfma_f32_16x16x32_bf16 v[6:9], v[230:233], v[202:205], v[6:9]
	v_mfma_f32_16x16x32_bf16 v[2:5], v[238:241], v[202:205], v[2:5]
	v_mfma_f32_16x16x32_bf16 v[50:53], v[234:237], v[150:153], v[50:53]
	v_mfma_f32_16x16x32_bf16 v[42:45], v[242:245], v[150:153], v[42:45]
	v_mfma_f32_16x16x32_bf16 v[34:37], v[234:237], v[158:161], v[34:37]
	v_mfma_f32_16x16x32_bf16 v[26:29], v[242:245], v[158:161], v[26:29]
	v_mfma_f32_16x16x32_bf16 v[18:21], v[234:237], v[198:201], v[18:21]
	v_mfma_f32_16x16x32_bf16 v[10:13], v[242:245], v[198:201], v[10:13]
	v_mfma_f32_16x16x32_bf16 v[6:9], v[234:237], v[206:209], v[6:9]
	v_mfma_f32_16x16x32_bf16 v[2:5], v[242:245], v[206:209], v[2:5]
	s_setprio 0
	s_barrier
	s_add_i32 s1, 0, 0x18000
	v_add_u32_e32 v142, s1, v217
	ds_read_b128 v[130:133], v142
	ds_read_b128 v[134:137], v142 offset:1024
	ds_read_b128 v[138:141], v142 offset:2048
	ds_read_b128 v[142:145], v142 offset:3072
	s_add_u32 s22, s44, 0x40000
	s_addc_u32 s23, s45, 0
	s_mov_b32 m0, s20
	v_lshl_add_u64 v[230:231], s[22:23], 0, v[182:183]
	ds_read_b128 v[146:149], v219 offset:32768
	ds_read_b128 v[150:153], v219 offset:33792
	ds_read_b128 v[154:157], v219 offset:34816
	ds_read_b128 v[158:161], v219 offset:35840
	ds_read_b128 v[194:197], v219 offset:36864
	ds_read_b128 v[198:201], v219 offset:37888
	ds_read_b128 v[202:205], v219 offset:38912
	ds_read_b128 v[206:209], v219 offset:39936
	global_load_lds_dwordx4 v[230:231], off
	v_lshl_add_u64 v[230:231], s[22:23], 0, v[180:181]
	s_mov_b32 m0, s21
	s_nop 0
	global_load_lds_dwordx4 v[230:231], off
	s_add_i32 s33, 0, 0x1c000
	v_add_u32_e32 v168, s33, v217
	ds_read_b128 v[230:233], v168
	ds_read_b128 v[234:237], v168 offset:1024
	ds_read_b128 v[238:241], v168 offset:2048
	ds_read_b128 v[242:245], v168 offset:3072
	s_waitcnt vmcnt(8)
	s_waitcnt lgkmcnt(0)
	s_barrier
	s_setprio 1
	v_mfma_f32_16x16x32_bf16 v[126:129], v[130:133], v[146:149], v[126:129]
	v_mfma_f32_16x16x32_bf16 v[122:125], v[138:141], v[146:149], v[122:125]
	v_mfma_f32_16x16x32_bf16 v[118:121], v[130:133], v[154:157], v[118:121]
	v_mfma_f32_16x16x32_bf16 v[110:113], v[138:141], v[154:157], v[110:113]
	v_mfma_f32_16x16x32_bf16 v[102:105], v[130:133], v[194:197], v[102:105]
	v_mfma_f32_16x16x32_bf16 v[94:97], v[138:141], v[194:197], v[94:97]
	v_mfma_f32_16x16x32_bf16 v[86:89], v[130:133], v[202:205], v[86:89]
	v_mfma_f32_16x16x32_bf16 v[78:81], v[138:141], v[202:205], v[78:81]
	v_mfma_f32_16x16x32_bf16 v[126:129], v[134:137], v[150:153], v[126:129]
	v_mfma_f32_16x16x32_bf16 v[122:125], v[142:145], v[150:153], v[122:125]
	v_mfma_f32_16x16x32_bf16 v[118:121], v[134:137], v[158:161], v[118:121]
	v_mfma_f32_16x16x32_bf16 v[110:113], v[142:145], v[158:161], v[110:113]
	v_mfma_f32_16x16x32_bf16 v[102:105], v[134:137], v[198:201], v[102:105]
	v_mfma_f32_16x16x32_bf16 v[94:97], v[142:145], v[198:201], v[94:97]
	v_mfma_f32_16x16x32_bf16 v[86:89], v[134:137], v[206:209], v[86:89]
	v_mfma_f32_16x16x32_bf16 v[78:81], v[142:145], v[206:209], v[78:81]
	v_mfma_f32_16x16x32_bf16 v[114:117], v[230:233], v[146:149], v[114:117]
	v_mfma_f32_16x16x32_bf16 v[106:109], v[238:241], v[146:149], v[106:109]
	v_mfma_f32_16x16x32_bf16 v[98:101], v[230:233], v[154:157], v[98:101]
	v_mfma_f32_16x16x32_bf16 v[90:93], v[238:241], v[154:157], v[90:93]
	v_mfma_f32_16x16x32_bf16 v[82:85], v[230:233], v[194:197], v[82:85]
	v_mfma_f32_16x16x32_bf16 v[74:77], v[238:241], v[194:197], v[74:77]
	v_mfma_f32_16x16x32_bf16 v[70:73], v[230:233], v[202:205], v[70:73]
	v_mfma_f32_16x16x32_bf16 v[66:69], v[238:241], v[202:205], v[66:69]
	v_mfma_f32_16x16x32_bf16 v[114:117], v[234:237], v[150:153], v[114:117]
	v_mfma_f32_16x16x32_bf16 v[106:109], v[242:245], v[150:153], v[106:109]
	v_mfma_f32_16x16x32_bf16 v[98:101], v[234:237], v[158:161], v[98:101]
	v_mfma_f32_16x16x32_bf16 v[90:93], v[242:245], v[158:161], v[90:93]
	v_mfma_f32_16x16x32_bf16 v[82:85], v[234:237], v[198:201], v[82:85]
	v_mfma_f32_16x16x32_bf16 v[74:77], v[242:245], v[198:201], v[74:77]
	v_mfma_f32_16x16x32_bf16 v[70:73], v[234:237], v[206:209], v[70:73]
	v_mfma_f32_16x16x32_bf16 v[66:69], v[242:245], v[206:209], v[66:69]
	s_setprio 0
	s_barrier
	ds_read_b128 v[146:149], v219 offset:49152
	ds_read_b128 v[150:153], v219 offset:50176
	ds_read_b128 v[154:157], v219 offset:51200
	ds_read_b128 v[158:161], v219 offset:52224
	ds_read_b128 v[194:197], v219 offset:53248
	ds_read_b128 v[198:201], v219 offset:54272
	ds_read_b128 v[202:205], v219 offset:55296
	ds_read_b128 v[206:209], v219 offset:56320
	s_add_i32 s1, s1, s4
	v_lshl_add_u64 v[176:177], v[176:177], 0, s[12:13]
	s_mov_b32 m0, s1
	s_nop 0
	global_load_lds_dwordx4 v[176:177], off
	v_lshl_add_u64 v[176:177], v[220:221], 0, s[12:13]
	s_add_i32 m0, s1, 0x2000
	s_nop 0
	global_load_lds_dwordx4 v[176:177], off
	s_mov_b32 m0, s34
	v_lshl_add_u64 v[176:177], v[246:247], 0, s[12:13]
	global_load_lds_dwordx4 v[176:177], off
	v_lshl_add_u64 v[176:177], v[248:249], 0, s[12:13]
	s_mov_b32 m0, s46
	s_nop 0
	global_load_lds_dwordx4 v[176:177], off
	s_add_u32 s22, s30, 0x40080
	s_addc_u32 s23, s31, 0
	s_add_i32 s1, s33, s4
	s_mov_b32 m0, s1
	s_nop 0
	global_load_lds_dwordx4 v0, s[22:23]
	s_add_i32 m0, s1, 0x2000
	s_nop 0
	global_load_lds_dwordx4 v178, s[22:23]
	s_waitcnt vmcnt(8)
	s_waitcnt lgkmcnt(0)
	s_barrier
	s_setprio 1
	v_mfma_f32_16x16x32_bf16 v[62:65], v[130:133], v[146:149], v[62:65]
	v_mfma_f32_16x16x32_bf16 v[58:61], v[138:141], v[146:149], v[58:61]
	v_mfma_f32_16x16x32_bf16 v[54:57], v[130:133], v[154:157], v[54:57]
	v_mfma_f32_16x16x32_bf16 v[46:49], v[138:141], v[154:157], v[46:49]
	v_mfma_f32_16x16x32_bf16 v[38:41], v[130:133], v[194:197], v[38:41]
	v_mfma_f32_16x16x32_bf16 v[30:33], v[138:141], v[194:197], v[30:33]
	v_mfma_f32_16x16x32_bf16 v[22:25], v[130:133], v[202:205], v[22:25]
	v_mfma_f32_16x16x32_bf16 v[14:17], v[138:141], v[202:205], v[14:17]
	v_mfma_f32_16x16x32_bf16 v[62:65], v[134:137], v[150:153], v[62:65]
	v_mfma_f32_16x16x32_bf16 v[58:61], v[142:145], v[150:153], v[58:61]
	v_mfma_f32_16x16x32_bf16 v[54:57], v[134:137], v[158:161], v[54:57]
	v_mfma_f32_16x16x32_bf16 v[46:49], v[142:145], v[158:161], v[46:49]
	v_mfma_f32_16x16x32_bf16 v[38:41], v[134:137], v[198:201], v[38:41]
	v_mfma_f32_16x16x32_bf16 v[30:33], v[142:145], v[198:201], v[30:33]
	v_mfma_f32_16x16x32_bf16 v[22:25], v[134:137], v[206:209], v[22:25]
	v_mfma_f32_16x16x32_bf16 v[14:17], v[142:145], v[206:209], v[14:17]
	v_mfma_f32_16x16x32_bf16 v[50:53], v[230:233], v[146:149], v[50:53]
	v_mfma_f32_16x16x32_bf16 v[42:45], v[238:241], v[146:149], v[42:45]
	v_mfma_f32_16x16x32_bf16 v[34:37], v[230:233], v[154:157], v[34:37]
	v_mfma_f32_16x16x32_bf16 v[26:29], v[238:241], v[154:157], v[26:29]
	v_mfma_f32_16x16x32_bf16 v[18:21], v[230:233], v[194:197], v[18:21]
	v_mfma_f32_16x16x32_bf16 v[10:13], v[238:241], v[194:197], v[10:13]
	v_mfma_f32_16x16x32_bf16 v[6:9], v[230:233], v[202:205], v[6:9]
	v_mfma_f32_16x16x32_bf16 v[2:5], v[238:241], v[202:205], v[2:5]
	v_mfma_f32_16x16x32_bf16 v[50:53], v[234:237], v[150:153], v[50:53]
	v_mfma_f32_16x16x32_bf16 v[42:45], v[242:245], v[150:153], v[42:45]
	v_mfma_f32_16x16x32_bf16 v[34:37], v[234:237], v[158:161], v[34:37]
	v_mfma_f32_16x16x32_bf16 v[26:29], v[242:245], v[158:161], v[26:29]
	v_mfma_f32_16x16x32_bf16 v[18:21], v[234:237], v[198:201], v[18:21]
	v_mfma_f32_16x16x32_bf16 v[10:13], v[242:245], v[198:201], v[10:13]
	v_mfma_f32_16x16x32_bf16 v[6:9], v[234:237], v[206:209], v[6:9]
	v_mfma_f32_16x16x32_bf16 v[2:5], v[242:245], v[206:209], v[2:5]
	s_setprio 0
	s_add_i32 s54, s54, 2
	s_add_u32 s42, s42, 0x100
	s_addc_u32 s43, s43, 0
	s_add_u32 s52, s52, 0x100
	s_addc_u32 s53, s53, 0
	s_cmp_gt_u32 s54, 13
	s_barrier
	s_cbranch_scc0 .LBB0_289
	s_cmpk_gt_u32 s0, 0xff
	s_cbranch_scc1 .Lrs_proj0_post
	s_barrier
.Lrs_proj0_post:
	v_lshl_add_u32 v208, s49, 8, v216
	v_ashrrev_i32_e32 v209, 31, v208
	v_lshlrev_b64 v[130:131], 6, v[208:209]
	v_or_b32_e32 v206, 16, v208
	v_lshl_add_u64 v[130:131], v[186:187], 0, v[130:131]
	v_ashrrev_i32_e32 v207, 31, v206
	global_load_dwordx4 v[154:157], v[130:131], off
	v_lshlrev_b64 v[130:131], 6, v[206:207]
	v_lshl_add_u64 v[130:131], v[186:187], 0, v[130:131]
	global_load_dwordx4 v[158:161], v[130:131], off
	v_or_b32_e32 v204, 32, v208
	v_ashrrev_i32_e32 v205, 31, v204
	v_lshlrev_b64 v[130:131], 6, v[204:205]
	v_or_b32_e32 v202, 48, v208
	v_lshl_add_u64 v[130:131], v[186:187], 0, v[130:131]
	v_ashrrev_i32_e32 v203, 31, v202
	global_load_dwordx4 v[150:153], v[130:131], off
	v_lshlrev_b64 v[130:131], 6, v[202:203]
	v_lshl_add_u64 v[130:131], v[186:187], 0, v[130:131]
	global_load_dwordx4 v[146:149], v[130:131], off
	v_add_u32_e32 v200, 0x80, v208
	v_ashrrev_i32_e32 v201, 31, v200
	v_lshlrev_b64 v[130:131], 6, v[200:201]
	v_add_u32_e32 v198, 0x90, v208
	v_lshl_add_u64 v[130:131], v[186:187], 0, v[130:131]
	v_ashrrev_i32_e32 v199, 31, v198
	global_load_dwordx4 v[142:145], v[130:131], off
	v_lshlrev_b64 v[130:131], 6, v[198:199]
	v_add_u32_e32 v196, 0xa0, v208
	v_lshl_add_u64 v[130:131], v[186:187], 0, v[130:131]
	v_ashrrev_i32_e32 v197, 31, v196
	global_load_dwordx4 v[138:141], v[130:131], off
	v_lshlrev_b64 v[130:131], 6, v[196:197]
	v_add_u32_e32 v194, 0xb0, v208
	v_lshl_add_u64 v[130:131], v[186:187], 0, v[130:131]
	v_ashrrev_i32_e32 v195, 31, v194
	global_load_dwordx4 v[134:137], v[130:131], off
	v_lshlrev_b64 v[130:131], 6, v[194:195]
	v_lshl_add_u64 v[130:131], v[186:187], 0, v[130:131]
	global_load_dwordx4 v[130:133], v[130:131], off
	v_and_b32_e32 v169, 64, v212
	v_xor_b32_e32 v168, 16, v212
	v_add_u32_e32 v169, 64, v169
	v_cmp_lt_i32_e32 vcc, v168, v169
	s_mov_b32 s22, 0x358637bd
	s_cmp_gt_i32 s48, 11
	v_cndmask_b32_e32 v168, v212, v168, vcc
	v_lshlrev_b32_e32 v221, 2, v168
	v_xor_b32_e32 v168, 32, v212
	v_cmp_lt_i32_e32 vcc, v168, v169
	s_cselect_b64 s[30:31], -1, 0
	v_readlane_b32 s50, v254, 42
	v_cndmask_b32_e32 v168, v212, v168, vcc
	v_lshlrev_b32_e32 v220, 2, v168
	s_mov_b64 s[44:45], -1
	s_movk_i32 s1, 0x1800
	s_movk_i32 s33, 0x7fff
	v_readlane_b32 s51, v254, 43
	s_waitcnt vmcnt(0)
	v_mov_b32_e32 v176, v155
	v_mov_b32_e32 v177, v156
	v_mov_b32_e32 v155, v157
	v_mov_b32_e32 v156, v159
	v_mov_b32_e32 v157, v160
	v_mov_b32_e32 v159, v161
	v_pk_add_f32 v[154:155], v[176:177], v[154:155]
	v_pk_add_f32 v[156:157], v[156:157], v[158:159]
	v_mov_b32_e32 v159, v154
	v_mov_b32_e32 v158, v156
	v_mov_b32_e32 v154, v157
	v_pk_add_f32 v[154:155], v[158:159], v[154:155]
	ds_bpermute_b32 v157, v221, v155
	ds_bpermute_b32 v156, v221, v154
	v_mov_b32_e32 v160, v151
	v_mov_b32_e32 v161, v152
	v_mov_b32_e32 v151, v153
	v_mov_b32_e32 v152, v147
	v_mov_b32_e32 v153, v148
	v_mov_b32_e32 v147, v149
	v_pk_add_f32 v[150:151], v[160:161], v[150:151]
	v_pk_add_f32 v[146:147], v[152:153], v[146:147]
	s_waitcnt lgkmcnt(0)
	v_pk_add_f32 v[154:155], v[154:155], v[156:157]
	v_mov_b32_e32 v148, v146
	v_mov_b32_e32 v149, v150
	v_mov_b32_e32 v150, v147
	ds_bpermute_b32 v157, v220, v155
	ds_bpermute_b32 v156, v220, v154
	v_pk_add_f32 v[146:147], v[148:149], v[150:151]
	ds_bpermute_b32 v149, v221, v147
	ds_bpermute_b32 v148, v221, v146
	v_mov_b64_e32 v[158:159], s[22:23]
	s_waitcnt lgkmcnt(2)
	v_pk_add_f32 v[154:155], v[154:155], v[156:157]
	s_mov_b32 s22, 0x3a800000
	v_pk_fma_f32 v[154:155], v[154:155], s[22:23], v[158:159] op_sel_hi:[1,0,0]
	s_waitcnt lgkmcnt(0)
	v_pk_add_f32 v[146:147], v[146:147], v[148:149]
	v_mul_f32_e32 v156, 0x4b800000, v155
	v_cmp_gt_f32_e64 s[42:43], s39, v155
	ds_bpermute_b32 v149, v220, v147
	ds_bpermute_b32 v148, v220, v146
	v_cndmask_b32_e64 v155, v155, v156, s[42:43]
	v_rsq_f32_e32 v155, v155
	v_mov_b32_e32 v150, v143
	v_mov_b32_e32 v151, v144
	v_mov_b32_e32 v143, v145
	v_mov_b32_e32 v144, v139
	v_mov_b32_e32 v145, v140
	v_mov_b32_e32 v139, v141
	s_waitcnt lgkmcnt(0)
	v_pk_add_f32 v[146:147], v[146:147], v[148:149]
	v_pk_add_f32 v[142:143], v[150:151], v[142:143]
	v_pk_add_f32 v[138:139], v[144:145], v[138:139]
	v_mul_f32_e32 v156, 0x45800000, v155
	v_pk_fma_f32 v[148:149], v[146:147], s[22:23], v[158:159] op_sel_hi:[1,0,0]
	v_mov_b32_e32 v140, v138
	v_mov_b32_e32 v141, v142
	v_mov_b32_e32 v142, v139
	v_cmp_gt_f32_e32 vcc, s39, v154
	v_cndmask_b32_e64 v156, v155, v156, s[42:43]
	v_mul_f32_e32 v155, 0x4b800000, v154
	v_mul_f32_e32 v146, 0x4b800000, v149
	v_cmp_gt_f32_e64 s[42:43], s39, v149
	v_pk_add_f32 v[138:139], v[140:141], v[142:143]
	v_mov_b32_e32 v142, v135
	v_mov_b32_e32 v143, v136
	v_mov_b32_e32 v135, v137
	v_mov_b32_e32 v136, v131
	v_mov_b32_e32 v137, v132
	v_mov_b32_e32 v131, v133
	v_cndmask_b32_e32 v154, v154, v155, vcc
	v_cndmask_b32_e64 v146, v149, v146, s[42:43]
	v_pk_add_f32 v[134:135], v[142:143], v[134:135]
	v_pk_add_f32 v[130:131], v[136:137], v[130:131]
	v_rsq_f32_e32 v154, v154
	v_rsq_f32_e32 v146, v146
	v_mov_b32_e32 v132, v130
	v_mov_b32_e32 v133, v134
	v_mov_b32_e32 v134, v131
	v_pk_add_f32 v[130:131], v[132:133], v[134:135]
	ds_bpermute_b32 v141, v221, v139
	ds_bpermute_b32 v140, v221, v138
	ds_bpermute_b32 v133, v221, v131
	ds_bpermute_b32 v132, v221, v130
	v_mul_f32_e32 v155, 0x45800000, v154
	v_mul_f32_e32 v147, 0x45800000, v146
	v_cndmask_b32_e32 v154, v154, v155, vcc
	v_cmp_gt_f32_e32 vcc, s39, v148
	v_cndmask_b32_e64 v146, v146, v147, s[42:43]
	v_mul_f32_e32 v147, 0x4b800000, v148
	v_cndmask_b32_e32 v147, v148, v147, vcc
	v_rsq_f32_e32 v147, v147
	s_waitcnt lgkmcnt(2)
	v_pk_add_f32 v[138:139], v[138:139], v[140:141]
	s_waitcnt lgkmcnt(0)
	v_pk_add_f32 v[132:133], v[130:131], v[132:133]
	ds_bpermute_b32 v141, v220, v139
	ds_bpermute_b32 v140, v220, v138
	ds_bpermute_b32 v135, v220, v133
	ds_bpermute_b32 v134, v220, v132
	v_mul_f32_e32 v148, 0x45800000, v147
	v_cndmask_b32_e64 v130, 0, 1, s[24:25]
	v_cndmask_b32_e32 v148, v147, v148, vcc
	s_and_b64 vcc, exec, s[30:31]
	v_cmp_ne_u32_e64 s[42:43], 1, v130
	s_cbranch_vccz .LBB0_294
	s_and_b64 vcc, exec, s[42:43]
	s_cbranch_vccnz .LBB0_293
	global_load_dwordx4 v[142:145], v[188:189], off
	v_lshlrev_b64 v[130:131], 7, v[208:209]
	v_lshl_add_u64 v[130:131], v[184:185], 0, v[130:131]
	s_waitcnt vmcnt(0)
	v_pk_fma_f32 v[144:145], v[128:129], v[156:157], v[144:145] op_sel_hi:[1,0,1]
	v_pk_fma_f32 v[142:143], v[126:127], v[156:157], v[142:143] op_sel_hi:[1,0,1]
	global_store_dwordx4 v[130:131], v[142:145], off
	global_load_dwordx4 v[142:145], v[188:189], off offset:16
	s_waitcnt vmcnt(0)
	v_pk_fma_f32 v[144:145], v[124:125], v[156:157], v[144:145] op_sel_hi:[1,0,1]
	v_pk_fma_f32 v[142:143], v[122:123], v[156:157], v[142:143] op_sel_hi:[1,0,1]
	global_store_dwordx4 v[130:131], v[142:145], off offset:16
	global_load_dwordx4 v[142:145], v[188:189], off
	v_lshlrev_b64 v[130:131], 7, v[206:207]
	v_lshl_add_u64 v[130:131], v[184:185], 0, v[130:131]
	s_waitcnt vmcnt(0)
	v_pk_fma_f32 v[144:145], v[120:121], v[154:155], v[144:145] op_sel_hi:[1,0,1]
	v_pk_fma_f32 v[142:143], v[118:119], v[154:155], v[142:143] op_sel_hi:[1,0,1]
	global_store_dwordx4 v[130:131], v[142:145], off
	global_load_dwordx4 v[142:145], v[188:189], off offset:16
	s_waitcnt vmcnt(0)
	v_pk_fma_f32 v[144:145], v[112:113], v[154:155], v[144:145] op_sel_hi:[1,0,1]
	v_pk_fma_f32 v[142:143], v[110:111], v[154:155], v[142:143] op_sel_hi:[1,0,1]
	global_store_dwordx4 v[130:131], v[142:145], off offset:16
	global_load_dwordx4 v[142:145], v[188:189], off
	v_lshlrev_b64 v[130:131], 7, v[204:205]
	v_lshl_add_u64 v[130:131], v[184:185], 0, v[130:131]
	s_waitcnt vmcnt(0)
	v_pk_fma_f32 v[144:145], v[104:105], v[146:147], v[144:145] op_sel_hi:[1,0,1]
	v_pk_fma_f32 v[142:143], v[102:103], v[146:147], v[142:143] op_sel_hi:[1,0,1]
	global_store_dwordx4 v[130:131], v[142:145], off
	global_load_dwordx4 v[142:145], v[188:189], off offset:16
	s_waitcnt vmcnt(0)
	v_pk_fma_f32 v[144:145], v[96:97], v[146:147], v[144:145] op_sel_hi:[1,0,1]
	v_pk_fma_f32 v[142:143], v[94:95], v[146:147], v[142:143] op_sel_hi:[1,0,1]
	global_store_dwordx4 v[130:131], v[142:145], off offset:16
	global_load_dwordx4 v[142:145], v[188:189], off
	v_lshlrev_b64 v[130:131], 7, v[202:203]
	v_lshl_add_u64 v[130:131], v[184:185], 0, v[130:131]
	s_waitcnt vmcnt(0)
	v_pk_fma_f32 v[144:145], v[88:89], v[148:149], v[144:145] op_sel_hi:[1,0,1]
	v_pk_fma_f32 v[142:143], v[86:87], v[148:149], v[142:143] op_sel_hi:[1,0,1]
	global_store_dwordx4 v[130:131], v[142:145], off
	global_load_dwordx4 v[142:145], v[188:189], off offset:16
	s_waitcnt vmcnt(0)
	v_pk_fma_f32 v[144:145], v[80:81], v[148:149], v[144:145] op_sel_hi:[1,0,1]
	v_pk_fma_f32 v[142:143], v[78:79], v[148:149], v[142:143] op_sel_hi:[1,0,1]
	global_store_dwordx4 v[130:131], v[142:145], off offset:16

.LBB0_353:
	s_andn2_b64 vcc, exec, s[6:7]
	s_cbranch_vccnz .LBB0_374
	v_mov_b32_e32 v16, v167
	s_waitcnt vmcnt(0) lgkmcnt(0)
	s_barrier
	s_andn2_b64 vcc, exec, s[76:77]
	v_readfirstlane_b32 s4, v16
	s_cbranch_vccnz .LBB0_374
	v_lshlrev_b32_e32 v0, 4, v16
	v_add_u32_e32 v2, 0x2000, v0
	v_ashrrev_i32_e32 v3, 31, v2
	v_lshrrev_b32_e32 v3, 22, v3
	v_add_u32_e32 v3, v2, v3
	v_ashrrev_i32_e32 v10, 10, v3
	v_mul_i32_i24_e32 v3, 0x400, v10
	v_sub_u32_e32 v2, v2, v3
	v_lshrrev_b32_e32 v3, 4, v2
	v_bitop3_b32 v2, v3, v2, 32 bitop3:0x6c
	v_ashrrev_i32_e32 v3, 31, v2
	v_lshrrev_b32_e32 v3, 26, v3
	s_cmp_eq_u32 s16, 0
	v_add_u32_e32 v3, v2, v3
	v_lshlrev_b32_e32 v4, 3, v10
	s_cselect_b64 s[6:7], -1, 0
	v_ashrrev_i32_e32 v11, 6, v3
	v_and_b32_e32 v4, -16, v4
	s_and_b64 s[0:1], s[6:7], exec
	v_add_u32_e32 v4, v11, v4
	v_and_b32_e32 v5, 3, v11
	s_mov_b32 s1, 0x1fffe0
	v_lshrrev_b32_e32 v6, 2, v4
	v_lshlrev_b32_e32 v7, 1, v4
	v_and_b32_e32 v3, 0xc0, v3
	v_and_or_b32 v5, v4, s1, v5
	v_and_b32_e32 v6, 4, v6
	v_and_b32_e32 v7, 24, v7
	v_sub_u32_e32 v2, v2, v3
	v_or3_b32 v5, v5, v6, v7
	v_lshlrev_b32_e32 v6, 5, v10
	v_ashrrev_i16_sdwa v2, v211, sext(v2) dst_sel:DWORD dst_unused:UNUSED_PAD src0_sel:DWORD src1_sel:BYTE_0
	v_and_b32_e32 v6, 32, v6
	v_bfe_i32 v12, v2, 0, 16
	v_add_lshl_u32 v2, v6, v12, 1
	v_lshl_add_u32 v138, v5, 11, v2
	v_lshl_add_u32 v140, v4, 11, v2
	v_bfe_i32 v2, v16, 27, 1
	v_lshrrev_b32_e32 v2, 22, v2
	v_add_u32_e32 v2, v0, v2
	v_and_b32_e32 v2, 0xfffffc00, v2
	v_sub_u32_e32 v0, v0, v2
	v_lshrrev_b32_e32 v2, 4, v0
	v_ashrrev_i32_e32 v3, 31, v16
	v_bitop3_b32 v0, v2, v0, 32 bitop3:0x6c
	v_lshrrev_b32_e32 v3, 26, v3
	v_ashrrev_i32_e32 v2, 31, v0
	v_add_u32_e32 v3, v16, v3
	v_lshrrev_b32_e32 v2, 26, v2
	v_ashrrev_i32_e32 v14, 6, v3
	v_add_u32_e32 v2, v0, v2
	v_lshlrev_b32_e32 v3, 3, v14
	v_ashrrev_i32_e32 v13, 6, v2
	v_and_b32_e32 v3, -16, v3
	s_cselect_b32 s0, 0, 0x2000000
	v_add_u32_e32 v3, v13, v3
	s_add_u32 s46, s96, s0
	v_and_b32_e32 v4, 3, v13
	v_lshrrev_b32_e32 v5, 2, v3
	v_lshlrev_b32_e32 v6, 1, v3
	v_and_b32_e32 v2, 0xc0, v2
	s_addc_u32 s47, s97, 0
	s_ashr_i32 s8, s4, 6
	v_and_or_b32 v4, v3, s1, v4
	v_and_b32_e32 v5, 4, v5
	v_and_b32_e32 v6, 24, v6
	v_sub_u32_e32 v0, v0, v2
	s_ashr_i32 s0, s4, 8
	s_lshl_b32 s48, s8, 10
	v_or3_b32 v4, v4, v5, v6
	v_lshlrev_b32_e32 v5, 5, v14
	v_ashrrev_i16_sdwa v0, v211, sext(v0) dst_sel:DWORD dst_unused:UNUSED_PAD src0_sel:DWORD src1_sel:BYTE_0
	v_readlane_b32 s16, v253, 24
	v_and_b32_e32 v5, 32, v5
	v_bfe_i32 v15, v0, 0, 16
	v_readlane_b32 s17, v253, 25
	s_add_u32 s30, s50, s16
	v_add_lshl_u32 v2, v5, v15, 1
	s_addc_u32 s31, s51, s17
	s_add_i32 s49, s48, 0
	v_lshl_add_u32 v0, v4, 11, v2
	s_add_i32 m0, s49, 0x10000
	v_readlane_b32 s16, v253, 33
	global_load_lds_dwordx4 v0, s[30:31]
	s_add_i32 m0, s49, 0x12000
	v_readlane_b32 s17, v253, 34
	s_add_u32 s28, s46, s16
	v_lshl_add_u32 v142, v3, 11, v2
	global_load_lds_dwordx4 v138, s[30:31]
	s_addc_u32 s29, s47, s17
	s_mov_b32 m0, s49
	s_add_i32 s50, s49, 0x2000
	global_load_lds_dwordx4 v142, s[28:29]
	s_mov_b32 m0, s50
	s_add_u32 s16, s30, 0x40000
	global_load_lds_dwordx4 v140, s[28:29]
	s_addc_u32 s17, s31, 0
	s_add_i32 m0, s49, 0x14000
	v_mov_b32_e32 v139, v1
	global_load_lds_dwordx4 v0, s[16:17]
	s_add_i32 m0, s49, 0x16000
	v_mov_b32_e32 v143, v1
	global_load_lds_dwordx4 v138, s[16:17]
	s_add_u32 s16, s28, 0x40000
	s_addc_u32 s17, s29, 0
	s_add_i32 s51, s49, 0x4000
	s_mov_b32 m0, s51
	s_add_i32 s52, s49, 0x6000
	global_load_lds_dwordx4 v142, s[16:17]
	s_mov_b32 m0, s52
	v_mov_b32_e32 v141, v1
	global_load_lds_dwordx4 v140, s[16:17]
	v_lshl_add_u64 v[8:9], s[30:31], 0, v[0:1]
	v_lshl_add_u64 v[6:7], s[30:31], 0, v[138:139]
	v_lshl_add_u64 v[4:5], s[28:29], 0, v[142:143]
	s_cmp_lg_u32 s0, 1
	v_lshl_add_u64 v[2:3], s[28:29], 0, v[140:141]
	s_cbranch_scc1 .LBB0_357
	s_nop 0

.LBB0_361:
	s_ashr_i32 s25, s24, 31
	s_lshl_b64 s[20:21], s[24:25], 19
	v_cmp_lt_i64_e32 vcc, s[26:27], v[174:175]
	s_add_u32 s26, s46, s20
	s_addc_u32 s27, s47, s21
	s_and_b64 s[20:21], vcc, exec
	s_cselect_b32 s17, s27, s29
	s_cselect_b32 s20, s26, s28
	s_ashr_i32 s9, s8, 31
	s_lshl_b64 s[22:23], s[8:9], 19
	v_readlane_b32 s36, v254, 42
	v_readlane_b32 s37, v254, 43
	s_add_u32 s36, s36, s22
	s_addc_u32 s37, s37, s23
	s_and_b64 s[22:23], vcc, exec
	s_cselect_b32 s9, s37, s31
	s_cselect_b32 s21, s36, s30
	s_add_u32 s28, s28, 0x40080
	s_addc_u32 s29, s29, 0
	s_add_u32 s25, s30, 0x100
	v_mov_b32_e32 v2, 0
	s_addc_u32 s34, s31, 0
	s_mov_b32 s44, -2
	v_mov_b32_e32 v3, v2
	v_mov_b32_e32 v4, v2
	v_mov_b32_e32 v5, v2
	v_mov_b32_e32 v6, v2
	v_mov_b32_e32 v7, v2
	v_mov_b32_e32 v8, v2
	v_mov_b32_e32 v9, v2
	v_mov_b32_e32 v18, v2
	v_mov_b32_e32 v19, v2
	v_mov_b32_e32 v20, v2
	v_mov_b32_e32 v21, v2
	v_mov_b32_e32 v22, v2
	v_mov_b32_e32 v23, v2
	v_mov_b32_e32 v24, v2
	v_mov_b32_e32 v25, v2
	v_mov_b32_e32 v34, v2
	v_mov_b32_e32 v35, v2
	v_mov_b32_e32 v36, v2
	v_mov_b32_e32 v37, v2
	v_mov_b32_e32 v38, v2
	v_mov_b32_e32 v39, v2
	v_mov_b32_e32 v40, v2
	v_mov_b32_e32 v41, v2
	v_mov_b32_e32 v50, v2
	v_mov_b32_e32 v51, v2
	v_mov_b32_e32 v52, v2
	v_mov_b32_e32 v53, v2
	v_mov_b32_e32 v54, v2
	v_mov_b32_e32 v55, v2
	v_mov_b32_e32 v56, v2
	v_mov_b32_e32 v57, v2
	v_mov_b32_e32 v10, v2
	v_mov_b32_e32 v11, v2
	v_mov_b32_e32 v12, v2
	v_mov_b32_e32 v13, v2
	v_mov_b32_e32 v14, v2
	v_mov_b32_e32 v15, v2
	v_mov_b32_e32 v16, v2
	v_mov_b32_e32 v17, v2
	v_mov_b32_e32 v26, v2
	v_mov_b32_e32 v27, v2
	v_mov_b32_e32 v28, v2
	v_mov_b32_e32 v29, v2
	v_mov_b32_e32 v30, v2
	v_mov_b32_e32 v31, v2
	v_mov_b32_e32 v32, v2
	v_mov_b32_e32 v33, v2
	v_mov_b32_e32 v42, v2
	v_mov_b32_e32 v43, v2
	v_mov_b32_e32 v44, v2
	v_mov_b32_e32 v45, v2
	v_mov_b32_e32 v46, v2
	v_mov_b32_e32 v47, v2
	v_mov_b32_e32 v48, v2
	v_mov_b32_e32 v49, v2
	v_mov_b32_e32 v58, v2
	v_mov_b32_e32 v59, v2
	v_mov_b32_e32 v60, v2
	v_mov_b32_e32 v61, v2
	v_mov_b32_e32 v62, v2
	v_mov_b32_e32 v63, v2
	v_mov_b32_e32 v64, v2
	v_mov_b32_e32 v65, v2
	v_mov_b32_e32 v66, v2
	v_mov_b32_e32 v67, v2
	v_mov_b32_e32 v68, v2
	v_mov_b32_e32 v69, v2
	v_mov_b32_e32 v70, v2
	v_mov_b32_e32 v71, v2
	v_mov_b32_e32 v72, v2
	v_mov_b32_e32 v73, v2
	v_mov_b32_e32 v82, v2
	v_mov_b32_e32 v83, v2
	v_mov_b32_e32 v84, v2
	v_mov_b32_e32 v85, v2
	v_mov_b32_e32 v86, v2
	v_mov_b32_e32 v87, v2
	v_mov_b32_e32 v88, v2
	v_mov_b32_e32 v89, v2
	v_mov_b32_e32 v98, v2
	v_mov_b32_e32 v99, v2
	v_mov_b32_e32 v100, v2
	v_mov_b32_e32 v101, v2
	v_mov_b32_e32 v102, v2
	v_mov_b32_e32 v103, v2
	v_mov_b32_e32 v104, v2
	v_mov_b32_e32 v105, v2
	v_mov_b32_e32 v114, v2
	v_mov_b32_e32 v115, v2
	v_mov_b32_e32 v116, v2
	v_mov_b32_e32 v117, v2
	v_mov_b32_e32 v118, v2
	v_mov_b32_e32 v119, v2
	v_mov_b32_e32 v120, v2
	v_mov_b32_e32 v121, v2
	v_mov_b32_e32 v74, v2
	v_mov_b32_e32 v75, v2
	v_mov_b32_e32 v76, v2
	v_mov_b32_e32 v77, v2
	v_mov_b32_e32 v78, v2
	v_mov_b32_e32 v79, v2
	v_mov_b32_e32 v80, v2
	v_mov_b32_e32 v81, v2
	v_mov_b32_e32 v90, v2
	v_mov_b32_e32 v91, v2
	v_mov_b32_e32 v92, v2
	v_mov_b32_e32 v93, v2
	v_mov_b32_e32 v94, v2
	v_mov_b32_e32 v95, v2
	v_mov_b32_e32 v96, v2
	v_mov_b32_e32 v97, v2
	v_mov_b32_e32 v106, v2
	v_mov_b32_e32 v107, v2
	v_mov_b32_e32 v108, v2
	v_mov_b32_e32 v109, v2
	v_mov_b32_e32 v110, v2
	v_mov_b32_e32 v111, v2
	v_mov_b32_e32 v112, v2
	v_mov_b32_e32 v113, v2
	v_mov_b32_e32 v122, v2
	v_mov_b32_e32 v123, v2
	v_mov_b32_e32 v124, v2
	v_mov_b32_e32 v125, v2
	v_mov_b32_e32 v126, v2
	v_mov_b32_e32 v127, v2
	v_mov_b32_e32 v128, v2
	v_mov_b32_e32 v129, v2
	s_cmpk_gt_u32 s4, 0xff
	s_cbranch_scc0 .Lrs_proj1_pre
	s_barrier
.Lrs_proj1_pre:
.LBB0_362:
	s_add_u32 s1, s28, 0xfffc0080
	s_addc_u32 s22, s29, -1
	s_add_i32 s23, 0, 0x10000
	v_add_u32_e32 v158, s23, v181
	ds_read_b128 v[130:133], v158
	ds_read_b128 v[134:137], v158 offset:1024
	ds_read_b128 v[154:157], v158 offset:2048
	ds_read_b128 v[186:189], v158 offset:3072
	s_cmp_eq_u32 s44, 12
	s_cselect_b32 s43, s17, s22
	s_cselect_b32 s42, s20, s1
	s_cselect_b32 s31, s9, s34
	s_cselect_b32 s30, s21, s25
	v_lshl_add_u64 v[160:161], s[28:29], 0, v[150:151]
	s_add_i32 m0, s49, 0xc000
	ds_read_b128 v[190:193], v185
	ds_read_b128 v[194:197], v185 offset:1024
	ds_read_b128 v[198:201], v185 offset:2048
	ds_read_b128 v[202:205], v185 offset:3072
	ds_read_b128 v[206:209], v185 offset:4096
	ds_read_b128 v[216:219], v185 offset:5120
	ds_read_b128 v[230:233], v185 offset:6144
	ds_read_b128 v[234:237], v185 offset:7168
	global_load_lds_dwordx4 v[160:161], off
	v_lshl_add_u64 v[160:161], s[28:29], 0, v[152:153]
	s_add_i32 m0, s49, 0xe000
	s_nop 0
	global_load_lds_dwordx4 v[160:161], off
	s_add_i32 s1, 0, 0x14000
	v_add_u32_e32 v158, s1, v181
	ds_read_b128 v[238:241], v158
	ds_read_b128 v[242:245], v158 offset:1024
	ds_read_b128 v[246:249], v158 offset:2048
	ds_read_b128 v[176:179], v158 offset:3072
	s_waitcnt vmcnt(8)
	s_waitcnt lgkmcnt(0)
	s_barrier
	s_setprio 1
	v_mfma_f32_16x16x32_bf16 v[126:129], v[130:133], v[190:193], v[126:129]
	v_mfma_f32_16x16x32_bf16 v[122:125], v[154:157], v[190:193], v[122:125]
	v_mfma_f32_16x16x32_bf16 v[110:113], v[130:133], v[198:201], v[110:113]
	v_mfma_f32_16x16x32_bf16 v[106:109], v[154:157], v[198:201], v[106:109]
	v_mfma_f32_16x16x32_bf16 v[94:97], v[130:133], v[206:209], v[94:97]
	v_mfma_f32_16x16x32_bf16 v[90:93], v[154:157], v[206:209], v[90:93]
	v_mfma_f32_16x16x32_bf16 v[78:81], v[130:133], v[230:233], v[78:81]
	v_mfma_f32_16x16x32_bf16 v[74:77], v[154:157], v[230:233], v[74:77]
	v_mfma_f32_16x16x32_bf16 v[126:129], v[134:137], v[194:197], v[126:129]
	v_mfma_f32_16x16x32_bf16 v[122:125], v[186:189], v[194:197], v[122:125]
	v_mfma_f32_16x16x32_bf16 v[110:113], v[134:137], v[202:205], v[110:113]
	v_mfma_f32_16x16x32_bf16 v[106:109], v[186:189], v[202:205], v[106:109]
	v_mfma_f32_16x16x32_bf16 v[94:97], v[134:137], v[216:219], v[94:97]
	v_mfma_f32_16x16x32_bf16 v[90:93], v[186:189], v[216:219], v[90:93]
	v_mfma_f32_16x16x32_bf16 v[78:81], v[134:137], v[234:237], v[78:81]
	v_mfma_f32_16x16x32_bf16 v[74:77], v[186:189], v[234:237], v[74:77]
	v_mfma_f32_16x16x32_bf16 v[118:121], v[238:241], v[190:193], v[118:121]
	v_mfma_f32_16x16x32_bf16 v[114:117], v[246:249], v[190:193], v[114:117]
	v_mfma_f32_16x16x32_bf16 v[102:105], v[238:241], v[198:201], v[102:105]
	v_mfma_f32_16x16x32_bf16 v[98:101], v[246:249], v[198:201], v[98:101]
	v_mfma_f32_16x16x32_bf16 v[86:89], v[238:241], v[206:209], v[86:89]
	v_mfma_f32_16x16x32_bf16 v[82:85], v[246:249], v[206:209], v[82:85]
	v_mfma_f32_16x16x32_bf16 v[70:73], v[238:241], v[230:233], v[70:73]
	v_mfma_f32_16x16x32_bf16 v[66:69], v[246:249], v[230:233], v[66:69]
	v_mfma_f32_16x16x32_bf16 v[118:121], v[242:245], v[194:197], v[118:121]
	v_mfma_f32_16x16x32_bf16 v[114:117], v[176:179], v[194:197], v[114:117]
	v_mfma_f32_16x16x32_bf16 v[102:105], v[242:245], v[202:205], v[102:105]
	v_mfma_f32_16x16x32_bf16 v[98:101], v[176:179], v[202:205], v[98:101]
	v_mfma_f32_16x16x32_bf16 v[86:89], v[242:245], v[216:219], v[86:89]
	v_mfma_f32_16x16x32_bf16 v[82:85], v[176:179], v[216:219], v[82:85]
	v_mfma_f32_16x16x32_bf16 v[70:73], v[242:245], v[234:237], v[70:73]
	v_mfma_f32_16x16x32_bf16 v[66:69], v[176:179], v[234:237], v[66:69]
	s_setprio 0
	s_barrier
	ds_read_b128 v[190:193], v185 offset:16384
	ds_read_b128 v[194:197], v185 offset:17408
	ds_read_b128 v[198:201], v185 offset:18432
	ds_read_b128 v[202:205], v185 offset:19456
	ds_read_b128 v[206:209], v185 offset:20480
	ds_read_b128 v[216:219], v185 offset:21504
	ds_read_b128 v[230:233], v185 offset:22528
	ds_read_b128 v[234:237], v185 offset:23552
	s_add_i32 s22, s23, s48
	v_lshl_add_u64 v[160:161], s[30:31], 0, v[0:1]
	s_mov_b32 m0, s22
	s_nop 0
	global_load_lds_dwordx4 v[160:161], off
	v_lshl_add_u64 v[220:221], s[30:31], 0, v[138:139]
	s_add_i32 m0, s22, 0x2000
	s_nop 0
	global_load_lds_dwordx4 v[220:221], off
	s_mov_b32 m0, s49
	v_lshl_add_u64 v[250:251], s[42:43], 0, v[142:143]
	global_load_lds_dwordx4 v[250:251], off
	v_lshl_add_u64 v[168:169], s[42:43], 0, v[140:141]
	s_mov_b32 m0, s50
	s_nop 0
	global_load_lds_dwordx4 v[168:169], off
	s_add_u32 s22, s30, 0x40000
	s_addc_u32 s23, s31, 0
	s_add_i32 s1, s1, s48
	s_mov_b32 m0, s1
	s_nop 0
	global_load_lds_dwordx4 v0, s[22:23]
	s_add_i32 m0, s1, 0x2000
	s_nop 0
	global_load_lds_dwordx4 v138, s[22:23]
	s_waitcnt vmcnt(8)
	s_waitcnt lgkmcnt(0)
	s_barrier
	s_setprio 1
	v_mfma_f32_16x16x32_bf16 v[62:65], v[130:133], v[190:193], v[62:65]
	v_mfma_f32_16x16x32_bf16 v[58:61], v[154:157], v[190:193], v[58:61]
	v_mfma_f32_16x16x32_bf16 v[46:49], v[130:133], v[198:201], v[46:49]
	v_mfma_f32_16x16x32_bf16 v[42:45], v[154:157], v[198:201], v[42:45]
	v_mfma_f32_16x16x32_bf16 v[30:33], v[130:133], v[206:209], v[30:33]
	v_mfma_f32_16x16x32_bf16 v[26:29], v[154:157], v[206:209], v[26:29]
	v_mfma_f32_16x16x32_bf16 v[14:17], v[130:133], v[230:233], v[14:17]
	v_mfma_f32_16x16x32_bf16 v[10:13], v[154:157], v[230:233], v[10:13]
	v_mfma_f32_16x16x32_bf16 v[62:65], v[134:137], v[194:197], v[62:65]
	v_mfma_f32_16x16x32_bf16 v[58:61], v[186:189], v[194:197], v[58:61]
	v_mfma_f32_16x16x32_bf16 v[46:49], v[134:137], v[202:205], v[46:49]
	v_mfma_f32_16x16x32_bf16 v[42:45], v[186:189], v[202:205], v[42:45]
	v_mfma_f32_16x16x32_bf16 v[30:33], v[134:137], v[216:219], v[30:33]
	v_mfma_f32_16x16x32_bf16 v[26:29], v[186:189], v[216:219], v[26:29]
	v_mfma_f32_16x16x32_bf16 v[14:17], v[134:137], v[234:237], v[14:17]
	v_mfma_f32_16x16x32_bf16 v[10:13], v[186:189], v[234:237], v[10:13]
	v_mfma_f32_16x16x32_bf16 v[54:57], v[238:241], v[190:193], v[54:57]
	v_mfma_f32_16x16x32_bf16 v[50:53], v[246:249], v[190:193], v[50:53]
	v_mfma_f32_16x16x32_bf16 v[38:41], v[238:241], v[198:201], v[38:41]
	v_mfma_f32_16x16x32_bf16 v[34:37], v[246:249], v[198:201], v[34:37]
	v_mfma_f32_16x16x32_bf16 v[22:25], v[238:241], v[206:209], v[22:25]
	v_mfma_f32_16x16x32_bf16 v[18:21], v[246:249], v[206:209], v[18:21]
	v_mfma_f32_16x16x32_bf16 v[6:9], v[238:241], v[230:233], v[6:9]
	v_mfma_f32_16x16x32_bf16 v[2:5], v[246:249], v[230:233], v[2:5]
	v_mfma_f32_16x16x32_bf16 v[54:57], v[242:245], v[194:197], v[54:57]
	v_mfma_f32_16x16x32_bf16 v[50:53], v[176:179], v[194:197], v[50:53]
	v_mfma_f32_16x16x32_bf16 v[38:41], v[242:245], v[202:205], v[38:41]
	v_mfma_f32_16x16x32_bf16 v[34:37], v[176:179], v[202:205], v[34:37]
	v_mfma_f32_16x16x32_bf16 v[22:25], v[242:245], v[216:219], v[22:25]
	v_mfma_f32_16x16x32_bf16 v[18:21], v[176:179], v[216:219], v[18:21]
	v_mfma_f32_16x16x32_bf16 v[6:9], v[242:245], v[234:237], v[6:9]
	v_mfma_f32_16x16x32_bf16 v[2:5], v[176:179], v[234:237], v[2:5]
	s_setprio 0
	s_barrier
	s_add_i32 s1, 0, 0x18000
	v_add_u32_e32 v158, s1, v181
	ds_read_b128 v[130:133], v158
	ds_read_b128 v[134:137], v158 offset:1024
	ds_read_b128 v[154:157], v158 offset:2048
	ds_read_b128 v[176:179], v158 offset:3072
	s_add_u32 s22, s42, 0x40000
	s_addc_u32 s23, s43, 0
	s_mov_b32 m0, s51
	v_lshl_add_u64 v[234:235], s[22:23], 0, v[142:143]
	ds_read_b128 v[186:189], v185 offset:32768
	ds_read_b128 v[190:193], v185 offset:33792
	ds_read_b128 v[194:197], v185 offset:34816
	ds_read_b128 v[198:201], v185 offset:35840
	ds_read_b128 v[202:205], v185 offset:36864
	ds_read_b128 v[206:209], v185 offset:37888
	ds_read_b128 v[216:219], v185 offset:38912
	ds_read_b128 v[230:233], v185 offset:39936
	global_load_lds_dwordx4 v[234:235], off
	v_lshl_add_u64 v[234:235], s[22:23], 0, v[140:141]
	s_mov_b32 m0, s52
	s_nop 0
	global_load_lds_dwordx4 v[234:235], off
	s_add_i32 s33, 0, 0x1c000
	v_add_u32_e32 v158, s33, v181
	ds_read_b128 v[234:237], v158
	ds_read_b128 v[238:241], v158 offset:1024
	ds_read_b128 v[242:245], v158 offset:2048
	ds_read_b128 v[246:249], v158 offset:3072
	s_waitcnt vmcnt(8)
	s_waitcnt lgkmcnt(0)
	s_barrier
	s_setprio 1
	v_mfma_f32_16x16x32_bf16 v[126:129], v[130:133], v[186:189], v[126:129]
	v_mfma_f32_16x16x32_bf16 v[122:125], v[154:157], v[186:189], v[122:125]
	v_mfma_f32_16x16x32_bf16 v[110:113], v[130:133], v[194:197], v[110:113]
	v_mfma_f32_16x16x32_bf16 v[106:109], v[154:157], v[194:197], v[106:109]
	v_mfma_f32_16x16x32_bf16 v[94:97], v[130:133], v[202:205], v[94:97]
	v_mfma_f32_16x16x32_bf16 v[90:93], v[154:157], v[202:205], v[90:93]
	v_mfma_f32_16x16x32_bf16 v[78:81], v[130:133], v[216:219], v[78:81]
	v_mfma_f32_16x16x32_bf16 v[74:77], v[154:157], v[216:219], v[74:77]
	v_mfma_f32_16x16x32_bf16 v[126:129], v[134:137], v[190:193], v[126:129]
	v_mfma_f32_16x16x32_bf16 v[122:125], v[176:179], v[190:193], v[122:125]
	v_mfma_f32_16x16x32_bf16 v[110:113], v[134:137], v[198:201], v[110:113]
	v_mfma_f32_16x16x32_bf16 v[106:109], v[176:179], v[198:201], v[106:109]
	v_mfma_f32_16x16x32_bf16 v[94:97], v[134:137], v[206:209], v[94:97]
	v_mfma_f32_16x16x32_bf16 v[90:93], v[176:179], v[206:209], v[90:93]
	v_mfma_f32_16x16x32_bf16 v[78:81], v[134:137], v[230:233], v[78:81]
	v_mfma_f32_16x16x32_bf16 v[74:77], v[176:179], v[230:233], v[74:77]
	v_mfma_f32_16x16x32_bf16 v[118:121], v[234:237], v[186:189], v[118:121]
	v_mfma_f32_16x16x32_bf16 v[114:117], v[242:245], v[186:189], v[114:117]
	v_mfma_f32_16x16x32_bf16 v[102:105], v[234:237], v[194:197], v[102:105]
	v_mfma_f32_16x16x32_bf16 v[98:101], v[242:245], v[194:197], v[98:101]
	v_mfma_f32_16x16x32_bf16 v[86:89], v[234:237], v[202:205], v[86:89]
	v_mfma_f32_16x16x32_bf16 v[82:85], v[242:245], v[202:205], v[82:85]
	v_mfma_f32_16x16x32_bf16 v[70:73], v[234:237], v[216:219], v[70:73]
	v_mfma_f32_16x16x32_bf16 v[66:69], v[242:245], v[216:219], v[66:69]
	v_mfma_f32_16x16x32_bf16 v[118:121], v[238:241], v[190:193], v[118:121]
	v_mfma_f32_16x16x32_bf16 v[114:117], v[246:249], v[190:193], v[114:117]
	v_mfma_f32_16x16x32_bf16 v[102:105], v[238:241], v[198:201], v[102:105]
	v_mfma_f32_16x16x32_bf16 v[98:101], v[246:249], v[198:201], v[98:101]
	v_mfma_f32_16x16x32_bf16 v[86:89], v[238:241], v[206:209], v[86:89]
	v_mfma_f32_16x16x32_bf16 v[82:85], v[246:249], v[206:209], v[82:85]
	v_mfma_f32_16x16x32_bf16 v[70:73], v[238:241], v[230:233], v[70:73]
	v_mfma_f32_16x16x32_bf16 v[66:69], v[246:249], v[230:233], v[66:69]
	s_setprio 0
	s_barrier
	ds_read_b128 v[186:189], v185 offset:49152
	ds_read_b128 v[190:193], v185 offset:50176
	ds_read_b128 v[194:197], v185 offset:51200
	ds_read_b128 v[198:201], v185 offset:52224
	ds_read_b128 v[202:205], v185 offset:53248
	ds_read_b128 v[206:209], v185 offset:54272
	ds_read_b128 v[216:219], v185 offset:55296
	ds_read_b128 v[230:233], v185 offset:56320
	s_add_i32 s1, s1, s48
	v_lshl_add_u64 v[160:161], v[160:161], 0, s[12:13]
	s_mov_b32 m0, s1
	s_nop 0
	global_load_lds_dwordx4 v[160:161], off
	v_lshl_add_u64 v[160:161], v[220:221], 0, s[12:13]
	s_add_i32 m0, s1, 0x2000
	s_nop 0
	global_load_lds_dwordx4 v[160:161], off
	s_mov_b32 m0, s55
	v_lshl_add_u64 v[160:161], v[250:251], 0, s[12:13]
	global_load_lds_dwordx4 v[160:161], off
	v_lshl_add_u64 v[160:161], v[168:169], 0, s[12:13]
	s_mov_b32 m0, s56
	s_nop 0
	global_load_lds_dwordx4 v[160:161], off
	s_add_u32 s22, s30, 0x40080
	s_addc_u32 s23, s31, 0
	s_add_i32 s1, s33, s48
	s_mov_b32 m0, s1
	s_nop 0
	global_load_lds_dwordx4 v0, s[22:23]
	s_add_i32 m0, s1, 0x2000
	s_nop 0
	global_load_lds_dwordx4 v138, s[22:23]
	s_waitcnt vmcnt(8)
	s_waitcnt lgkmcnt(0)
	s_barrier
	s_setprio 1
	v_mfma_f32_16x16x32_bf16 v[62:65], v[130:133], v[186:189], v[62:65]
	v_mfma_f32_16x16x32_bf16 v[58:61], v[154:157], v[186:189], v[58:61]
	v_mfma_f32_16x16x32_bf16 v[46:49], v[130:133], v[194:197], v[46:49]
	v_mfma_f32_16x16x32_bf16 v[42:45], v[154:157], v[194:197], v[42:45]
	v_mfma_f32_16x16x32_bf16 v[30:33], v[130:133], v[202:205], v[30:33]
	v_mfma_f32_16x16x32_bf16 v[26:29], v[154:157], v[202:205], v[26:29]
	v_mfma_f32_16x16x32_bf16 v[14:17], v[130:133], v[216:219], v[14:17]
	v_mfma_f32_16x16x32_bf16 v[10:13], v[154:157], v[216:219], v[10:13]
	v_mfma_f32_16x16x32_bf16 v[62:65], v[134:137], v[190:193], v[62:65]
	v_mfma_f32_16x16x32_bf16 v[58:61], v[176:179], v[190:193], v[58:61]
	v_mfma_f32_16x16x32_bf16 v[46:49], v[134:137], v[198:201], v[46:49]
	v_mfma_f32_16x16x32_bf16 v[42:45], v[176:179], v[198:201], v[42:45]
	v_mfma_f32_16x16x32_bf16 v[30:33], v[134:137], v[206:209], v[30:33]
	v_mfma_f32_16x16x32_bf16 v[26:29], v[176:179], v[206:209], v[26:29]
	v_mfma_f32_16x16x32_bf16 v[14:17], v[134:137], v[230:233], v[14:17]
	v_mfma_f32_16x16x32_bf16 v[10:13], v[176:179], v[230:233], v[10:13]
	v_mfma_f32_16x16x32_bf16 v[54:57], v[234:237], v[186:189], v[54:57]
	v_mfma_f32_16x16x32_bf16 v[50:53], v[242:245], v[186:189], v[50:53]
	v_mfma_f32_16x16x32_bf16 v[38:41], v[234:237], v[194:197], v[38:41]
	v_mfma_f32_16x16x32_bf16 v[34:37], v[242:245], v[194:197], v[34:37]
	v_mfma_f32_16x16x32_bf16 v[22:25], v[234:237], v[202:205], v[22:25]
	v_mfma_f32_16x16x32_bf16 v[18:21], v[242:245], v[202:205], v[18:21]
	v_mfma_f32_16x16x32_bf16 v[6:9], v[234:237], v[216:219], v[6:9]
	v_mfma_f32_16x16x32_bf16 v[2:5], v[242:245], v[216:219], v[2:5]
	v_mfma_f32_16x16x32_bf16 v[54:57], v[238:241], v[190:193], v[54:57]
	v_mfma_f32_16x16x32_bf16 v[50:53], v[246:249], v[190:193], v[50:53]
	v_mfma_f32_16x16x32_bf16 v[38:41], v[238:241], v[198:201], v[38:41]
	v_mfma_f32_16x16x32_bf16 v[34:37], v[246:249], v[198:201], v[34:37]
	v_mfma_f32_16x16x32_bf16 v[22:25], v[238:241], v[206:209], v[22:25]
	v_mfma_f32_16x16x32_bf16 v[18:21], v[246:249], v[206:209], v[18:21]
	v_mfma_f32_16x16x32_bf16 v[6:9], v[238:241], v[230:233], v[6:9]
	v_mfma_f32_16x16x32_bf16 v[2:5], v[246:249], v[230:233], v[2:5]
	s_setprio 0
	s_add_i32 s44, s44, 2
	s_add_u32 s28, s28, 0x100
	s_addc_u32 s29, s29, 0
	s_add_u32 s25, s25, 0x100
	s_addc_u32 s34, s34, 0
	s_cmp_gt_u32 s44, 13
	s_barrier
	s_cbranch_scc0 .LBB0_362
	s_cmpk_gt_u32 s4, 0xff
	s_cbranch_scc1 .Lrs_proj1_post
	s_barrier
.Lrs_proj1_post:
	v_and_b32_e32 v131, 64, v212
	v_xor_b32_e32 v130, 16, v212
	v_add_u32_e32 v131, 64, v131
	v_lshl_add_u32 v190, s16, 8, v159
	v_cmp_lt_i32_e32 vcc, v130, v131
	v_add_u32_e32 v156, s54, v190
	v_or_b32_e32 v134, 16, v156
	v_cndmask_b32_e32 v130, v212, v130, vcc
	v_lshlrev_b32_e32 v191, 2, v130
	v_xor_b32_e32 v130, 32, v212
	v_cmp_lt_i32_e32 vcc, v130, v131
	v_ashrrev_i32_e32 v157, 31, v156
	v_ashrrev_i32_e32 v135, 31, v134
	v_cndmask_b32_e32 v130, v212, v130, vcc
	v_lshlrev_b64 v[136:137], 6, v[156:157]
	v_lshlrev_b64 v[134:135], 6, v[134:135]
	v_lshlrev_b32_e32 v192, 2, v130
	v_lshl_add_u64 v[130:131], v[144:145], 0, v[136:137]
	v_lshl_add_u64 v[160:161], v[144:145], 0, v[134:135]
	global_load_dwordx4 v[130:133], v[130:131], off
	v_lshl_or_b32 v154, s0, 8, v183
	global_load_dwordx4 v[186:189], v[160:161], off
	v_or_b32_e32 v160, 32, v156
	v_ashrrev_i32_e32 v161, 31, v160
	v_lshlrev_b64 v[178:179], 6, v[160:161]
	v_or_b32_e32 v156, 48, v156
	v_lshl_add_u64 v[160:161], v[144:145], 0, v[178:179]
	v_ashrrev_i32_e32 v157, 31, v156
	global_load_dwordx4 v[194:197], v[160:161], off
	v_lshlrev_b64 v[160:161], 6, v[156:157]
	v_lshl_add_u64 v[156:157], v[144:145], 0, v[160:161]
	global_load_dwordx4 v[198:201], v[156:157], off
	s_ashr_i32 s0, s0, 2
	s_mul_hi_i32 s1, s0, 0x55555556
	s_lshr_b32 s9, s1, 31
	s_add_i32 s1, s1, s9
	s_mul_i32 s1, s1, 3
	s_sub_i32 s0, s0, s1
	s_cmp_lt_i32 s0, 2
	s_cselect_b64 s[0:1], -1, 0
	s_and_b64 s[28:29], s[6:7], s[0:1]
	v_ashrrev_i32_e32 v155, 31, v154
	s_mov_b64 s[44:45], -1
	v_or_b32_e32 v193, 48, v190
	s_waitcnt vmcnt(0)
	v_mov_b32_e32 v156, v131
	v_mov_b32_e32 v157, v132
	v_mov_b32_e32 v131, v133
	v_mov_b32_e32 v132, v187
	v_mov_b32_e32 v133, v188
	v_mov_b32_e32 v187, v189
	v_pk_add_f32 v[130:131], v[156:157], v[130:131]
	v_pk_add_f32 v[132:133], v[132:133], v[186:187]
	v_mov_b32_e32 v157, v130
	v_mov_b32_e32 v156, v132
	v_mov_b32_e32 v130, v133
	v_pk_add_f32 v[130:131], v[156:157], v[130:131]
	ds_bpermute_b32 v133, v191, v131
	ds_bpermute_b32 v132, v191, v130
	v_mov_b32_e32 v157, v200
	s_waitcnt lgkmcnt(0)
	v_pk_add_f32 v[130:131], v[130:131], v[132:133]
	ds_bpermute_b32 v133, v192, v131
	ds_bpermute_b32 v132, v192, v130
	s_waitcnt lgkmcnt(0)
	v_pk_add_f32 v[130:131], v[130:131], v[132:133]
	v_mov_b64_e32 v[132:133], s[60:61]
	v_pk_fma_f32 v[130:131], v[130:131], s[58:59], v[132:133] op_sel_hi:[1,0,0]
	s_nop 0
	v_mul_f32_e32 v156, 0x4b800000, v131
	v_cmp_gt_f32_e64 s[42:43], s39, v131
	v_cmp_gt_f32_e32 vcc, s39, v130
	s_nop 0
	v_cndmask_b32_e64 v131, v131, v156, s[42:43]
	v_rsq_f32_e32 v131, v131
	s_nop 0
	v_mul_f32_e32 v156, 0x45800000, v131
	v_cndmask_b32_e64 v184, v131, v156, s[42:43]
	v_mul_f32_e32 v131, 0x4b800000, v130
	v_cndmask_b32_e32 v130, v130, v131, vcc
	v_rsq_f32_e32 v130, v130
	v_mov_b32_e32 v156, v199
	v_mov_b32_e32 v199, v201
	v_pk_add_f32 v[156:157], v[156:157], v[198:199]
	v_mul_f32_e32 v131, 0x45800000, v130
	v_cndmask_b32_e32 v182, v130, v131, vcc
	v_mov_b32_e32 v130, v195
	v_mov_b32_e32 v131, v196
	v_mov_b32_e32 v195, v197
	v_pk_add_f32 v[130:131], v[130:131], v[194:195]
	v_mov_b32_e32 v176, v156
	v_mov_b32_e32 v177, v130
	v_mov_b32_e32 v130, v157
	v_pk_add_f32 v[130:131], v[176:177], v[130:131]
	ds_bpermute_b32 v157, v191, v131
	ds_bpermute_b32 v156, v191, v130
	v_or_b32_e32 v195, 16, v190
	v_or_b32_e32 v194, 32, v190
	s_waitcnt lgkmcnt(0)
	v_pk_add_f32 v[130:131], v[130:131], v[156:157]
	ds_bpermute_b32 v157, v192, v131
	ds_bpermute_b32 v156, v192, v130
	s_waitcnt lgkmcnt(0)
	v_pk_add_f32 v[130:131], v[130:131], v[156:157]
	s_nop 0
	v_pk_fma_f32 v[130:131], v[130:131], s[58:59], v[132:133] op_sel_hi:[1,0,0]
	v_lshlrev_b64 v[156:157], 1, v[154:155]
	v_mul_f32_e32 v132, 0x4b800000, v131
	v_cmp_gt_f32_e64 s[42:43], s39, v131
	v_cmp_gt_f32_e32 vcc, s39, v130
	s_nop 0
	v_cndmask_b32_e64 v131, v131, v132, s[42:43]
	v_rsq_f32_e32 v131, v131
	s_nop 0
	v_mul_f32_e32 v132, 0x45800000, v131
	v_cndmask_b32_e64 v180, v131, v132, s[42:43]
	v_mul_f32_e32 v131, 0x4b800000, v130
	v_cndmask_b32_e32 v130, v130, v131, vcc
	v_rsq_f32_e32 v130, v130
	s_nop 0
	v_mul_f32_e32 v131, 0x45800000, v130
	v_cndmask_b32_e32 v158, v130, v131, vcc
	s_and_b64 vcc, exec, s[28:29]
	s_cbranch_vccnz .LBB0_365
	v_mov_b64_e32 v[176:177], s[68:69]
	v_mad_i64_i32 v[130:131], s[0:1], v190, s86, v[176:177]
	v_lshl_add_u64 v[186:187], v[130:131], 0, v[156:157]
	v_pk_mul_f32 v[132:133], v[128:129], v[184:185] op_sel_hi:[1,0]
	v_pk_mul_f32 v[130:131], v[126:127], v[184:185] op_sel_hi:[1,0]
	v_pk_mul_f32 v[188:189], v[124:125], v[184:185] op_sel_hi:[1,0]
	v_pk_mul_f32 v[196:197], v[122:123], v[184:185] op_sel_hi:[1,0]
	v_cvt_pk_bf16_f32 v130, v130, v131
	v_cvt_pk_bf16_f32 v131, v132, v133
	v_cvt_pk_bf16_f32 v132, v196, v197
	v_cvt_pk_bf16_f32 v133, v188, v189
	global_store_dwordx4 v[186:187], v[130:133], off
	v_pk_mul_f32 v[188:189], v[116:117], v[184:185] op_sel_hi:[1,0]
	v_pk_mul_f32 v[196:197], v[114:115], v[184:185] op_sel_hi:[1,0]
	v_pk_mul_f32 v[132:133], v[120:121], v[184:185] op_sel_hi:[1,0]
	v_pk_mul_f32 v[130:131], v[118:119], v[184:185] op_sel_hi:[1,0]
	s_mov_b64 s[44:45], 0
	v_cvt_pk_bf16_f32 v130, v130, v131
	v_cvt_pk_bf16_f32 v131, v132, v133
	v_cvt_pk_bf16_f32 v132, v196, v197
	v_cvt_pk_bf16_f32 v133, v188, v189
	global_store_dwordx4 v[186:187], v[130:133], off offset:256
	v_pk_mul_f32 v[188:189], v[108:109], v[182:183] op_sel_hi:[1,0]
	v_pk_mul_f32 v[196:197], v[106:107], v[182:183] op_sel_hi:[1,0]
	v_mad_i64_i32 v[130:131], s[0:1], v195, s86, v[176:177]
	v_lshl_add_u64 v[186:187], v[130:131], 0, v[156:157]
	v_pk_mul_f32 v[132:133], v[112:113], v[182:183] op_sel_hi:[1,0]
	v_pk_mul_f32 v[130:131], v[110:111], v[182:183] op_sel_hi:[1,0]
	s_nop 0
	v_cvt_pk_bf16_f32 v130, v130, v131
	v_cvt_pk_bf16_f32 v131, v132, v133
	v_cvt_pk_bf16_f32 v132, v196, v197
	v_cvt_pk_bf16_f32 v133, v188, v189
	global_store_dwordx4 v[186:187], v[130:133], off
	v_pk_mul_f32 v[188:189], v[100:101], v[182:183] op_sel_hi:[1,0]
	v_pk_mul_f32 v[196:197], v[98:99], v[182:183] op_sel_hi:[1,0]
	v_pk_mul_f32 v[132:133], v[104:105], v[182:183] op_sel_hi:[1,0]
	v_pk_mul_f32 v[130:131], v[102:103], v[182:183] op_sel_hi:[1,0]
	s_nop 0
	v_cvt_pk_bf16_f32 v130, v130, v131
	v_cvt_pk_bf16_f32 v131, v132, v133
	v_cvt_pk_bf16_f32 v132, v196, v197
	v_cvt_pk_bf16_f32 v133, v188, v189
	global_store_dwordx4 v[186:187], v[130:133], off offset:256
	v_pk_mul_f32 v[188:189], v[92:93], v[180:181] op_sel_hi:[1,0]
	v_pk_mul_f32 v[196:197], v[90:91], v[180:181] op_sel_hi:[1,0]
	v_mad_i64_i32 v[130:131], s[0:1], v194, s86, v[176:177]
	v_lshl_add_u64 v[186:187], v[130:131], 0, v[156:157]
	v_pk_mul_f32 v[132:133], v[96:97], v[180:181] op_sel_hi:[1,0]
	v_pk_mul_f32 v[130:131], v[94:95], v[180:181] op_sel_hi:[1,0]
	s_nop 0
	v_cvt_pk_bf16_f32 v130, v130, v131
	v_cvt_pk_bf16_f32 v131, v132, v133
	v_cvt_pk_bf16_f32 v132, v196, v197
	v_cvt_pk_bf16_f32 v133, v188, v189
	global_store_dwordx4 v[186:187], v[130:133], off
	v_pk_mul_f32 v[188:189], v[84:85], v[180:181] op_sel_hi:[1,0]
	v_pk_mul_f32 v[196:197], v[82:83], v[180:181] op_sel_hi:[1,0]
	v_pk_mul_f32 v[132:133], v[88:89], v[180:181] op_sel_hi:[1,0]
	v_pk_mul_f32 v[130:131], v[86:87], v[180:181] op_sel_hi:[1,0]
	s_nop 0
	v_cvt_pk_bf16_f32 v130, v130, v131
	v_cvt_pk_bf16_f32 v131, v132, v133
	v_cvt_pk_bf16_f32 v132, v196, v197
	v_cvt_pk_bf16_f32 v133, v188, v189
	global_store_dwordx4 v[186:187], v[130:133], off offset:256
	v_pk_mul_f32 v[186:187], v[76:77], v[158:159] op_sel_hi:[1,0]
	v_pk_mul_f32 v[196:197], v[74:75], v[158:159] op_sel_hi:[1,0]
	v_mad_i64_i32 v[130:131], s[0:1], v193, s86, v[176:177]
	v_lshl_add_u64 v[176:177], v[130:131], 0, v[156:157]
	v_pk_mul_f32 v[132:133], v[80:81], v[158:159] op_sel_hi:[1,0]
	v_pk_mul_f32 v[130:131], v[78:79], v[158:159] op_sel_hi:[1,0]
	v_mad_i64_i32 v[188:189], s[0:1], v193, s86, 0
	v_cvt_pk_bf16_f32 v130, v130, v131
	v_cvt_pk_bf16_f32 v131, v132, v133
	v_cvt_pk_bf16_f32 v132, v196, v197
	v_cvt_pk_bf16_f32 v133, v186, v187
	global_store_dwordx4 v[176:177], v[130:133], off
	v_pk_mul_f32 v[176:177], v[66:67], v[158:159] op_sel_hi:[1,0]
	v_pk_mul_f32 v[186:187], v[68:69], v[158:159] op_sel_hi:[1,0]
	v_pk_mul_f32 v[132:133], v[72:73], v[158:159] op_sel_hi:[1,0]
	v_pk_mul_f32 v[130:131], v[70:71], v[158:159] op_sel_hi:[1,0]
	s_nop 0
	v_cvt_pk_bf16_f32 v130, v130, v131
	v_cvt_pk_bf16_f32 v131, v132, v133
	v_cvt_pk_bf16_f32 v132, v176, v177

.LBB0_371:
	s_waitcnt vmcnt(0)
	s_cmpk_gt_u32 s4, 0xff
	s_cbranch_scc1 .LBB0_373
	s_nop 0
